# hand-written RG-LRU tile loops (phases 3+4): register-resident segment scans, MFMA token remap, 2 barriers per tile
# speedup vs baseline: 1.1895x; 1.0643x over previous
; __device__ __forceinline__ float bf2f(u16 h) { return __uint_as_float(((unsigned)h) << 16); }
; __device__ __forceinline__ void lru_tile(const Params& P, int chunk, int head, int pass, char* smem_raw) {
;     ...
;   const int tid = VTID, lane = tid & 63, wid = tid >> 6;
;   const int q = tid >> 6, ch = tid & 63;
;   const int row0 = chunk * 128;
;   int seq_lo, seq_hi;
;   if (chunk < 256) { seq_lo = (chunk >> 6) << 13; seq_hi = seq_lo + 8192; }
;   else { const int b = (chunk - 256) >> 1; seq_lo = N_X + b * 256; seq_hi = seq_lo + 256; }
;   const int gch = head * 64 + ch;
;   const float* hfbuf = reinterpret_cast<const float*>(P.hy);
;   float* hfw = reinterpret_cast<float*>(P.hy);
;   {
;     const float w0 = P.conv_w[gch], w1 = P.conv_w[512 + gch], w2 = P.conv_w[1024 + gch], w3 = P.conv_w[1536 + gch];
;     const float cb = P.conv_b[gch];
;     const u16* zu = P.zq + gch;
;     const int r = row0 + q * 32;
;     float uv[35];
; #pragma unroll
;     for (int i = 0; i < 35; ++i) {
;       const int rr = r - 2 + i;
;       uv[i] = (rr >= seq_lo && rr < seq_hi) ? bf2f(zu[(long)rr * 1536]) : 0.f;
; __device__ __forceinline__ void run_phase(const Params& P, const int ph, char* smem_raw) {
;     ...
;     case 3:
;       for (int t = VBID; t < 2112; t += VGRID) lru_tile(P, t >> 3, t & 7, 1, smv_raw);
.LBB0_287:
	v_readlane_b32 s0, v252, 0
	v_readlane_b32 s1, v252, 1
	v_readfirstlane_b32 s68, v153
	s_nop 3
	s_sub_u32 s0, s0, 0x170
	s_subb_u32 s1, s1, 0
	s_load_dwordx2 s[10:11], s[0:1], 0x148
	s_load_dwordx2 s[12:13], s[0:1], 0x158
	s_load_dwordx2 s[18:19], s[0:1], 0x130
	s_load_dwordx2 s[20:21], s[0:1], 0x128
	s_load_dwordx4 s[24:27], s[0:1], 0x70
	s_load_dwordx2 s[28:29], s[0:1], 0x88
	s_load_dwordx2 s[30:31], s[0:1], 0x98
	s_load_dwordx2 s[36:37], s[0:1], 0xa0
	s_lshl_b32 s4, s2, 1
	s_add_u32 s68, s4, s68
	s_mov_b32 s69, 0
	s_mov_b32 s70, 4
	s_cmp_lt_u32 s68, 64
	s_cselect_b32 s70, 5, 4
	s_mov_b32 s72, 0xffff0000
	s_mov_b32 s73, -1
	s_mov_b32 s74, 0
	s_mov_b32 s75, -1
	s_mov_b32 s76, 0
	s_mov_b32 s77, 0xffff0000
	s_mov_b32 s78, -1
	s_mov_b32 s79, 0x0000ffff
	s_mov_b32 s80, -1
	s_mov_b32 s81, 0
	s_mov_b32 s82, 0x0000ffff
	s_mov_b32 s83, 0
	v_and_b32_e32 v138, 63, v152
	v_lshrrev_b32_e32 v139, 4, v138
	v_and_b32_e32 v140, 15, v138
	v_bfe_u32 v141, v152, 6, 2
	v_lshl_add_u32 v255, v141, 4, v140
	v_mul_u32_u24_e32 v253, 0x12000, v153
	v_add_u32_e32 v253, 16, v253
	v_mul_u32_u24_e32 v134, 0x18000, v139
	v_lshl_add_u32 v134, v255, 1, v134
	v_lshlrev_b32_e32 v237, 16, v139
	v_lshl_add_u32 v237, v255, 1, v237
	v_lshlrev_b32_e32 v250, 3, v255
	v_lshlrev_b32_e32 v251, 7, v255
	v_lshl_add_u32 v251, v139, 4, v251
	v_lshrrev_b32_e32 v254, 3, v140
	v_lshl_add_u32 v254, v141, 1, v254
	v_lshlrev_b32_e32 v202, 1, v139
	v_xor_b32_e32 v89, v254, v202
	v_xor_b32_e32 v130, 1, v89
	v_and_b32_e32 v203, 7, v140
	v_lshl_add_u32 v202, v139, 12, v253
	v_lshl_add_u32 v202, v203, 1, v202
	v_lshl_add_u32 v89, v89, 4, v202
	v_lshl_add_u32 v130, v130, 4, v202
	v_lshrrev_b32_e32 v202, 2, v140
	v_and_b32_e32 v203, 3, v140
	v_lshl_add_u32 v254, v202, 5, v203
	v_lshl_add_u32 v254, v254, 7, v253
	v_lshrrev_b32_e32 v203, 1, v203
	v_lshl_add_u32 v202, v202, 1, v203
	v_xor_b32_e32 v202, v139, v202
	v_lshl_add_u32 v131, v202, 4, v254
	v_xor_b32_e32 v202, 4, v202
	v_lshl_add_u32 v133, v202, 4, v254
	v_cmp_eq_u32_e32 vcc, 0, v139
	s_mov_b64 s[84:85], vcc
	v_cmp_eq_u32_e32 vcc, 3, v139
	s_mov_b64 s[86:87], vcc
	s_waitcnt lgkmcnt(0)
.Lmy_lrua_tile:
	s_lshl_b32 s4, s69, 9
	s_add_u32 s4, s4, s68
	s_lshr_b32 s71, s4, 3
	s_and_b32 s5, s4, 7
	s_lshl_b32 s56, s5, 6
	s_cmp_lt_u32 s71, 256
	s_cbranch_scc0 .Lmy_lrua_ctx
	s_and_b32 s57, s71, 63
	s_mov_b32 s60, 63
	s_branch .Lmy_lrua_fl
.Lmy_lrua_ctx:
	s_and_b32 s57, s71, 1
	s_mov_b32 s60, 1
.Lmy_lrua_fl:
	s_cmp_eq_u32 s57, 0
	s_cselect_b64 s[0:1], s[84:85], 0
	s_cmp_eq_u32 s57, s60
	s_cselect_b64 s[4:5], s[86:87], 0
	v_cndmask_b32_e64 v202, 1.0, 0, s[0:1]
	v_cndmask_b32_e64 v203, 1.0, 0, s[4:5]
	v_mov_b32_e32 v255, 0x1800
	v_cndmask_b32_e64 v150, 0, v255, s[0:1]
	v_lshlrev_b32_e32 v136, 1, v150
	v_add_u32_e32 v136, v134, v136
	v_add_u32_e32 v150, v134, v150
	v_cndmask_b32_e64 v151, 0, v255, s[4:5]
	v_sub_u32_e32 v151, v134, v151
	s_lshl_b32 s61, s71, 7
	s_mul_i32 s0, s61, 0xc00
	s_lshl_b32 s1, s56, 1
	s_add_u32 s0, s0, s1
	s_add_u32 s4, s10, s0
	s_addc_u32 s5, s11, 0
	s_sub_u32 s4, s4, 0x1800
	s_subb_u32 s5, s5, 0
	global_load_ushort v90, v136, s[4:5]
	s_add_u32 s4, s4, 0xc00
	s_addc_u32 s5, s5, 0
	global_load_ushort v91, v150, s[4:5]
	s_add_u32 s4, s4, 0xc00
	s_addc_u32 s5, s5, 0
	global_load_ushort v92, v134, s[4:5]
	s_add_u32 s4, s4, 0xc00
	s_addc_u32 s5, s5, 0
	global_load_ushort v93, v134, s[4:5]
	s_add_u32 s4, s4, 0xc00
	s_addc_u32 s5, s5, 0
	global_load_ushort v94, v134, s[4:5]
	s_add_u32 s4, s4, 0xc00
	s_addc_u32 s5, s5, 0
	global_load_ushort v95, v134, s[4:5]
	s_add_u32 s4, s4, 0xc00
	s_addc_u32 s5, s5, 0
	global_load_ushort v96, v134, s[4:5]
	s_add_u32 s4, s4, 0xc00
	s_addc_u32 s5, s5, 0
	global_load_ushort v97, v134, s[4:5]
	s_add_u32 s4, s4, 0xc00
	s_addc_u32 s5, s5, 0
	global_load_ushort v98, v134, s[4:5]
	s_add_u32 s4, s4, 0xc00
	s_addc_u32 s5, s5, 0
	global_load_ushort v99, v134, s[4:5]
	s_add_u32 s4, s4, 0xc00
	s_addc_u32 s5, s5, 0
	global_load_ushort v100, v134, s[4:5]
	s_add_u32 s4, s4, 0xc00
	s_addc_u32 s5, s5, 0
	global_load_ushort v101, v134, s[4:5]
	s_add_u32 s4, s4, 0xc00
	s_addc_u32 s5, s5, 0
	global_load_ushort v102, v134, s[4:5]
	s_add_u32 s4, s4, 0xc00
	s_addc_u32 s5, s5, 0
	global_load_ushort v103, v134, s[4:5]
	s_add_u32 s4, s4, 0xc00
	s_addc_u32 s5, s5, 0
	global_load_ushort v104, v134, s[4:5]
	s_add_u32 s4, s4, 0xc00
	s_addc_u32 s5, s5, 0
	global_load_ushort v105, v134, s[4:5]
	s_add_u32 s4, s4, 0xc00
	s_addc_u32 s5, s5, 0
	global_load_ushort v106, v134, s[4:5]
	s_add_u32 s4, s4, 0xc00
	s_addc_u32 s5, s5, 0
	global_load_ushort v107, v134, s[4:5]
	s_add_u32 s4, s4, 0xc00
	s_addc_u32 s5, s5, 0
	global_load_ushort v108, v134, s[4:5]
	s_add_u32 s4, s4, 0xc00
	s_addc_u32 s5, s5, 0
	global_load_ushort v109, v134, s[4:5]
	s_add_u32 s4, s4, 0xc00
	s_addc_u32 s5, s5, 0
	global_load_ushort v110, v134, s[4:5]
	s_add_u32 s4, s4, 0xc00
	s_addc_u32 s5, s5, 0
	global_load_ushort v111, v134, s[4:5]
	s_add_u32 s4, s4, 0xc00
	s_addc_u32 s5, s5, 0
	global_load_ushort v112, v134, s[4:5]
	s_add_u32 s4, s4, 0xc00
	s_addc_u32 s5, s5, 0
	global_load_ushort v113, v134, s[4:5]
	s_add_u32 s4, s4, 0xc00
	s_addc_u32 s5, s5, 0
	global_load_ushort v114, v134, s[4:5]
	s_add_u32 s4, s4, 0xc00
	s_addc_u32 s5, s5, 0
	global_load_ushort v115, v134, s[4:5]
	s_add_u32 s4, s4, 0xc00
	s_addc_u32 s5, s5, 0
	global_load_ushort v116, v134, s[4:5]
	s_add_u32 s4, s4, 0xc00
	s_addc_u32 s5, s5, 0
	global_load_ushort v117, v134, s[4:5]
	s_add_u32 s4, s4, 0xc00
	s_addc_u32 s5, s5, 0
	global_load_ushort v118, v134, s[4:5]
	s_add_u32 s4, s4, 0xc00
	s_addc_u32 s5, s5, 0
	global_load_ushort v119, v134, s[4:5]
	s_add_u32 s4, s4, 0xc00
	s_addc_u32 s5, s5, 0
	global_load_ushort v120, v134, s[4:5]
	s_add_u32 s4, s4, 0xc00
	s_addc_u32 s5, s5, 0
	global_load_ushort v121, v134, s[4:5]
	s_add_u32 s4, s4, 0xc00
	s_addc_u32 s5, s5, 0
	global_load_ushort v122, v134, s[4:5]
	s_add_u32 s4, s4, 0xc00
	s_addc_u32 s5, s5, 0
	global_load_ushort v123, v134, s[4:5]
	s_add_u32 s4, s4, 0xc00
	s_addc_u32 s5, s5, 0
	global_load_ushort v124, v151, s[4:5]
	v_bfe_u32 v255, v152, 6, 2
	v_and_b32_e32 v253, 15, v152
	v_lshl_add_u32 v255, v255, 4, v253
	v_add_u32_e32 v255, s56, v255
	v_lshlrev_b32_e32 v255, 2, v255
	global_load_dword v65, v255, s[24:25]
	global_load_dword v67, v255, s[24:25] offset:2048
	s_add_u32 s0, s24, 0x1000
	s_addc_u32 s1, s25, 0
	global_load_dword v68, v255, s[0:1]
	global_load_dword v70, v255, s[0:1] offset:2048
	global_load_dword v73, v255, s[26:27]
	s_barrier
; __device__ __forceinline__ float bf2f(u16 h) { return __uint_as_float(((unsigned)h) << 16); }
; __device__ __forceinline__ void lru_tile(const Params& P, int chunk, int head, int pass, char* smem_raw) {
;     ...
;     float uv[35];
; #pragma unroll
;     for (int i = 0; i < 35; ++i) {
;       const int rr = r - 2 + i;
;       uv[i] = (rr >= seq_lo && rr < seq_hi) ? bf2f(zu[(long)rr * 1536]) : 0.f;
;     }
;     __syncthreads();
; #pragma unroll
;     for (int i = 0; i < 32; ++i) {
;       const float v = cb + uv[i] * w0 + uv[i + 1] * w1 + uv[i + 2] * w2 + uv[i + 3] * w3;
;       sm_uc[(q * 32 + i) * LDSS + ch] = f2bf(v);
	s_waitcnt vmcnt(0)
	v_lshlrev_b32_e32 v90, 16, v90
	v_lshlrev_b32_e32 v91, 16, v91
	v_lshlrev_b32_e32 v92, 16, v92
	v_lshlrev_b32_e32 v93, 16, v93
	v_lshlrev_b32_e32 v94, 16, v94
	v_lshlrev_b32_e32 v95, 16, v95
	v_lshlrev_b32_e32 v96, 16, v96
	v_lshlrev_b32_e32 v97, 16, v97
	v_lshlrev_b32_e32 v98, 16, v98
	v_lshlrev_b32_e32 v99, 16, v99
	v_lshlrev_b32_e32 v100, 16, v100
	v_lshlrev_b32_e32 v101, 16, v101
	v_lshlrev_b32_e32 v102, 16, v102
	v_lshlrev_b32_e32 v103, 16, v103
	v_lshlrev_b32_e32 v104, 16, v104
	v_lshlrev_b32_e32 v105, 16, v105
	v_lshlrev_b32_e32 v106, 16, v106
	v_lshlrev_b32_e32 v107, 16, v107
	v_lshlrev_b32_e32 v108, 16, v108
	v_lshlrev_b32_e32 v109, 16, v109
	v_lshlrev_b32_e32 v110, 16, v110
	v_lshlrev_b32_e32 v111, 16, v111
	v_lshlrev_b32_e32 v112, 16, v112
	v_lshlrev_b32_e32 v113, 16, v113
	v_lshlrev_b32_e32 v114, 16, v114
	v_lshlrev_b32_e32 v115, 16, v115
	v_lshlrev_b32_e32 v116, 16, v116
	v_lshlrev_b32_e32 v117, 16, v117
	v_lshlrev_b32_e32 v118, 16, v118
	v_lshlrev_b32_e32 v119, 16, v119
	v_lshlrev_b32_e32 v120, 16, v120
	v_lshlrev_b32_e32 v121, 16, v121
	v_lshlrev_b32_e32 v122, 16, v122
	v_lshlrev_b32_e32 v123, 16, v123
	v_lshlrev_b32_e32 v124, 16, v124
	v_mul_f32_e32 v90, v90, v202
	v_mul_f32_e32 v91, v91, v202
	v_mul_f32_e32 v124, v124, v203
	v_fma_f32 v162, v90, v65, v73
	v_fma_f32 v162, v91, v67, v162
	v_fma_f32 v162, v92, v68, v162
	v_fma_f32 v162, v93, v70, v162
	v_fma_f32 v163, v91, v65, v73
	v_fma_f32 v163, v92, v67, v163
	v_fma_f32 v163, v93, v68, v163
	v_fma_f32 v163, v94, v70, v163
	v_fma_f32 v164, v92, v65, v73
	v_fma_f32 v164, v93, v67, v164
	v_fma_f32 v164, v94, v68, v164
	v_fma_f32 v164, v95, v70, v164
	v_fma_f32 v165, v93, v65, v73
	v_fma_f32 v165, v94, v67, v165
	v_fma_f32 v165, v95, v68, v165
	v_fma_f32 v165, v96, v70, v165
	v_fma_f32 v166, v94, v65, v73
	v_fma_f32 v166, v95, v67, v166
	v_fma_f32 v166, v96, v68, v166
	v_fma_f32 v166, v97, v70, v166
	v_fma_f32 v167, v95, v65, v73
	v_fma_f32 v167, v96, v67, v167
	v_fma_f32 v167, v97, v68, v167
	v_fma_f32 v167, v98, v70, v167
	v_fma_f32 v168, v96, v65, v73
	v_fma_f32 v168, v97, v67, v168
	v_fma_f32 v168, v98, v68, v168
	v_fma_f32 v168, v99, v70, v168
	v_fma_f32 v169, v97, v65, v73
	v_fma_f32 v169, v98, v67, v169
	v_fma_f32 v169, v99, v68, v169
	v_fma_f32 v169, v100, v70, v169
	v_fma_f32 v170, v98, v65, v73
	v_fma_f32 v170, v99, v67, v170
	v_fma_f32 v170, v100, v68, v170
	v_fma_f32 v170, v101, v70, v170
	v_fma_f32 v171, v99, v65, v73
	v_fma_f32 v171, v100, v67, v171
	v_fma_f32 v171, v101, v68, v171
	v_fma_f32 v171, v102, v70, v171
	v_fma_f32 v172, v100, v65, v73
	v_fma_f32 v172, v101, v67, v172
	v_fma_f32 v172, v102, v68, v172
	v_fma_f32 v172, v103, v70, v172
	v_fma_f32 v173, v101, v65, v73
	v_fma_f32 v173, v102, v67, v173
	v_fma_f32 v173, v103, v68, v173
	v_fma_f32 v173, v104, v70, v173
	v_fma_f32 v174, v102, v65, v73
	v_fma_f32 v174, v103, v67, v174
	v_fma_f32 v174, v104, v68, v174
	v_fma_f32 v174, v105, v70, v174
	v_fma_f32 v175, v103, v65, v73
	v_fma_f32 v175, v104, v67, v175
	v_fma_f32 v175, v105, v68, v175
	v_fma_f32 v175, v106, v70, v175
	v_fma_f32 v176, v104, v65, v73
	v_fma_f32 v176, v105, v67, v176
	v_fma_f32 v176, v106, v68, v176
	v_fma_f32 v176, v107, v70, v176
	v_fma_f32 v177, v105, v65, v73
	v_fma_f32 v177, v106, v67, v177
	v_fma_f32 v177, v107, v68, v177
	v_fma_f32 v177, v108, v70, v177
	v_fma_f32 v178, v106, v65, v73
	v_fma_f32 v178, v107, v67, v178
	v_fma_f32 v178, v108, v68, v178
	v_fma_f32 v178, v109, v70, v178
	v_fma_f32 v179, v107, v65, v73
	v_fma_f32 v179, v108, v67, v179
	v_fma_f32 v179, v109, v68, v179
	v_fma_f32 v179, v110, v70, v179
	v_fma_f32 v180, v108, v65, v73
	v_fma_f32 v180, v109, v67, v180
	v_fma_f32 v180, v110, v68, v180
	v_fma_f32 v180, v111, v70, v180
	v_fma_f32 v181, v109, v65, v73
	v_fma_f32 v181, v110, v67, v181
	v_fma_f32 v181, v111, v68, v181
	v_fma_f32 v181, v112, v70, v181
	v_fma_f32 v182, v110, v65, v73
	v_fma_f32 v182, v111, v67, v182
	v_fma_f32 v182, v112, v68, v182
	v_fma_f32 v182, v113, v70, v182
	v_fma_f32 v183, v111, v65, v73
	v_fma_f32 v183, v112, v67, v183
	v_fma_f32 v183, v113, v68, v183
	v_fma_f32 v183, v114, v70, v183
	v_fma_f32 v184, v112, v65, v73
	v_fma_f32 v184, v113, v67, v184
	v_fma_f32 v184, v114, v68, v184
	v_fma_f32 v184, v115, v70, v184
	v_fma_f32 v185, v113, v65, v73
	v_fma_f32 v185, v114, v67, v185
	v_fma_f32 v185, v115, v68, v185
	v_fma_f32 v185, v116, v70, v185
	v_fma_f32 v186, v114, v65, v73
	v_fma_f32 v186, v115, v67, v186
	v_fma_f32 v186, v116, v68, v186
	v_fma_f32 v186, v117, v70, v186
	v_fma_f32 v187, v115, v65, v73
	v_fma_f32 v187, v116, v67, v187
	v_fma_f32 v187, v117, v68, v187
	v_fma_f32 v187, v118, v70, v187
	v_fma_f32 v188, v116, v65, v73
	v_fma_f32 v188, v117, v67, v188
	v_fma_f32 v188, v118, v68, v188
	v_fma_f32 v188, v119, v70, v188
	v_fma_f32 v189, v117, v65, v73
	v_fma_f32 v189, v118, v67, v189
	v_fma_f32 v189, v119, v68, v189
	v_fma_f32 v189, v120, v70, v189
	v_fma_f32 v190, v118, v65, v73
	v_fma_f32 v190, v119, v67, v190
	v_fma_f32 v190, v120, v68, v190
	v_fma_f32 v190, v121, v70, v190
	v_fma_f32 v191, v119, v65, v73
	v_fma_f32 v191, v120, v67, v191
	v_fma_f32 v191, v121, v68, v191
	v_fma_f32 v191, v122, v70, v191
	v_fma_f32 v192, v120, v65, v73
	v_fma_f32 v192, v121, v67, v192
	v_fma_f32 v192, v122, v68, v192
	v_fma_f32 v192, v123, v70, v192
	v_fma_f32 v193, v121, v65, v73
	v_fma_f32 v193, v122, v67, v193
	v_fma_f32 v193, v123, v68, v193
	v_fma_f32 v193, v124, v70, v193
	v_cvt_pk_bf16_f32 v162, v162, v162
	v_cvt_pk_bf16_f32 v163, v163, v163
	v_cvt_pk_bf16_f32 v164, v164, v164
	v_cvt_pk_bf16_f32 v165, v165, v165
	v_cvt_pk_bf16_f32 v166, v166, v166
	v_cvt_pk_bf16_f32 v167, v167, v167
; __device__ __forceinline__ void lru_tile(const Params& P, int chunk, int head, int pass, char* smem_raw) {
;     ...
; #pragma unroll
;     for (int i = 0; i < 32; ++i) {
;       const float v = cb + uv[i] * w0 + uv[i + 1] * w1 + uv[i + 2] * w2 + uv[i + 3] * w3;
;       sm_uc[(q * 32 + i) * LDSS + ch] = f2bf(v);
;     }
;     ...
;   for (int d = 0; d < 2; ++d) {
;     __syncthreads();
; #pragma unroll
;     for (int i = 0; i < 4; ++i) {
;       const int idx = tid + 256 * i, rowi = idx >> 3, kg = idx & 7;
;       *reinterpret_cast<uint4*>(&sm_w[rowi * LDSS + kg * 8]) = ldg16(P.wg + ((long)(d * 8 + head) * 128 + rowi) * 64 + kg * 8);
;     }
;     float ba[4], bi[4], c8[4];
; #pragma unroll
;     for (int tc = 0; tc < 4; ++tc) {
;       const int cidx = d * 512 + head * 64 + 16 * tc + (lane & 15);
;       ba[tc] = P.b_a[cidx] * -1.4426950408889634f; bi[tc] = P.b_i[cidx] * -1.4426950408889634f;
;       const float nl = -P.lam[cidx];
;       const float e_ = __expf(nl);
;       const float sp = (nl > 20.f) ? nl
;                      : (e_ < 0.03f ? e_ * (1.f - e_ * (0.5f - e_ * (0.33333334f - 0.25f * e_))) : __logf(1.f + e_));
;       c8[tc] = 8.f * 1.4426950408889634f * sp;
;     }
;     __syncthreads();
;     float cA = 1.f, cB = (pass == 2) ? sm_init[d * 64 + ch] : 0.f;
;     for (int sbi = 0; sbi < 2; ++sbi) {
;       const int sb = (d == 0) ? sbi : 1 - sbi;
;       f32x4 acc[8];
; #pragma unroll
;       for (int t = 0; t < 8; ++t) acc[t] = f32x4{0.f, 0.f, 0.f, 0.f};
; #pragma unroll
;       for (int s = 0; s < 2; ++s) {
;         const bf16x8 af = *reinterpret_cast<const bf16x8*>(&sm_uc[(sb * 64 + wid * 16 + (lane & 15)) * LDSS + s * 32 + (lane >> 4) * 8]);
; #pragma unroll
;         for (int t = 0; t < 8; ++t) {
;           const bf16x8 bfr = *reinterpret_cast<const bf16x8*>(&sm_w[(t * 16 + (lane & 15)) * LDSS + s * 32 + (lane >> 4) * 8]);
;           acc[t] = __builtin_amdgcn_mfma_f32_16x16x32_bf16(af, bfr, acc[t], 0, 0, 0);
;         }
;       }
	v_cvt_pk_bf16_f32 v168, v168, v168
	v_cvt_pk_bf16_f32 v169, v169, v169
	v_cvt_pk_bf16_f32 v170, v170, v170
	v_cvt_pk_bf16_f32 v171, v171, v171
	v_cvt_pk_bf16_f32 v172, v172, v172
	v_cvt_pk_bf16_f32 v173, v173, v173
	v_cvt_pk_bf16_f32 v174, v174, v174
	v_cvt_pk_bf16_f32 v175, v175, v175
	v_cvt_pk_bf16_f32 v176, v176, v176
	v_cvt_pk_bf16_f32 v177, v177, v177
	v_cvt_pk_bf16_f32 v178, v178, v178
	v_cvt_pk_bf16_f32 v179, v179, v179
	v_cvt_pk_bf16_f32 v180, v180, v180
	v_cvt_pk_bf16_f32 v181, v181, v181
	v_cvt_pk_bf16_f32 v182, v182, v182
	v_cvt_pk_bf16_f32 v183, v183, v183
	v_cvt_pk_bf16_f32 v184, v184, v184
	v_cvt_pk_bf16_f32 v185, v185, v185
	v_cvt_pk_bf16_f32 v186, v186, v186
	v_cvt_pk_bf16_f32 v187, v187, v187
	v_cvt_pk_bf16_f32 v188, v188, v188
	v_cvt_pk_bf16_f32 v189, v189, v189
	v_cvt_pk_bf16_f32 v190, v190, v190
	v_cvt_pk_bf16_f32 v191, v191, v191
	v_cvt_pk_bf16_f32 v192, v192, v192
	v_cvt_pk_bf16_f32 v193, v193, v193
	ds_write_b16 v89, v162 offset:0
	ds_write_b16 v89, v163 offset:128
	ds_write_b16 v130, v164 offset:256
	ds_write_b16 v130, v165 offset:384
	ds_write_b16 v89, v166 offset:512
	ds_write_b16 v89, v167 offset:640
	ds_write_b16 v130, v168 offset:768
	ds_write_b16 v130, v169 offset:896
	ds_write_b16 v89, v170 offset:1024
	ds_write_b16 v89, v171 offset:1152
	ds_write_b16 v130, v172 offset:1280
	ds_write_b16 v130, v173 offset:1408
	ds_write_b16 v89, v174 offset:1536
	ds_write_b16 v89, v175 offset:1664
	ds_write_b16 v130, v176 offset:1792
	ds_write_b16 v130, v177 offset:1920
	ds_write_b16 v89, v178 offset:2048
	ds_write_b16 v89, v179 offset:2176
	ds_write_b16 v130, v180 offset:2304
	ds_write_b16 v130, v181 offset:2432
	ds_write_b16 v89, v182 offset:2560
	ds_write_b16 v89, v183 offset:2688
	ds_write_b16 v130, v184 offset:2816
	ds_write_b16 v130, v185 offset:2944
	ds_write_b16 v89, v186 offset:3072
	ds_write_b16 v89, v187 offset:3200
	ds_write_b16 v130, v188 offset:3328
	ds_write_b16 v130, v189 offset:3456
	ds_write_b16 v89, v190 offset:3584
	ds_write_b16 v89, v191 offset:3712
	ds_write_b16 v130, v192 offset:3840
	ds_write_b16 v130, v193 offset:3968
	v_lshlrev_b32_e32 v162, 16, v162
	v_lshlrev_b32_e32 v163, 16, v163
	v_lshlrev_b32_e32 v164, 16, v164
	v_lshlrev_b32_e32 v165, 16, v165
	v_lshlrev_b32_e32 v166, 16, v166
	v_lshlrev_b32_e32 v167, 16, v167
	v_lshlrev_b32_e32 v168, 16, v168
	v_lshlrev_b32_e32 v169, 16, v169
	v_lshlrev_b32_e32 v170, 16, v170
	v_lshlrev_b32_e32 v171, 16, v171
	v_lshlrev_b32_e32 v172, 16, v172
	v_lshlrev_b32_e32 v173, 16, v173
	v_lshlrev_b32_e32 v174, 16, v174
	v_lshlrev_b32_e32 v175, 16, v175
	v_lshlrev_b32_e32 v176, 16, v176
	v_lshlrev_b32_e32 v177, 16, v177
	v_lshlrev_b32_e32 v178, 16, v178
	v_lshlrev_b32_e32 v179, 16, v179
	v_lshlrev_b32_e32 v180, 16, v180
	v_lshlrev_b32_e32 v181, 16, v181
	v_lshlrev_b32_e32 v182, 16, v182
	v_lshlrev_b32_e32 v183, 16, v183
	v_lshlrev_b32_e32 v184, 16, v184
	v_lshlrev_b32_e32 v185, 16, v185
	v_lshlrev_b32_e32 v186, 16, v186
	v_lshlrev_b32_e32 v187, 16, v187
	v_lshlrev_b32_e32 v188, 16, v188
	v_lshlrev_b32_e32 v189, 16, v189
	v_lshlrev_b32_e32 v190, 16, v190
	v_lshlrev_b32_e32 v191, 16, v191
	v_lshlrev_b32_e32 v192, 16, v192
	v_lshlrev_b32_e32 v193, 16, v193
	s_waitcnt lgkmcnt(0)
	s_barrier
	s_lshl_b32 s0, s56, 8
	s_add_u32 s0, s0, 0x0
	s_add_u32 s4, s20, s0
	s_addc_u32 s5, s21, 0
	global_load_dwordx4 v[238:241], v251, s[4:5]
	global_load_dwordx4 v[242:245], v251, s[4:5] offset:64
	s_add_u32 s4, s4, 0x2000
	s_addc_u32 s5, s5, 0
	global_load_dwordx4 v[246:249], v251, s[4:5]
	global_load_dwordx4 v[194:197], v251, s[4:5] offset:64
	v_bfe_u32 v255, v152, 6, 2
	v_and_b32_e32 v253, 15, v152
	v_lshl_add_u32 v255, v255, 4, v253
	v_add_u32_e32 v255, s56, v255
	v_lshlrev_b32_e32 v255, 2, v255
	s_add_u32 s0, s28, 0x0
	s_addc_u32 s1, s29, 0
	global_load_dword v75, v255, s[0:1]
	s_add_u32 s0, s30, 0x0
	s_addc_u32 s1, s31, 0
	global_load_dword v84, v255, s[0:1]
	s_add_u32 s0, s36, 0x0
	s_addc_u32 s1, s37, 0
	global_load_dword v85, v255, s[0:1]
	ds_read_b128 v[76:79], v131 offset:0
	ds_read_b128 v[80:83], v133 offset:0
	ds_read_b128 v[122:125], v131 offset:512
	ds_read_b128 v[126:129], v133 offset:512
	s_waitcnt vmcnt(3)
	s_waitcnt lgkmcnt(3)
	v_mfma_f32_16x16x32_bf16 v[0:3], v[76:79], v[238:241], 0
	v_mfma_f32_16x16x32_bf16 v[90:93], v[76:79], v[246:249], 0
	ds_read_b128 v[76:79], v131 offset:1024
	s_waitcnt lgkmcnt(3)
	v_mfma_f32_16x16x32_bf16 v[0:3], v[80:83], v[242:245], v[0:3]
	v_mfma_f32_16x16x32_bf16 v[90:93], v[80:83], v[194:197], v[90:93]
	ds_read_b128 v[80:83], v133 offset:1024
	s_waitcnt lgkmcnt(3)
	v_mfma_f32_16x16x32_bf16 v[4:7], v[122:125], v[238:241], 0
	v_mfma_f32_16x16x32_bf16 v[94:97], v[122:125], v[246:249], 0
	ds_read_b128 v[122:125], v131 offset:1536
	s_waitcnt lgkmcnt(3)
	v_mfma_f32_16x16x32_bf16 v[4:7], v[126:129], v[242:245], v[4:7]
	v_mfma_f32_16x16x32_bf16 v[94:97], v[126:129], v[194:197], v[94:97]
	ds_read_b128 v[126:129], v133 offset:1536
	s_waitcnt lgkmcnt(3)
	v_mfma_f32_16x16x32_bf16 v[8:11], v[76:79], v[238:241], 0
	v_mfma_f32_16x16x32_bf16 v[98:101], v[76:79], v[246:249], 0
	ds_read_b128 v[76:79], v131 offset:2048
	s_waitcnt lgkmcnt(3)
	v_mfma_f32_16x16x32_bf16 v[8:11], v[80:83], v[242:245], v[8:11]
	v_mfma_f32_16x16x32_bf16 v[98:101], v[80:83], v[194:197], v[98:101]
	ds_read_b128 v[80:83], v133 offset:2048
	s_waitcnt lgkmcnt(3)
	v_mfma_f32_16x16x32_bf16 v[12:15], v[122:125], v[238:241], 0
	v_mfma_f32_16x16x32_bf16 v[102:105], v[122:125], v[246:249], 0
	ds_read_b128 v[122:125], v131 offset:2560
	s_waitcnt lgkmcnt(3)
	v_mfma_f32_16x16x32_bf16 v[12:15], v[126:129], v[242:245], v[12:15]
	v_mfma_f32_16x16x32_bf16 v[102:105], v[126:129], v[194:197], v[102:105]
	ds_read_b128 v[126:129], v133 offset:2560
	s_waitcnt lgkmcnt(3)
; __device__ __forceinline__ float bf2f(u16 h) { return __uint_as_float(((unsigned)h) << 16); }
; __device__ __forceinline__ void lru_tile(const Params& P, int chunk, int head, int pass, char* smem_raw) {
;     ...
; #pragma unroll
;     for (int tc = 0; tc < 4; ++tc) {
;       const int cidx = d * 512 + head * 64 + 16 * tc + (lane & 15);
;       ba[tc] = P.b_a[cidx] * -1.4426950408889634f; bi[tc] = P.b_i[cidx] * -1.4426950408889634f;
;       const float nl = -P.lam[cidx];
;       const float e_ = __expf(nl);
;       const float sp = (nl > 20.f) ? nl
;                      : (e_ < 0.03f ? e_ * (1.f - e_ * (0.5f - e_ * (0.33333334f - 0.25f * e_))) : __logf(1.f + e_));
;       c8[tc] = 8.f * 1.4426950408889634f * sp;
;     ...
; #pragma unroll
;       for (int t = 0; t < 8; ++t) acc[t] = f32x4{0.f, 0.f, 0.f, 0.f};
; #pragma unroll
;       for (int s = 0; s < 2; ++s) {
;         const bf16x8 af = *reinterpret_cast<const bf16x8*>(&sm_uc[(sb * 64 + wid * 16 + (lane & 15)) * LDSS + s * 32 + (lane >> 4) * 8]);
; #pragma unroll
;         for (int t = 0; t < 8; ++t) {
;           const bf16x8 bfr = *reinterpret_cast<const bf16x8*>(&sm_w[(t * 16 + (lane & 15)) * LDSS + s * 32 + (lane >> 4) * 8]);
;           acc[t] = __builtin_amdgcn_mfma_f32_16x16x32_bf16(af, bfr, acc[t], 0, 0, 0);
;         }
;       }
; #pragma unroll
;       for (int tc = 0; tc < 4; ++tc)
; #pragma unroll
;         for (int reg = 0; reg < 4; ++reg) {
;           const int tl = wid * 16 + (lane >> 4) * 4 + reg;
;           const int c = 16 * tc + (lane & 15);
;           const float r = __builtin_amdgcn_rcpf(1.f + __builtin_amdgcn_exp2f(acc[tc][reg] + ba[tc]));
;           const float ii = __builtin_amdgcn_rcpf(1.f + __builtin_amdgcn_exp2f(acc[tc + 4][reg] + bi[tc]));
;           const float la = -c8[tc] * r;
;           const float a = __builtin_amdgcn_exp2f(la);
;           const float ucv = bf2f(sm_uc[(sb * 64 + tl) * LDSS + c]);
;           const float bt = __builtin_amdgcn_sqrtf(fmaxf(1.f - a * a, 0.f)) * (ii * ucv);
;           sm_a[tl * 64 + c] = a;
;           sm_b[tl * 64 + c] = bt;
;         }
	v_mfma_f32_16x16x32_bf16 v[16:19], v[76:79], v[238:241], 0
	v_mfma_f32_16x16x32_bf16 v[106:109], v[76:79], v[246:249], 0
	ds_read_b128 v[76:79], v131 offset:3072
	s_waitcnt lgkmcnt(3)
	v_mfma_f32_16x16x32_bf16 v[16:19], v[80:83], v[242:245], v[16:19]
	v_mfma_f32_16x16x32_bf16 v[106:109], v[80:83], v[194:197], v[106:109]
	ds_read_b128 v[80:83], v133 offset:3072
	s_waitcnt lgkmcnt(3)
	v_mfma_f32_16x16x32_bf16 v[20:23], v[122:125], v[238:241], 0
	v_mfma_f32_16x16x32_bf16 v[110:113], v[122:125], v[246:249], 0
	ds_read_b128 v[122:125], v131 offset:3584
	s_waitcnt lgkmcnt(3)
	v_mfma_f32_16x16x32_bf16 v[20:23], v[126:129], v[242:245], v[20:23]
	v_mfma_f32_16x16x32_bf16 v[110:113], v[126:129], v[194:197], v[110:113]
	ds_read_b128 v[126:129], v133 offset:3584
	s_waitcnt lgkmcnt(3)
	v_mfma_f32_16x16x32_bf16 v[24:27], v[76:79], v[238:241], 0
	v_mfma_f32_16x16x32_bf16 v[114:117], v[76:79], v[246:249], 0
	s_waitcnt lgkmcnt(2)
	v_mfma_f32_16x16x32_bf16 v[24:27], v[80:83], v[242:245], v[24:27]
	v_mfma_f32_16x16x32_bf16 v[114:117], v[80:83], v[194:197], v[114:117]
	s_waitcnt lgkmcnt(1)
	v_mfma_f32_16x16x32_bf16 v[28:31], v[122:125], v[238:241], 0
	v_mfma_f32_16x16x32_bf16 v[118:121], v[122:125], v[246:249], 0
	s_waitcnt lgkmcnt(0)
	v_mfma_f32_16x16x32_bf16 v[28:31], v[126:129], v[242:245], v[28:31]
	v_mfma_f32_16x16x32_bf16 v[118:121], v[126:129], v[194:197], v[118:121]
	s_waitcnt vmcnt(0)
	v_mul_f32_e32 v75, 0xbfb8aa3b, v75
	v_mul_f32_e32 v84, 0xbfb8aa3b, v84
	v_sub_f32_e32 v138, 0, v85
	v_mul_f32_e32 v139, 0x3fb8aa3b, v138
	v_exp_f32_e32 v139, v139
	v_mul_f32_e32 v140, 0xbe800000, v139
	v_add_f32_e32 v140, 0x3eaaaaab, v140
	v_fma_f32 v140, -v139, v140, 0.5
	v_fma_f32 v140, -v139, v140, 1.0
	v_mul_f32_e32 v140, v139, v140
	v_add_f32_e32 v141, 1.0, v139
	v_log_f32_e32 v141, v141
	v_mov_b32_e32 v255, 0x3cf5c28f
	v_mul_f32_e32 v141, 0x3f317218, v141
	v_cmp_gt_f32_e32 vcc, v255, v139
	s_nop 1
	v_cndmask_b32_e32 v140, v141, v140, vcc
	v_mov_b32_e32 v255, 0x41a00000
	v_cmp_lt_f32_e32 vcc, v255, v138
	s_nop 1
	v_cndmask_b32_e32 v140, v140, v138, vcc
	v_mul_f32_e32 v85, 0xc138aa3b, v140
	s_nop 7
	v_add_f32_e32 v0, v0, v75
	v_add_f32_e32 v1, v1, v75
	v_add_f32_e32 v2, v2, v75
	v_add_f32_e32 v3, v3, v75
	v_add_f32_e32 v90, v90, v84
	v_add_f32_e32 v91, v91, v84
	v_add_f32_e32 v92, v92, v84
	v_add_f32_e32 v93, v93, v84
	v_exp_f32_e32 v0, v0
	v_exp_f32_e32 v1, v1
	v_exp_f32_e32 v2, v2
	v_exp_f32_e32 v3, v3
	v_exp_f32_e32 v90, v90
	v_exp_f32_e32 v91, v91
	v_exp_f32_e32 v92, v92
	v_exp_f32_e32 v93, v93
	v_add_f32_e32 v0, 1.0, v0
	v_add_f32_e32 v1, 1.0, v1
	v_add_f32_e32 v2, 1.0, v2
	v_add_f32_e32 v3, 1.0, v3
	v_add_f32_e32 v90, 1.0, v90
	v_add_f32_e32 v91, 1.0, v91
	v_add_f32_e32 v92, 1.0, v92
	v_add_f32_e32 v93, 1.0, v93
	v_rcp_f32_e32 v0, v0
	v_rcp_f32_e32 v1, v1
	v_rcp_f32_e32 v2, v2
	v_rcp_f32_e32 v3, v3
	v_rcp_f32_e32 v90, v90
	v_rcp_f32_e32 v91, v91
	v_rcp_f32_e32 v92, v92
	v_rcp_f32_e32 v93, v93
	v_mul_f32_e32 v0, v85, v0
	v_mul_f32_e32 v1, v85, v1
	v_mul_f32_e32 v2, v85, v2
	v_mul_f32_e32 v3, v85, v3
	v_mul_f32_e32 v90, v90, v162
	v_mul_f32_e32 v91, v91, v163
	v_mul_f32_e32 v92, v92, v164
	v_mul_f32_e32 v93, v93, v165
	v_exp_f32_e32 v0, v0
	v_exp_f32_e32 v1, v1
	v_exp_f32_e32 v2, v2
	v_exp_f32_e32 v3, v3
	s_nop 0
	v_fma_f32 v138, -v0, v0, 1.0
	v_fma_f32 v139, -v1, v1, 1.0
	v_fma_f32 v140, -v2, v2, 1.0
	v_fma_f32 v141, -v3, v3, 1.0
	v_max_f32_e32 v138, 0, v138
	v_max_f32_e32 v139, 0, v139
	v_max_f32_e32 v140, 0, v140
	v_max_f32_e32 v141, 0, v141
	v_sqrt_f32_e32 v138, v138
	v_sqrt_f32_e32 v139, v139
	v_sqrt_f32_e32 v140, v140
	v_sqrt_f32_e32 v141, v141
	s_nop 0
	v_mul_f32_e32 v90, v138, v90
	v_mul_f32_e32 v91, v139, v91
	v_mul_f32_e32 v92, v140, v92
	v_mul_f32_e32 v93, v141, v93
	v_add_f32_e32 v4, v4, v75
	v_add_f32_e32 v5, v5, v75
	v_add_f32_e32 v6, v6, v75
	v_add_f32_e32 v7, v7, v75
	v_add_f32_e32 v94, v94, v84
	v_add_f32_e32 v95, v95, v84
	v_add_f32_e32 v96, v96, v84
	v_add_f32_e32 v97, v97, v84
	v_exp_f32_e32 v4, v4
	v_exp_f32_e32 v5, v5
	v_exp_f32_e32 v6, v6
	v_exp_f32_e32 v7, v7
	v_exp_f32_e32 v94, v94
	v_exp_f32_e32 v95, v95
	v_exp_f32_e32 v96, v96
	v_exp_f32_e32 v97, v97
	v_add_f32_e32 v4, 1.0, v4
	v_add_f32_e32 v5, 1.0, v5
	v_add_f32_e32 v6, 1.0, v6
	v_add_f32_e32 v7, 1.0, v7
	v_add_f32_e32 v94, 1.0, v94
	v_add_f32_e32 v95, 1.0, v95
	v_add_f32_e32 v96, 1.0, v96
	v_add_f32_e32 v97, 1.0, v97
	v_rcp_f32_e32 v4, v4
	v_rcp_f32_e32 v5, v5
	v_rcp_f32_e32 v6, v6
	v_rcp_f32_e32 v7, v7
	v_rcp_f32_e32 v94, v94
	v_rcp_f32_e32 v95, v95
	v_rcp_f32_e32 v96, v96
	v_rcp_f32_e32 v97, v97
	v_mul_f32_e32 v4, v85, v4
	v_mul_f32_e32 v5, v85, v5
	v_mul_f32_e32 v6, v85, v6
	v_mul_f32_e32 v7, v85, v7
	v_mul_f32_e32 v94, v94, v166
	v_mul_f32_e32 v95, v95, v167
	v_mul_f32_e32 v96, v96, v168
	v_mul_f32_e32 v97, v97, v169
	v_exp_f32_e32 v4, v4
	v_exp_f32_e32 v5, v5
	v_exp_f32_e32 v6, v6
	v_exp_f32_e32 v7, v7
	s_nop 0
	v_fma_f32 v138, -v4, v4, 1.0
	v_fma_f32 v139, -v5, v5, 1.0
	v_fma_f32 v140, -v6, v6, 1.0
	v_fma_f32 v141, -v7, v7, 1.0
	v_max_f32_e32 v138, 0, v138
	v_max_f32_e32 v139, 0, v139
	v_max_f32_e32 v140, 0, v140
	v_max_f32_e32 v141, 0, v141
	v_sqrt_f32_e32 v138, v138
	v_sqrt_f32_e32 v139, v139
	v_sqrt_f32_e32 v140, v140
	v_sqrt_f32_e32 v141, v141
	s_nop 0
	v_mul_f32_e32 v94, v138, v94
	v_mul_f32_e32 v95, v139, v95
	v_mul_f32_e32 v96, v140, v96
	v_mul_f32_e32 v97, v141, v97
	v_add_f32_e32 v8, v8, v75
	v_add_f32_e32 v9, v9, v75
	v_add_f32_e32 v10, v10, v75
	v_add_f32_e32 v11, v11, v75
	v_add_f32_e32 v98, v98, v84
	v_add_f32_e32 v99, v99, v84
	v_add_f32_e32 v100, v100, v84
	v_add_f32_e32 v101, v101, v84
	v_exp_f32_e32 v8, v8
	v_exp_f32_e32 v9, v9
	v_exp_f32_e32 v10, v10
; __device__ __forceinline__ float bf2f(u16 h) { return __uint_as_float(((unsigned)h) << 16); }
; __device__ __forceinline__ void lru_tile(const Params& P, int chunk, int head, int pass, char* smem_raw) {
;     ...
;       for (int tc = 0; tc < 4; ++tc)
; #pragma unroll
;         for (int reg = 0; reg < 4; ++reg) {
;           const int tl = wid * 16 + (lane >> 4) * 4 + reg;
;           const int c = 16 * tc + (lane & 15);
;           const float r = __builtin_amdgcn_rcpf(1.f + __builtin_amdgcn_exp2f(acc[tc][reg] + ba[tc]));
;           const float ii = __builtin_amdgcn_rcpf(1.f + __builtin_amdgcn_exp2f(acc[tc + 4][reg] + bi[tc]));
;           const float la = -c8[tc] * r;
;           const float a = __builtin_amdgcn_exp2f(la);
;           const float ucv = bf2f(sm_uc[(sb * 64 + tl) * LDSS + c]);
;           const float bt = __builtin_amdgcn_sqrtf(fmaxf(1.f - a * a, 0.f)) * (ii * ucv);
;           sm_a[tl * 64 + c] = a;
;           sm_b[tl * 64 + c] = bt;
;         }
	v_exp_f32_e32 v11, v11
	v_exp_f32_e32 v98, v98
	v_exp_f32_e32 v99, v99
	v_exp_f32_e32 v100, v100
	v_exp_f32_e32 v101, v101
	v_add_f32_e32 v8, 1.0, v8
	v_add_f32_e32 v9, 1.0, v9
	v_add_f32_e32 v10, 1.0, v10
	v_add_f32_e32 v11, 1.0, v11
	v_add_f32_e32 v98, 1.0, v98
	v_add_f32_e32 v99, 1.0, v99
	v_add_f32_e32 v100, 1.0, v100
	v_add_f32_e32 v101, 1.0, v101
	v_rcp_f32_e32 v8, v8
	v_rcp_f32_e32 v9, v9
	v_rcp_f32_e32 v10, v10
	v_rcp_f32_e32 v11, v11
	v_rcp_f32_e32 v98, v98
	v_rcp_f32_e32 v99, v99
	v_rcp_f32_e32 v100, v100
	v_rcp_f32_e32 v101, v101
	v_mul_f32_e32 v8, v85, v8
	v_mul_f32_e32 v9, v85, v9
	v_mul_f32_e32 v10, v85, v10
	v_mul_f32_e32 v11, v85, v11
	v_mul_f32_e32 v98, v98, v170
	v_mul_f32_e32 v99, v99, v171
	v_mul_f32_e32 v100, v100, v172
	v_mul_f32_e32 v101, v101, v173
	v_exp_f32_e32 v8, v8
	v_exp_f32_e32 v9, v9
	v_exp_f32_e32 v10, v10
	v_exp_f32_e32 v11, v11
	s_nop 0
	v_fma_f32 v138, -v8, v8, 1.0
	v_fma_f32 v139, -v9, v9, 1.0
	v_fma_f32 v140, -v10, v10, 1.0
	v_fma_f32 v141, -v11, v11, 1.0
	v_max_f32_e32 v138, 0, v138
	v_max_f32_e32 v139, 0, v139
	v_max_f32_e32 v140, 0, v140
	v_max_f32_e32 v141, 0, v141
	v_sqrt_f32_e32 v138, v138
	v_sqrt_f32_e32 v139, v139
	v_sqrt_f32_e32 v140, v140
	v_sqrt_f32_e32 v141, v141
	s_nop 0
	v_mul_f32_e32 v98, v138, v98
	v_mul_f32_e32 v99, v139, v99
	v_mul_f32_e32 v100, v140, v100
	v_mul_f32_e32 v101, v141, v101
	v_add_f32_e32 v12, v12, v75
	v_add_f32_e32 v13, v13, v75
	v_add_f32_e32 v14, v14, v75
	v_add_f32_e32 v15, v15, v75
	v_add_f32_e32 v102, v102, v84
	v_add_f32_e32 v103, v103, v84
	v_add_f32_e32 v104, v104, v84
	v_add_f32_e32 v105, v105, v84
	v_exp_f32_e32 v12, v12
	v_exp_f32_e32 v13, v13
	v_exp_f32_e32 v14, v14
	v_exp_f32_e32 v15, v15
	v_exp_f32_e32 v102, v102
	v_exp_f32_e32 v103, v103
	v_exp_f32_e32 v104, v104
	v_exp_f32_e32 v105, v105
	v_add_f32_e32 v12, 1.0, v12
	v_add_f32_e32 v13, 1.0, v13
	v_add_f32_e32 v14, 1.0, v14
	v_add_f32_e32 v15, 1.0, v15
	v_add_f32_e32 v102, 1.0, v102
	v_add_f32_e32 v103, 1.0, v103
	v_add_f32_e32 v104, 1.0, v104
	v_add_f32_e32 v105, 1.0, v105
	v_rcp_f32_e32 v12, v12
	v_rcp_f32_e32 v13, v13
	v_rcp_f32_e32 v14, v14
	v_rcp_f32_e32 v15, v15
	v_rcp_f32_e32 v102, v102
	v_rcp_f32_e32 v103, v103
	v_rcp_f32_e32 v104, v104
	v_rcp_f32_e32 v105, v105
	v_mul_f32_e32 v12, v85, v12
	v_mul_f32_e32 v13, v85, v13
	v_mul_f32_e32 v14, v85, v14
	v_mul_f32_e32 v15, v85, v15
	v_mul_f32_e32 v102, v102, v174
	v_mul_f32_e32 v103, v103, v175
	v_mul_f32_e32 v104, v104, v176
	v_mul_f32_e32 v105, v105, v177
	v_exp_f32_e32 v12, v12
	v_exp_f32_e32 v13, v13
	v_exp_f32_e32 v14, v14
	v_exp_f32_e32 v15, v15
	s_nop 0
	v_fma_f32 v138, -v12, v12, 1.0
	v_fma_f32 v139, -v13, v13, 1.0
	v_fma_f32 v140, -v14, v14, 1.0
	v_fma_f32 v141, -v15, v15, 1.0
	v_max_f32_e32 v138, 0, v138
	v_max_f32_e32 v139, 0, v139
	v_max_f32_e32 v140, 0, v140
	v_max_f32_e32 v141, 0, v141
	v_sqrt_f32_e32 v138, v138
	v_sqrt_f32_e32 v139, v139
	v_sqrt_f32_e32 v140, v140
	v_sqrt_f32_e32 v141, v141
	s_nop 0
	v_mul_f32_e32 v102, v138, v102
	v_mul_f32_e32 v103, v139, v103
	v_mul_f32_e32 v104, v140, v104
	v_mul_f32_e32 v105, v141, v105
	v_add_f32_e32 v16, v16, v75
	v_add_f32_e32 v17, v17, v75
	v_add_f32_e32 v18, v18, v75
	v_add_f32_e32 v19, v19, v75
	v_add_f32_e32 v106, v106, v84
	v_add_f32_e32 v107, v107, v84
	v_add_f32_e32 v108, v108, v84
	v_add_f32_e32 v109, v109, v84
	v_exp_f32_e32 v16, v16
	v_exp_f32_e32 v17, v17
	v_exp_f32_e32 v18, v18
	v_exp_f32_e32 v19, v19
	v_exp_f32_e32 v106, v106
	v_exp_f32_e32 v107, v107
	v_exp_f32_e32 v108, v108
	v_exp_f32_e32 v109, v109
	v_add_f32_e32 v16, 1.0, v16
	v_add_f32_e32 v17, 1.0, v17
	v_add_f32_e32 v18, 1.0, v18
	v_add_f32_e32 v19, 1.0, v19
	v_add_f32_e32 v106, 1.0, v106
	v_add_f32_e32 v107, 1.0, v107
	v_add_f32_e32 v108, 1.0, v108
	v_add_f32_e32 v109, 1.0, v109
	v_rcp_f32_e32 v16, v16
	v_rcp_f32_e32 v17, v17
	v_rcp_f32_e32 v18, v18
	v_rcp_f32_e32 v19, v19
	v_rcp_f32_e32 v106, v106
	v_rcp_f32_e32 v107, v107
	v_rcp_f32_e32 v108, v108
	v_rcp_f32_e32 v109, v109
	v_mul_f32_e32 v16, v85, v16
	v_mul_f32_e32 v17, v85, v17
	v_mul_f32_e32 v18, v85, v18
	v_mul_f32_e32 v19, v85, v19
	v_mul_f32_e32 v106, v106, v178
	v_mul_f32_e32 v107, v107, v179
	v_mul_f32_e32 v108, v108, v180
	v_mul_f32_e32 v109, v109, v181
	v_exp_f32_e32 v16, v16
	v_exp_f32_e32 v17, v17
	v_exp_f32_e32 v18, v18
	v_exp_f32_e32 v19, v19
	s_nop 0
	v_fma_f32 v138, -v16, v16, 1.0
	v_fma_f32 v139, -v17, v17, 1.0
	v_fma_f32 v140, -v18, v18, 1.0
	v_fma_f32 v141, -v19, v19, 1.0
	v_max_f32_e32 v138, 0, v138
	v_max_f32_e32 v139, 0, v139
	v_max_f32_e32 v140, 0, v140
	v_max_f32_e32 v141, 0, v141
	v_sqrt_f32_e32 v138, v138
	v_sqrt_f32_e32 v139, v139
	v_sqrt_f32_e32 v140, v140
	v_sqrt_f32_e32 v141, v141
	s_nop 0
	v_mul_f32_e32 v106, v138, v106
	v_mul_f32_e32 v107, v139, v107
	v_mul_f32_e32 v108, v140, v108
	v_mul_f32_e32 v109, v141, v109
	v_add_f32_e32 v20, v20, v75
	v_add_f32_e32 v21, v21, v75
	v_add_f32_e32 v22, v22, v75
	v_add_f32_e32 v23, v23, v75
	v_add_f32_e32 v110, v110, v84
	v_add_f32_e32 v111, v111, v84
	v_add_f32_e32 v112, v112, v84
	v_add_f32_e32 v113, v113, v84
	v_exp_f32_e32 v20, v20
	v_exp_f32_e32 v21, v21
	v_exp_f32_e32 v22, v22
	v_exp_f32_e32 v23, v23
	v_exp_f32_e32 v110, v110
	v_exp_f32_e32 v111, v111
	v_exp_f32_e32 v112, v112
	v_exp_f32_e32 v113, v113
	v_add_f32_e32 v20, 1.0, v20
	v_add_f32_e32 v21, 1.0, v21
	v_add_f32_e32 v22, 1.0, v22
	v_add_f32_e32 v23, 1.0, v23
	v_add_f32_e32 v110, 1.0, v110
	v_add_f32_e32 v111, 1.0, v111
	v_add_f32_e32 v112, 1.0, v112
	v_add_f32_e32 v113, 1.0, v113
	v_rcp_f32_e32 v20, v20
	v_rcp_f32_e32 v21, v21
	v_rcp_f32_e32 v22, v22
	v_rcp_f32_e32 v23, v23
	v_rcp_f32_e32 v110, v110
	v_rcp_f32_e32 v111, v111
; __device__ __forceinline__ float bf2f(u16 h) { return __uint_as_float(((unsigned)h) << 16); }
; __device__ __forceinline__ void lru_tile(const Params& P, int chunk, int head, int pass, char* smem_raw) {
;     ...
;       for (int tc = 0; tc < 4; ++tc)
; #pragma unroll
;         for (int reg = 0; reg < 4; ++reg) {
;           const int tl = wid * 16 + (lane >> 4) * 4 + reg;
;           const int c = 16 * tc + (lane & 15);
;           const float r = __builtin_amdgcn_rcpf(1.f + __builtin_amdgcn_exp2f(acc[tc][reg] + ba[tc]));
;           const float ii = __builtin_amdgcn_rcpf(1.f + __builtin_amdgcn_exp2f(acc[tc + 4][reg] + bi[tc]));
;           const float la = -c8[tc] * r;
;           const float a = __builtin_amdgcn_exp2f(la);
;           const float ucv = bf2f(sm_uc[(sb * 64 + tl) * LDSS + c]);
;           const float bt = __builtin_amdgcn_sqrtf(fmaxf(1.f - a * a, 0.f)) * (ii * ucv);
;           sm_a[tl * 64 + c] = a;
;           sm_b[tl * 64 + c] = bt;
;         }
;       __syncthreads();
;       const int pos = (d == 0) ? q : 3 - q;
;       {
;         float Pp = 1.f, H = 0.f;
; #pragma unroll 4
;         for (int i = 0; i < 16; ++i) {
;           const int tl = (d == 0) ? (q * 16 + i) : (q * 16 + 15 - i);
;           const float a = sm_a[tl * 64 + ch], b = sm_b[tl * 64 + ch];
;           H = a * H + b; Pp *= a;
;         }
;         sm_ph[pos * 64 + ch] = make_float2(Pp, H);
	v_rcp_f32_e32 v112, v112
	v_rcp_f32_e32 v113, v113
	v_mul_f32_e32 v20, v85, v20
	v_mul_f32_e32 v21, v85, v21
	v_mul_f32_e32 v22, v85, v22
	v_mul_f32_e32 v23, v85, v23
	v_mul_f32_e32 v110, v110, v182
	v_mul_f32_e32 v111, v111, v183
	v_mul_f32_e32 v112, v112, v184
	v_mul_f32_e32 v113, v113, v185
	v_exp_f32_e32 v20, v20
	v_exp_f32_e32 v21, v21
	v_exp_f32_e32 v22, v22
	v_exp_f32_e32 v23, v23
	s_nop 0
	v_fma_f32 v138, -v20, v20, 1.0
	v_fma_f32 v139, -v21, v21, 1.0
	v_fma_f32 v140, -v22, v22, 1.0
	v_fma_f32 v141, -v23, v23, 1.0
	v_max_f32_e32 v138, 0, v138
	v_max_f32_e32 v139, 0, v139
	v_max_f32_e32 v140, 0, v140
	v_max_f32_e32 v141, 0, v141
	v_sqrt_f32_e32 v138, v138
	v_sqrt_f32_e32 v139, v139
	v_sqrt_f32_e32 v140, v140
	v_sqrt_f32_e32 v141, v141
	s_nop 0
	v_mul_f32_e32 v110, v138, v110
	v_mul_f32_e32 v111, v139, v111
	v_mul_f32_e32 v112, v140, v112
	v_mul_f32_e32 v113, v141, v113
	v_add_f32_e32 v24, v24, v75
	v_add_f32_e32 v25, v25, v75
	v_add_f32_e32 v26, v26, v75
	v_add_f32_e32 v27, v27, v75
	v_add_f32_e32 v114, v114, v84
	v_add_f32_e32 v115, v115, v84
	v_add_f32_e32 v116, v116, v84
	v_add_f32_e32 v117, v117, v84
	v_exp_f32_e32 v24, v24
	v_exp_f32_e32 v25, v25
	v_exp_f32_e32 v26, v26
	v_exp_f32_e32 v27, v27
	v_exp_f32_e32 v114, v114
	v_exp_f32_e32 v115, v115
	v_exp_f32_e32 v116, v116
	v_exp_f32_e32 v117, v117
	v_add_f32_e32 v24, 1.0, v24
	v_add_f32_e32 v25, 1.0, v25
	v_add_f32_e32 v26, 1.0, v26
	v_add_f32_e32 v27, 1.0, v27
	v_add_f32_e32 v114, 1.0, v114
	v_add_f32_e32 v115, 1.0, v115
	v_add_f32_e32 v116, 1.0, v116
	v_add_f32_e32 v117, 1.0, v117
	v_rcp_f32_e32 v24, v24
	v_rcp_f32_e32 v25, v25
	v_rcp_f32_e32 v26, v26
	v_rcp_f32_e32 v27, v27
	v_rcp_f32_e32 v114, v114
	v_rcp_f32_e32 v115, v115
	v_rcp_f32_e32 v116, v116
	v_rcp_f32_e32 v117, v117
	v_mul_f32_e32 v24, v85, v24
	v_mul_f32_e32 v25, v85, v25
	v_mul_f32_e32 v26, v85, v26
	v_mul_f32_e32 v27, v85, v27
	v_mul_f32_e32 v114, v114, v186
	v_mul_f32_e32 v115, v115, v187
	v_mul_f32_e32 v116, v116, v188
	v_mul_f32_e32 v117, v117, v189
	v_exp_f32_e32 v24, v24
	v_exp_f32_e32 v25, v25
	v_exp_f32_e32 v26, v26
	v_exp_f32_e32 v27, v27
	s_nop 0
	v_fma_f32 v138, -v24, v24, 1.0
	v_fma_f32 v139, -v25, v25, 1.0
	v_fma_f32 v140, -v26, v26, 1.0
	v_fma_f32 v141, -v27, v27, 1.0
	v_max_f32_e32 v138, 0, v138
	v_max_f32_e32 v139, 0, v139
	v_max_f32_e32 v140, 0, v140
	v_max_f32_e32 v141, 0, v141
	v_sqrt_f32_e32 v138, v138
	v_sqrt_f32_e32 v139, v139
	v_sqrt_f32_e32 v140, v140
	v_sqrt_f32_e32 v141, v141
	s_nop 0
	v_mul_f32_e32 v114, v138, v114
	v_mul_f32_e32 v115, v139, v115
	v_mul_f32_e32 v116, v140, v116
	v_mul_f32_e32 v117, v141, v117
	v_add_f32_e32 v28, v28, v75
	v_add_f32_e32 v29, v29, v75
	v_add_f32_e32 v30, v30, v75
	v_add_f32_e32 v31, v31, v75
	v_add_f32_e32 v118, v118, v84
	v_add_f32_e32 v119, v119, v84
	v_add_f32_e32 v120, v120, v84
	v_add_f32_e32 v121, v121, v84
	v_exp_f32_e32 v28, v28
	v_exp_f32_e32 v29, v29
	v_exp_f32_e32 v30, v30
	v_exp_f32_e32 v31, v31
	v_exp_f32_e32 v118, v118
	v_exp_f32_e32 v119, v119
	v_exp_f32_e32 v120, v120
	v_exp_f32_e32 v121, v121
	v_add_f32_e32 v28, 1.0, v28
	v_add_f32_e32 v29, 1.0, v29
	v_add_f32_e32 v30, 1.0, v30
	v_add_f32_e32 v31, 1.0, v31
	v_add_f32_e32 v118, 1.0, v118
	v_add_f32_e32 v119, 1.0, v119
	v_add_f32_e32 v120, 1.0, v120
	v_add_f32_e32 v121, 1.0, v121
	v_rcp_f32_e32 v28, v28
	v_rcp_f32_e32 v29, v29
	v_rcp_f32_e32 v30, v30
	v_rcp_f32_e32 v31, v31
	v_rcp_f32_e32 v118, v118
	v_rcp_f32_e32 v119, v119
	v_rcp_f32_e32 v120, v120
	v_rcp_f32_e32 v121, v121
	v_mul_f32_e32 v28, v85, v28
	v_mul_f32_e32 v29, v85, v29
	v_mul_f32_e32 v30, v85, v30
	v_mul_f32_e32 v31, v85, v31
	v_mul_f32_e32 v118, v118, v190
	v_mul_f32_e32 v119, v119, v191
	v_mul_f32_e32 v120, v120, v192
	v_mul_f32_e32 v121, v121, v193
	v_exp_f32_e32 v28, v28
	v_exp_f32_e32 v29, v29
	v_exp_f32_e32 v30, v30
	v_exp_f32_e32 v31, v31
	s_nop 0
	v_fma_f32 v138, -v28, v28, 1.0
	v_fma_f32 v139, -v29, v29, 1.0
	v_fma_f32 v140, -v30, v30, 1.0
	v_fma_f32 v141, -v31, v31, 1.0
	v_max_f32_e32 v138, 0, v138
	v_max_f32_e32 v139, 0, v139
	v_max_f32_e32 v140, 0, v140
	v_max_f32_e32 v141, 0, v141
	v_sqrt_f32_e32 v138, v138
	v_sqrt_f32_e32 v139, v139
	v_sqrt_f32_e32 v140, v140
	v_sqrt_f32_e32 v141, v141
	s_nop 0
	v_mul_f32_e32 v118, v138, v118
	v_mul_f32_e32 v119, v139, v119
	v_mul_f32_e32 v120, v140, v120
	v_mul_f32_e32 v121, v141, v121
	v_mov_b32_e32 v253, v0
	v_mov_b32_e32 v254, v90
	v_fma_f32 v254, v1, v254, v91
	v_mul_f32_e32 v253, v253, v1
	v_fma_f32 v254, v2, v254, v92
	v_mul_f32_e32 v253, v253, v2
	v_fma_f32 v254, v3, v254, v93
	v_mul_f32_e32 v253, v253, v3
	v_fma_f32 v254, v4, v254, v94
	v_mul_f32_e32 v253, v253, v4
	v_fma_f32 v254, v5, v254, v95
	v_mul_f32_e32 v253, v253, v5
	v_fma_f32 v254, v6, v254, v96
	v_mul_f32_e32 v253, v253, v6
	v_fma_f32 v254, v7, v254, v97
	v_mul_f32_e32 v253, v253, v7
	v_fma_f32 v254, v8, v254, v98
	v_mul_f32_e32 v253, v253, v8
	v_fma_f32 v254, v9, v254, v99
	v_mul_f32_e32 v253, v253, v9
	v_fma_f32 v254, v10, v254, v100
	v_mul_f32_e32 v253, v253, v10
	v_fma_f32 v254, v11, v254, v101
	v_mul_f32_e32 v253, v253, v11
	v_fma_f32 v254, v12, v254, v102
	v_mul_f32_e32 v253, v253, v12
	v_fma_f32 v254, v13, v254, v103
	v_mul_f32_e32 v253, v253, v13
	v_fma_f32 v254, v14, v254, v104
	v_mul_f32_e32 v253, v253, v14
	v_fma_f32 v254, v15, v254, v105
	v_mul_f32_e32 v253, v253, v15
	v_fma_f32 v254, v16, v254, v106
	v_mul_f32_e32 v253, v253, v16
	v_fma_f32 v254, v17, v254, v107
	v_mul_f32_e32 v253, v253, v17
	v_fma_f32 v254, v18, v254, v108
	v_mul_f32_e32 v253, v253, v18
	v_fma_f32 v254, v19, v254, v109
	v_mul_f32_e32 v253, v253, v19
	v_fma_f32 v254, v20, v254, v110
	v_mul_f32_e32 v253, v253, v20
; __device__ __forceinline__ float bf2f(u16 h) { return __uint_as_float(((unsigned)h) << 16); }
; __device__ __forceinline__ void lru_tile(const Params& P, int chunk, int head, int pass, char* smem_raw) {
;     ...
;         float Pp = 1.f, H = 0.f;
; #pragma unroll 4
;         for (int i = 0; i < 16; ++i) {
;           const int tl = (d == 0) ? (q * 16 + i) : (q * 16 + 15 - i);
;           const float a = sm_a[tl * 64 + ch], b = sm_b[tl * 64 + ch];
;           H = a * H + b; Pp *= a;
;         }
;         sm_ph[pos * 64 + ch] = make_float2(Pp, H);
;       }
;       __syncthreads();
;       const float2 p0 = sm_ph[ch], p1 = sm_ph[64 + ch], p2 = sm_ph[128 + ch], p3 = sm_ph[192 + ch];
;       if (pass == 2) {
;         float hin = cB;
;         if (pos > 0) hin = p0.x * hin + p0.y;
;         if (pos > 1) hin = p1.x * hin + p1.y;
;         if (pos > 2) hin = p2.x * hin + p2.y;
;         float h = hin;
;         float hfp[16], gp[16];
;         if (d == 1) {
; #pragma unroll
;           for (int i = 0; i < 16; ++i) {
;             const long rowp = row0 + sb * 64 + q * 16 + 15 - i;
;             hfp[i] = hfbuf[rowp * 512 + gch];
;             gp[i] = bf2f(P.zq[rowp * 1536 + 512 + gch]);
;           }
;         }
; #pragma unroll
;         for (int i = 0; i < 16; ++i) {
;           const int tl = (d == 0) ? (q * 16 + i) : (q * 16 + 15 - i);
;           const float a = sm_a[tl * 64 + ch], b = sm_b[tl * 64 + ch];
;           h = a * h + b;
;           const long row = row0 + sb * 64 + tl;
;           if (d == 0) {
;             hfw[row * 512 + gch] = h;
;           } else {
;             const float hfv = hfp[i];
;             const float g = gp[i];
;             const float tz = 0.7978845608028654f * (g + 0.044715f * g * g * g);
;             const float th = 1.f - 2.f * __builtin_amdgcn_rcpf(1.f + __expf(2.f * tz));
;             const float ge = 0.5f * g * (1.f + th);
;             P.cat[row * 1024 + gch] = f2bf((hfv + h) * ge);
;           }
;         }
;       }
;       cB = p0.x * cB + p0.y; cA *= p0.x;
;       cB = p1.x * cB + p1.y; cA *= p1.x;
;       cB = p2.x * cB + p2.y; cA *= p2.x;
;       cB = p3.x * cB + p3.y; cA *= p3.x;
;       __syncthreads();
;     }
;     if (pass == 1 && q == 0) P.summ[((long)d * 264 + chunk) * 512 + gch] = make_float2(cA, cB);
	v_fma_f32 v254, v21, v254, v111
	v_mul_f32_e32 v253, v253, v21
	v_fma_f32 v254, v22, v254, v112
	v_mul_f32_e32 v253, v253, v22
	v_fma_f32 v254, v23, v254, v113
	v_mul_f32_e32 v253, v253, v23
	v_fma_f32 v254, v24, v254, v114
	v_mul_f32_e32 v253, v253, v24
	v_fma_f32 v254, v25, v254, v115
	v_mul_f32_e32 v253, v253, v25
	v_fma_f32 v254, v26, v254, v116
	v_mul_f32_e32 v253, v253, v26
	v_fma_f32 v254, v27, v254, v117
	v_mul_f32_e32 v253, v253, v27
	v_fma_f32 v254, v28, v254, v118
	v_mul_f32_e32 v253, v253, v28
	v_fma_f32 v254, v29, v254, v119
	v_mul_f32_e32 v253, v253, v29
	v_fma_f32 v254, v30, v254, v120
	v_mul_f32_e32 v253, v253, v30
	v_fma_f32 v254, v31, v254, v121
	v_mul_f32_e32 v253, v253, v31
	v_mov_b32_e32 v138, v253
	v_mov_b32_e32 v139, v253
	s_nop 1
	v_permlane16_swap_b32_e32 v138, v139
	v_mov_b32_e32 v140, v138
	v_mov_b32_e32 v141, v139
	s_nop 1
	v_permlane32_swap_b32_e32 v138, v140
	v_permlane32_swap_b32_e32 v139, v141
	v_mov_b32_e32 v198, v254
	v_mov_b32_e32 v199, v254
	s_nop 1
	v_permlane16_swap_b32_e32 v198, v199
	v_mov_b32_e32 v200, v198
	v_mov_b32_e32 v201, v199
	s_nop 1
	v_permlane32_swap_b32_e32 v198, v200
	v_permlane32_swap_b32_e32 v199, v201
	v_mov_b32_e32 v136, 0
	v_fma_f32 v150, v138, v136, v198
	v_fma_f32 v151, v139, v150, v199
	v_fma_f32 v202, v140, v151, v200
	v_fma_f32 v254, v141, v202, v201
	v_mul_f32_e32 v253, v138, v139
	v_mul_f32_e32 v253, v253, v140
	v_mul_f32_e32 v200, v253, v141
	v_mov_b32_e32 v201, v254
	s_add_u32 s0, s71, 0
	s_lshl_b32 s0, s0, 12
	s_lshl_b32 s1, s56, 3
	s_add_u32 s0, s0, s1
	s_add_u32 s4, s18, s0
	s_addc_u32 s5, s19, 0
	global_store_dwordx2 v250, v[200:201], s[4:5]
	s_lshl_b32 s0, s56, 8
	s_add_u32 s0, s0, 0x20000
	s_add_u32 s4, s20, s0
	s_addc_u32 s5, s21, 0
	global_load_dwordx4 v[238:241], v251, s[4:5]
	global_load_dwordx4 v[242:245], v251, s[4:5] offset:64
	s_add_u32 s4, s4, 0x2000
	s_addc_u32 s5, s5, 0
	global_load_dwordx4 v[246:249], v251, s[4:5]
	global_load_dwordx4 v[194:197], v251, s[4:5] offset:64
	v_bfe_u32 v255, v152, 6, 2
	v_and_b32_e32 v253, 15, v152
	v_lshl_add_u32 v255, v255, 4, v253
	v_add_u32_e32 v255, s56, v255
	v_lshlrev_b32_e32 v255, 2, v255
	s_add_u32 s0, s28, 0x800
	s_addc_u32 s1, s29, 0
	global_load_dword v75, v255, s[0:1]
	s_add_u32 s0, s30, 0x800
	s_addc_u32 s1, s31, 0
	global_load_dword v84, v255, s[0:1]
	s_add_u32 s0, s36, 0x800
	s_addc_u32 s1, s37, 0
	global_load_dword v85, v255, s[0:1]
	ds_read_b128 v[76:79], v131 offset:0
	ds_read_b128 v[80:83], v133 offset:0
	ds_read_b128 v[122:125], v131 offset:512
	ds_read_b128 v[126:129], v133 offset:512
	s_waitcnt vmcnt(3)
	s_waitcnt lgkmcnt(3)
	v_mfma_f32_16x16x32_bf16 v[0:3], v[76:79], v[238:241], 0
	v_mfma_f32_16x16x32_bf16 v[90:93], v[76:79], v[246:249], 0
	ds_read_b128 v[76:79], v131 offset:1024
	s_waitcnt lgkmcnt(3)
	v_mfma_f32_16x16x32_bf16 v[0:3], v[80:83], v[242:245], v[0:3]
	v_mfma_f32_16x16x32_bf16 v[90:93], v[80:83], v[194:197], v[90:93]
	ds_read_b128 v[80:83], v133 offset:1024
	s_waitcnt lgkmcnt(3)
	v_mfma_f32_16x16x32_bf16 v[4:7], v[122:125], v[238:241], 0
	v_mfma_f32_16x16x32_bf16 v[94:97], v[122:125], v[246:249], 0
	ds_read_b128 v[122:125], v131 offset:1536
	s_waitcnt lgkmcnt(3)
	v_mfma_f32_16x16x32_bf16 v[4:7], v[126:129], v[242:245], v[4:7]
	v_mfma_f32_16x16x32_bf16 v[94:97], v[126:129], v[194:197], v[94:97]
	ds_read_b128 v[126:129], v133 offset:1536
	s_waitcnt lgkmcnt(3)
	v_mfma_f32_16x16x32_bf16 v[8:11], v[76:79], v[238:241], 0
	v_mfma_f32_16x16x32_bf16 v[98:101], v[76:79], v[246:249], 0
	ds_read_b128 v[76:79], v131 offset:2048
	s_waitcnt lgkmcnt(3)
	v_mfma_f32_16x16x32_bf16 v[8:11], v[80:83], v[242:245], v[8:11]
	v_mfma_f32_16x16x32_bf16 v[98:101], v[80:83], v[194:197], v[98:101]
	ds_read_b128 v[80:83], v133 offset:2048
	s_waitcnt lgkmcnt(3)
	v_mfma_f32_16x16x32_bf16 v[12:15], v[122:125], v[238:241], 0
	v_mfma_f32_16x16x32_bf16 v[102:105], v[122:125], v[246:249], 0
	ds_read_b128 v[122:125], v131 offset:2560
	s_waitcnt lgkmcnt(3)
	v_mfma_f32_16x16x32_bf16 v[12:15], v[126:129], v[242:245], v[12:15]
	v_mfma_f32_16x16x32_bf16 v[102:105], v[126:129], v[194:197], v[102:105]
	ds_read_b128 v[126:129], v133 offset:2560
	s_waitcnt lgkmcnt(3)
	v_mfma_f32_16x16x32_bf16 v[16:19], v[76:79], v[238:241], 0
	v_mfma_f32_16x16x32_bf16 v[106:109], v[76:79], v[246:249], 0
	ds_read_b128 v[76:79], v131 offset:3072
	s_waitcnt lgkmcnt(3)
	v_mfma_f32_16x16x32_bf16 v[16:19], v[80:83], v[242:245], v[16:19]
	v_mfma_f32_16x16x32_bf16 v[106:109], v[80:83], v[194:197], v[106:109]
	ds_read_b128 v[80:83], v133 offset:3072
	s_waitcnt lgkmcnt(3)
	v_mfma_f32_16x16x32_bf16 v[20:23], v[122:125], v[238:241], 0
	v_mfma_f32_16x16x32_bf16 v[110:113], v[122:125], v[246:249], 0
	ds_read_b128 v[122:125], v131 offset:3584
	s_waitcnt lgkmcnt(3)
	v_mfma_f32_16x16x32_bf16 v[20:23], v[126:129], v[242:245], v[20:23]
	v_mfma_f32_16x16x32_bf16 v[110:113], v[126:129], v[194:197], v[110:113]
	ds_read_b128 v[126:129], v133 offset:3584
	s_waitcnt lgkmcnt(3)
	v_mfma_f32_16x16x32_bf16 v[24:27], v[76:79], v[238:241], 0
	v_mfma_f32_16x16x32_bf16 v[114:117], v[76:79], v[246:249], 0
	s_waitcnt lgkmcnt(2)
	v_mfma_f32_16x16x32_bf16 v[24:27], v[80:83], v[242:245], v[24:27]
	v_mfma_f32_16x16x32_bf16 v[114:117], v[80:83], v[194:197], v[114:117]
	s_waitcnt lgkmcnt(1)
	v_mfma_f32_16x16x32_bf16 v[28:31], v[122:125], v[238:241], 0
	v_mfma_f32_16x16x32_bf16 v[118:121], v[122:125], v[246:249], 0
	s_waitcnt lgkmcnt(0)
	v_mfma_f32_16x16x32_bf16 v[28:31], v[126:129], v[242:245], v[28:31]
	v_mfma_f32_16x16x32_bf16 v[118:121], v[126:129], v[194:197], v[118:121]
	s_waitcnt vmcnt(0)
; __device__ __forceinline__ float bf2f(u16 h) { return __uint_as_float(((unsigned)h) << 16); }
; __device__ __forceinline__ void lru_tile(const Params& P, int chunk, int head, int pass, char* smem_raw) {
;     ...
; #pragma unroll
;     for (int tc = 0; tc < 4; ++tc) {
;       const int cidx = d * 512 + head * 64 + 16 * tc + (lane & 15);
;       ba[tc] = P.b_a[cidx] * -1.4426950408889634f; bi[tc] = P.b_i[cidx] * -1.4426950408889634f;
;       const float nl = -P.lam[cidx];
;       const float e_ = __expf(nl);
;       const float sp = (nl > 20.f) ? nl
;                      : (e_ < 0.03f ? e_ * (1.f - e_ * (0.5f - e_ * (0.33333334f - 0.25f * e_))) : __logf(1.f + e_));
;       c8[tc] = 8.f * 1.4426950408889634f * sp;
;     }
;     __syncthreads();
;     float cA = 1.f, cB = (pass == 2) ? sm_init[d * 64 + ch] : 0.f;
;     for (int sbi = 0; sbi < 2; ++sbi) {
;       const int sb = (d == 0) ? sbi : 1 - sbi;
;       f32x4 acc[8];
; #pragma unroll
;       for (int t = 0; t < 8; ++t) acc[t] = f32x4{0.f, 0.f, 0.f, 0.f};
; #pragma unroll
;       for (int s = 0; s < 2; ++s) {
;         const bf16x8 af = *reinterpret_cast<const bf16x8*>(&sm_uc[(sb * 64 + wid * 16 + (lane & 15)) * LDSS + s * 32 + (lane >> 4) * 8]);
; #pragma unroll
;         for (int t = 0; t < 8; ++t) {
;           const bf16x8 bfr = *reinterpret_cast<const bf16x8*>(&sm_w[(t * 16 + (lane & 15)) * LDSS + s * 32 + (lane >> 4) * 8]);
;           acc[t] = __builtin_amdgcn_mfma_f32_16x16x32_bf16(af, bfr, acc[t], 0, 0, 0);
;         }
;       }
; #pragma unroll
;       for (int tc = 0; tc < 4; ++tc)
; #pragma unroll
;         for (int reg = 0; reg < 4; ++reg) {
;           const int tl = wid * 16 + (lane >> 4) * 4 + reg;
;           const int c = 16 * tc + (lane & 15);
;           const float r = __builtin_amdgcn_rcpf(1.f + __builtin_amdgcn_exp2f(acc[tc][reg] + ba[tc]));
;           const float ii = __builtin_amdgcn_rcpf(1.f + __builtin_amdgcn_exp2f(acc[tc + 4][reg] + bi[tc]));
;           const float la = -c8[tc] * r;
;           const float a = __builtin_amdgcn_exp2f(la);
;           const float ucv = bf2f(sm_uc[(sb * 64 + tl) * LDSS + c]);
;           const float bt = __builtin_amdgcn_sqrtf(fmaxf(1.f - a * a, 0.f)) * (ii * ucv);
;           sm_a[tl * 64 + c] = a;
;           sm_b[tl * 64 + c] = bt;
;         }
	v_mul_f32_e32 v75, 0xbfb8aa3b, v75
	v_mul_f32_e32 v84, 0xbfb8aa3b, v84
	v_sub_f32_e32 v138, 0, v85
	v_mul_f32_e32 v139, 0x3fb8aa3b, v138
	v_exp_f32_e32 v139, v139
	v_mul_f32_e32 v140, 0xbe800000, v139
	v_add_f32_e32 v140, 0x3eaaaaab, v140
	v_fma_f32 v140, -v139, v140, 0.5
	v_fma_f32 v140, -v139, v140, 1.0
	v_mul_f32_e32 v140, v139, v140
	v_add_f32_e32 v141, 1.0, v139
	v_log_f32_e32 v141, v141
	v_mov_b32_e32 v255, 0x3cf5c28f
	v_mul_f32_e32 v141, 0x3f317218, v141
	v_cmp_gt_f32_e32 vcc, v255, v139
	s_nop 1
	v_cndmask_b32_e32 v140, v141, v140, vcc
	v_mov_b32_e32 v255, 0x41a00000
	v_cmp_lt_f32_e32 vcc, v255, v138
	s_nop 1
	v_cndmask_b32_e32 v140, v140, v138, vcc
	v_mul_f32_e32 v85, 0xc138aa3b, v140
	s_nop 7
	v_add_f32_e32 v0, v0, v75
	v_add_f32_e32 v1, v1, v75
	v_add_f32_e32 v2, v2, v75
	v_add_f32_e32 v3, v3, v75
	v_add_f32_e32 v90, v90, v84
	v_add_f32_e32 v91, v91, v84
	v_add_f32_e32 v92, v92, v84
	v_add_f32_e32 v93, v93, v84
	v_exp_f32_e32 v0, v0
	v_exp_f32_e32 v1, v1
	v_exp_f32_e32 v2, v2
	v_exp_f32_e32 v3, v3
	v_exp_f32_e32 v90, v90
	v_exp_f32_e32 v91, v91
	v_exp_f32_e32 v92, v92
	v_exp_f32_e32 v93, v93
	v_add_f32_e32 v0, 1.0, v0
	v_add_f32_e32 v1, 1.0, v1
	v_add_f32_e32 v2, 1.0, v2
	v_add_f32_e32 v3, 1.0, v3
	v_add_f32_e32 v90, 1.0, v90
	v_add_f32_e32 v91, 1.0, v91
	v_add_f32_e32 v92, 1.0, v92
	v_add_f32_e32 v93, 1.0, v93
	v_rcp_f32_e32 v0, v0
	v_rcp_f32_e32 v1, v1
	v_rcp_f32_e32 v2, v2
	v_rcp_f32_e32 v3, v3
	v_rcp_f32_e32 v90, v90
	v_rcp_f32_e32 v91, v91
	v_rcp_f32_e32 v92, v92
	v_rcp_f32_e32 v93, v93
	v_mul_f32_e32 v0, v85, v0
	v_mul_f32_e32 v1, v85, v1
	v_mul_f32_e32 v2, v85, v2
	v_mul_f32_e32 v3, v85, v3
	v_mul_f32_e32 v90, v90, v162
	v_mul_f32_e32 v91, v91, v163
	v_mul_f32_e32 v92, v92, v164
	v_mul_f32_e32 v93, v93, v165
	v_exp_f32_e32 v0, v0
	v_exp_f32_e32 v1, v1
	v_exp_f32_e32 v2, v2
	v_exp_f32_e32 v3, v3
	s_nop 0
	v_fma_f32 v138, -v0, v0, 1.0
	v_fma_f32 v139, -v1, v1, 1.0
	v_fma_f32 v140, -v2, v2, 1.0
	v_fma_f32 v141, -v3, v3, 1.0
	v_max_f32_e32 v138, 0, v138
	v_max_f32_e32 v139, 0, v139
	v_max_f32_e32 v140, 0, v140
	v_max_f32_e32 v141, 0, v141
	v_sqrt_f32_e32 v138, v138
	v_sqrt_f32_e32 v139, v139
	v_sqrt_f32_e32 v140, v140
	v_sqrt_f32_e32 v141, v141
	s_nop 0
	v_mul_f32_e32 v90, v138, v90
	v_mul_f32_e32 v91, v139, v91
	v_mul_f32_e32 v92, v140, v92
	v_mul_f32_e32 v93, v141, v93
	v_add_f32_e32 v4, v4, v75
	v_add_f32_e32 v5, v5, v75
	v_add_f32_e32 v6, v6, v75
	v_add_f32_e32 v7, v7, v75
	v_add_f32_e32 v94, v94, v84
	v_add_f32_e32 v95, v95, v84
	v_add_f32_e32 v96, v96, v84
	v_add_f32_e32 v97, v97, v84
	v_exp_f32_e32 v4, v4
	v_exp_f32_e32 v5, v5
	v_exp_f32_e32 v6, v6
	v_exp_f32_e32 v7, v7
	v_exp_f32_e32 v94, v94
	v_exp_f32_e32 v95, v95
	v_exp_f32_e32 v96, v96
	v_exp_f32_e32 v97, v97
	v_add_f32_e32 v4, 1.0, v4
	v_add_f32_e32 v5, 1.0, v5
	v_add_f32_e32 v6, 1.0, v6
	v_add_f32_e32 v7, 1.0, v7
	v_add_f32_e32 v94, 1.0, v94
	v_add_f32_e32 v95, 1.0, v95
	v_add_f32_e32 v96, 1.0, v96
	v_add_f32_e32 v97, 1.0, v97
	v_rcp_f32_e32 v4, v4
	v_rcp_f32_e32 v5, v5
	v_rcp_f32_e32 v6, v6
	v_rcp_f32_e32 v7, v7
	v_rcp_f32_e32 v94, v94
	v_rcp_f32_e32 v95, v95
	v_rcp_f32_e32 v96, v96
	v_rcp_f32_e32 v97, v97
	v_mul_f32_e32 v4, v85, v4
	v_mul_f32_e32 v5, v85, v5
	v_mul_f32_e32 v6, v85, v6
	v_mul_f32_e32 v7, v85, v7
	v_mul_f32_e32 v94, v94, v166
	v_mul_f32_e32 v95, v95, v167
	v_mul_f32_e32 v96, v96, v168
	v_mul_f32_e32 v97, v97, v169
	v_exp_f32_e32 v4, v4
	v_exp_f32_e32 v5, v5
	v_exp_f32_e32 v6, v6
	v_exp_f32_e32 v7, v7
	s_nop 0
	v_fma_f32 v138, -v4, v4, 1.0
	v_fma_f32 v139, -v5, v5, 1.0
	v_fma_f32 v140, -v6, v6, 1.0
	v_fma_f32 v141, -v7, v7, 1.0
	v_max_f32_e32 v138, 0, v138
	v_max_f32_e32 v139, 0, v139
	v_max_f32_e32 v140, 0, v140
	v_max_f32_e32 v141, 0, v141
	v_sqrt_f32_e32 v138, v138
	v_sqrt_f32_e32 v139, v139
	v_sqrt_f32_e32 v140, v140
	v_sqrt_f32_e32 v141, v141
	s_nop 0
	v_mul_f32_e32 v94, v138, v94
	v_mul_f32_e32 v95, v139, v95
	v_mul_f32_e32 v96, v140, v96
	v_mul_f32_e32 v97, v141, v97
	v_add_f32_e32 v8, v8, v75
	v_add_f32_e32 v9, v9, v75
	v_add_f32_e32 v10, v10, v75
	v_add_f32_e32 v11, v11, v75
	v_add_f32_e32 v98, v98, v84
	v_add_f32_e32 v99, v99, v84
	v_add_f32_e32 v100, v100, v84
	v_add_f32_e32 v101, v101, v84
	v_exp_f32_e32 v8, v8
	v_exp_f32_e32 v9, v9
	v_exp_f32_e32 v10, v10
	v_exp_f32_e32 v11, v11
	v_exp_f32_e32 v98, v98
	v_exp_f32_e32 v99, v99
	v_exp_f32_e32 v100, v100
	v_exp_f32_e32 v101, v101
	v_add_f32_e32 v8, 1.0, v8
	v_add_f32_e32 v9, 1.0, v9
	v_add_f32_e32 v10, 1.0, v10
	v_add_f32_e32 v11, 1.0, v11
	v_add_f32_e32 v98, 1.0, v98
	v_add_f32_e32 v99, 1.0, v99
	v_add_f32_e32 v100, 1.0, v100
	v_add_f32_e32 v101, 1.0, v101
	v_rcp_f32_e32 v8, v8
	v_rcp_f32_e32 v9, v9
	v_rcp_f32_e32 v10, v10
	v_rcp_f32_e32 v11, v11
	v_rcp_f32_e32 v98, v98
	v_rcp_f32_e32 v99, v99
	v_rcp_f32_e32 v100, v100
	v_rcp_f32_e32 v101, v101
	v_mul_f32_e32 v8, v85, v8
	v_mul_f32_e32 v9, v85, v9
	v_mul_f32_e32 v10, v85, v10
	v_mul_f32_e32 v11, v85, v11
	v_mul_f32_e32 v98, v98, v170
	v_mul_f32_e32 v99, v99, v171
	v_mul_f32_e32 v100, v100, v172
	v_mul_f32_e32 v101, v101, v173
	v_exp_f32_e32 v8, v8
	v_exp_f32_e32 v9, v9
	v_exp_f32_e32 v10, v10
	v_exp_f32_e32 v11, v11
	s_nop 0
	v_fma_f32 v138, -v8, v8, 1.0
	v_fma_f32 v139, -v9, v9, 1.0
	v_fma_f32 v140, -v10, v10, 1.0
	v_fma_f32 v141, -v11, v11, 1.0
	v_max_f32_e32 v138, 0, v138
	v_max_f32_e32 v139, 0, v139
	v_max_f32_e32 v140, 0, v140
	v_max_f32_e32 v141, 0, v141
	v_sqrt_f32_e32 v138, v138
	v_sqrt_f32_e32 v139, v139
	v_sqrt_f32_e32 v140, v140
	v_sqrt_f32_e32 v141, v141
	s_nop 0
	v_mul_f32_e32 v98, v138, v98
	v_mul_f32_e32 v99, v139, v99
	v_mul_f32_e32 v100, v140, v100
	v_mul_f32_e32 v101, v141, v101
	v_add_f32_e32 v12, v12, v75
; __device__ __forceinline__ float bf2f(u16 h) { return __uint_as_float(((unsigned)h) << 16); }
; __device__ __forceinline__ void lru_tile(const Params& P, int chunk, int head, int pass, char* smem_raw) {
;     ...
;       for (int tc = 0; tc < 4; ++tc)
; #pragma unroll
;         for (int reg = 0; reg < 4; ++reg) {
;           const int tl = wid * 16 + (lane >> 4) * 4 + reg;
;           const int c = 16 * tc + (lane & 15);
;           const float r = __builtin_amdgcn_rcpf(1.f + __builtin_amdgcn_exp2f(acc[tc][reg] + ba[tc]));
;           const float ii = __builtin_amdgcn_rcpf(1.f + __builtin_amdgcn_exp2f(acc[tc + 4][reg] + bi[tc]));
;           const float la = -c8[tc] * r;
;           const float a = __builtin_amdgcn_exp2f(la);
;           const float ucv = bf2f(sm_uc[(sb * 64 + tl) * LDSS + c]);
;           const float bt = __builtin_amdgcn_sqrtf(fmaxf(1.f - a * a, 0.f)) * (ii * ucv);
;           sm_a[tl * 64 + c] = a;
;           sm_b[tl * 64 + c] = bt;
;         }
	v_add_f32_e32 v13, v13, v75
	v_add_f32_e32 v14, v14, v75
	v_add_f32_e32 v15, v15, v75
	v_add_f32_e32 v102, v102, v84
	v_add_f32_e32 v103, v103, v84
	v_add_f32_e32 v104, v104, v84
	v_add_f32_e32 v105, v105, v84
	v_exp_f32_e32 v12, v12
	v_exp_f32_e32 v13, v13
	v_exp_f32_e32 v14, v14
	v_exp_f32_e32 v15, v15
	v_exp_f32_e32 v102, v102
	v_exp_f32_e32 v103, v103
	v_exp_f32_e32 v104, v104
	v_exp_f32_e32 v105, v105
	v_add_f32_e32 v12, 1.0, v12
	v_add_f32_e32 v13, 1.0, v13
	v_add_f32_e32 v14, 1.0, v14
	v_add_f32_e32 v15, 1.0, v15
	v_add_f32_e32 v102, 1.0, v102
	v_add_f32_e32 v103, 1.0, v103
	v_add_f32_e32 v104, 1.0, v104
	v_add_f32_e32 v105, 1.0, v105
	v_rcp_f32_e32 v12, v12
	v_rcp_f32_e32 v13, v13
	v_rcp_f32_e32 v14, v14
	v_rcp_f32_e32 v15, v15
	v_rcp_f32_e32 v102, v102
	v_rcp_f32_e32 v103, v103
	v_rcp_f32_e32 v104, v104
	v_rcp_f32_e32 v105, v105
	v_mul_f32_e32 v12, v85, v12
	v_mul_f32_e32 v13, v85, v13
	v_mul_f32_e32 v14, v85, v14
	v_mul_f32_e32 v15, v85, v15
	v_mul_f32_e32 v102, v102, v174
	v_mul_f32_e32 v103, v103, v175
	v_mul_f32_e32 v104, v104, v176
	v_mul_f32_e32 v105, v105, v177
	v_exp_f32_e32 v12, v12
	v_exp_f32_e32 v13, v13
	v_exp_f32_e32 v14, v14
	v_exp_f32_e32 v15, v15
	s_nop 0
	v_fma_f32 v138, -v12, v12, 1.0
	v_fma_f32 v139, -v13, v13, 1.0
	v_fma_f32 v140, -v14, v14, 1.0
	v_fma_f32 v141, -v15, v15, 1.0
	v_max_f32_e32 v138, 0, v138
	v_max_f32_e32 v139, 0, v139
	v_max_f32_e32 v140, 0, v140
	v_max_f32_e32 v141, 0, v141
	v_sqrt_f32_e32 v138, v138
	v_sqrt_f32_e32 v139, v139
	v_sqrt_f32_e32 v140, v140
	v_sqrt_f32_e32 v141, v141
	s_nop 0
	v_mul_f32_e32 v102, v138, v102
	v_mul_f32_e32 v103, v139, v103
	v_mul_f32_e32 v104, v140, v104
	v_mul_f32_e32 v105, v141, v105
	v_add_f32_e32 v16, v16, v75
	v_add_f32_e32 v17, v17, v75
	v_add_f32_e32 v18, v18, v75
	v_add_f32_e32 v19, v19, v75
	v_add_f32_e32 v106, v106, v84
	v_add_f32_e32 v107, v107, v84
	v_add_f32_e32 v108, v108, v84
	v_add_f32_e32 v109, v109, v84
	v_exp_f32_e32 v16, v16
	v_exp_f32_e32 v17, v17
	v_exp_f32_e32 v18, v18
	v_exp_f32_e32 v19, v19
	v_exp_f32_e32 v106, v106
	v_exp_f32_e32 v107, v107
	v_exp_f32_e32 v108, v108
	v_exp_f32_e32 v109, v109
	v_add_f32_e32 v16, 1.0, v16
	v_add_f32_e32 v17, 1.0, v17
	v_add_f32_e32 v18, 1.0, v18
	v_add_f32_e32 v19, 1.0, v19
	v_add_f32_e32 v106, 1.0, v106
	v_add_f32_e32 v107, 1.0, v107
	v_add_f32_e32 v108, 1.0, v108
	v_add_f32_e32 v109, 1.0, v109
	v_rcp_f32_e32 v16, v16
	v_rcp_f32_e32 v17, v17
	v_rcp_f32_e32 v18, v18
	v_rcp_f32_e32 v19, v19
	v_rcp_f32_e32 v106, v106
	v_rcp_f32_e32 v107, v107
	v_rcp_f32_e32 v108, v108
	v_rcp_f32_e32 v109, v109
	v_mul_f32_e32 v16, v85, v16
	v_mul_f32_e32 v17, v85, v17
	v_mul_f32_e32 v18, v85, v18
	v_mul_f32_e32 v19, v85, v19
	v_mul_f32_e32 v106, v106, v178
	v_mul_f32_e32 v107, v107, v179
	v_mul_f32_e32 v108, v108, v180
	v_mul_f32_e32 v109, v109, v181
	v_exp_f32_e32 v16, v16
	v_exp_f32_e32 v17, v17
	v_exp_f32_e32 v18, v18
	v_exp_f32_e32 v19, v19
	s_nop 0
	v_fma_f32 v138, -v16, v16, 1.0
	v_fma_f32 v139, -v17, v17, 1.0
	v_fma_f32 v140, -v18, v18, 1.0
	v_fma_f32 v141, -v19, v19, 1.0
	v_max_f32_e32 v138, 0, v138
	v_max_f32_e32 v139, 0, v139
	v_max_f32_e32 v140, 0, v140
	v_max_f32_e32 v141, 0, v141
	v_sqrt_f32_e32 v138, v138
	v_sqrt_f32_e32 v139, v139
	v_sqrt_f32_e32 v140, v140
	v_sqrt_f32_e32 v141, v141
	s_nop 0
	v_mul_f32_e32 v106, v138, v106
	v_mul_f32_e32 v107, v139, v107
	v_mul_f32_e32 v108, v140, v108
	v_mul_f32_e32 v109, v141, v109
	v_add_f32_e32 v20, v20, v75
	v_add_f32_e32 v21, v21, v75
	v_add_f32_e32 v22, v22, v75
	v_add_f32_e32 v23, v23, v75
	v_add_f32_e32 v110, v110, v84
	v_add_f32_e32 v111, v111, v84
	v_add_f32_e32 v112, v112, v84
	v_add_f32_e32 v113, v113, v84
	v_exp_f32_e32 v20, v20
	v_exp_f32_e32 v21, v21
	v_exp_f32_e32 v22, v22
	v_exp_f32_e32 v23, v23
	v_exp_f32_e32 v110, v110
	v_exp_f32_e32 v111, v111
	v_exp_f32_e32 v112, v112
	v_exp_f32_e32 v113, v113
	v_add_f32_e32 v20, 1.0, v20
	v_add_f32_e32 v21, 1.0, v21
	v_add_f32_e32 v22, 1.0, v22
	v_add_f32_e32 v23, 1.0, v23
	v_add_f32_e32 v110, 1.0, v110
	v_add_f32_e32 v111, 1.0, v111
	v_add_f32_e32 v112, 1.0, v112
	v_add_f32_e32 v113, 1.0, v113
	v_rcp_f32_e32 v20, v20
	v_rcp_f32_e32 v21, v21
	v_rcp_f32_e32 v22, v22
	v_rcp_f32_e32 v23, v23
	v_rcp_f32_e32 v110, v110
	v_rcp_f32_e32 v111, v111
	v_rcp_f32_e32 v112, v112
	v_rcp_f32_e32 v113, v113
	v_mul_f32_e32 v20, v85, v20
	v_mul_f32_e32 v21, v85, v21
	v_mul_f32_e32 v22, v85, v22
	v_mul_f32_e32 v23, v85, v23
	v_mul_f32_e32 v110, v110, v182
	v_mul_f32_e32 v111, v111, v183
	v_mul_f32_e32 v112, v112, v184
	v_mul_f32_e32 v113, v113, v185
	v_exp_f32_e32 v20, v20
	v_exp_f32_e32 v21, v21
	v_exp_f32_e32 v22, v22
	v_exp_f32_e32 v23, v23
	s_nop 0
	v_fma_f32 v138, -v20, v20, 1.0
	v_fma_f32 v139, -v21, v21, 1.0
	v_fma_f32 v140, -v22, v22, 1.0
	v_fma_f32 v141, -v23, v23, 1.0
	v_max_f32_e32 v138, 0, v138
	v_max_f32_e32 v139, 0, v139
	v_max_f32_e32 v140, 0, v140
	v_max_f32_e32 v141, 0, v141
	v_sqrt_f32_e32 v138, v138
	v_sqrt_f32_e32 v139, v139
	v_sqrt_f32_e32 v140, v140
	v_sqrt_f32_e32 v141, v141
	s_nop 0
	v_mul_f32_e32 v110, v138, v110
	v_mul_f32_e32 v111, v139, v111
	v_mul_f32_e32 v112, v140, v112
	v_mul_f32_e32 v113, v141, v113
	v_add_f32_e32 v24, v24, v75
	v_add_f32_e32 v25, v25, v75
	v_add_f32_e32 v26, v26, v75
	v_add_f32_e32 v27, v27, v75
	v_add_f32_e32 v114, v114, v84
	v_add_f32_e32 v115, v115, v84
	v_add_f32_e32 v116, v116, v84
	v_add_f32_e32 v117, v117, v84
	v_exp_f32_e32 v24, v24
	v_exp_f32_e32 v25, v25
	v_exp_f32_e32 v26, v26
	v_exp_f32_e32 v27, v27
	v_exp_f32_e32 v114, v114
	v_exp_f32_e32 v115, v115
	v_exp_f32_e32 v116, v116
	v_exp_f32_e32 v117, v117
	v_add_f32_e32 v24, 1.0, v24
	v_add_f32_e32 v25, 1.0, v25
	v_add_f32_e32 v26, 1.0, v26
; __device__ __forceinline__ float bf2f(u16 h) { return __uint_as_float(((unsigned)h) << 16); }
; __device__ __forceinline__ void lru_tile(const Params& P, int chunk, int head, int pass, char* smem_raw) {
;     ...
;       for (int tc = 0; tc < 4; ++tc)
; #pragma unroll
;         for (int reg = 0; reg < 4; ++reg) {
;           const int tl = wid * 16 + (lane >> 4) * 4 + reg;
;           const int c = 16 * tc + (lane & 15);
;           const float r = __builtin_amdgcn_rcpf(1.f + __builtin_amdgcn_exp2f(acc[tc][reg] + ba[tc]));
;           const float ii = __builtin_amdgcn_rcpf(1.f + __builtin_amdgcn_exp2f(acc[tc + 4][reg] + bi[tc]));
;           const float la = -c8[tc] * r;
;           const float a = __builtin_amdgcn_exp2f(la);
;           const float ucv = bf2f(sm_uc[(sb * 64 + tl) * LDSS + c]);
;           const float bt = __builtin_amdgcn_sqrtf(fmaxf(1.f - a * a, 0.f)) * (ii * ucv);
;           sm_a[tl * 64 + c] = a;
;           sm_b[tl * 64 + c] = bt;
;         }
;       __syncthreads();
;       const int pos = (d == 0) ? q : 3 - q;
;       {
;         float Pp = 1.f, H = 0.f;
; #pragma unroll 4
;         for (int i = 0; i < 16; ++i) {
;           const int tl = (d == 0) ? (q * 16 + i) : (q * 16 + 15 - i);
;           const float a = sm_a[tl * 64 + ch], b = sm_b[tl * 64 + ch];
;           H = a * H + b; Pp *= a;
;         }
;         sm_ph[pos * 64 + ch] = make_float2(Pp, H);
;     ...
;       cB = p0.x * cB + p0.y; cA *= p0.x;
;       cB = p1.x * cB + p1.y; cA *= p1.x;
;       cB = p2.x * cB + p2.y; cA *= p2.x;
;       cB = p3.x * cB + p3.y; cA *= p3.x;
;       __syncthreads();
;     }
;     if (pass == 1 && q == 0) P.summ[((long)d * 264 + chunk) * 512 + gch] = make_float2(cA, cB);
	v_add_f32_e32 v27, 1.0, v27
	v_add_f32_e32 v114, 1.0, v114
	v_add_f32_e32 v115, 1.0, v115
	v_add_f32_e32 v116, 1.0, v116
	v_add_f32_e32 v117, 1.0, v117
	v_rcp_f32_e32 v24, v24
	v_rcp_f32_e32 v25, v25
	v_rcp_f32_e32 v26, v26
	v_rcp_f32_e32 v27, v27
	v_rcp_f32_e32 v114, v114
	v_rcp_f32_e32 v115, v115
	v_rcp_f32_e32 v116, v116
	v_rcp_f32_e32 v117, v117
	v_mul_f32_e32 v24, v85, v24
	v_mul_f32_e32 v25, v85, v25
	v_mul_f32_e32 v26, v85, v26
	v_mul_f32_e32 v27, v85, v27
	v_mul_f32_e32 v114, v114, v186
	v_mul_f32_e32 v115, v115, v187
	v_mul_f32_e32 v116, v116, v188
	v_mul_f32_e32 v117, v117, v189
	v_exp_f32_e32 v24, v24
	v_exp_f32_e32 v25, v25
	v_exp_f32_e32 v26, v26
	v_exp_f32_e32 v27, v27
	s_nop 0
	v_fma_f32 v138, -v24, v24, 1.0
	v_fma_f32 v139, -v25, v25, 1.0
	v_fma_f32 v140, -v26, v26, 1.0
	v_fma_f32 v141, -v27, v27, 1.0
	v_max_f32_e32 v138, 0, v138
	v_max_f32_e32 v139, 0, v139
	v_max_f32_e32 v140, 0, v140
	v_max_f32_e32 v141, 0, v141
	v_sqrt_f32_e32 v138, v138
	v_sqrt_f32_e32 v139, v139
	v_sqrt_f32_e32 v140, v140
	v_sqrt_f32_e32 v141, v141
	s_nop 0
	v_mul_f32_e32 v114, v138, v114
	v_mul_f32_e32 v115, v139, v115
	v_mul_f32_e32 v116, v140, v116
	v_mul_f32_e32 v117, v141, v117
	v_add_f32_e32 v28, v28, v75
	v_add_f32_e32 v29, v29, v75
	v_add_f32_e32 v30, v30, v75
	v_add_f32_e32 v31, v31, v75
	v_add_f32_e32 v118, v118, v84
	v_add_f32_e32 v119, v119, v84
	v_add_f32_e32 v120, v120, v84
	v_add_f32_e32 v121, v121, v84
	v_exp_f32_e32 v28, v28
	v_exp_f32_e32 v29, v29
	v_exp_f32_e32 v30, v30
	v_exp_f32_e32 v31, v31
	v_exp_f32_e32 v118, v118
	v_exp_f32_e32 v119, v119
	v_exp_f32_e32 v120, v120
	v_exp_f32_e32 v121, v121
	v_add_f32_e32 v28, 1.0, v28
	v_add_f32_e32 v29, 1.0, v29
	v_add_f32_e32 v30, 1.0, v30
	v_add_f32_e32 v31, 1.0, v31
	v_add_f32_e32 v118, 1.0, v118
	v_add_f32_e32 v119, 1.0, v119
	v_add_f32_e32 v120, 1.0, v120
	v_add_f32_e32 v121, 1.0, v121
	v_rcp_f32_e32 v28, v28
	v_rcp_f32_e32 v29, v29
	v_rcp_f32_e32 v30, v30
	v_rcp_f32_e32 v31, v31
	v_rcp_f32_e32 v118, v118
	v_rcp_f32_e32 v119, v119
	v_rcp_f32_e32 v120, v120
	v_rcp_f32_e32 v121, v121
	v_mul_f32_e32 v28, v85, v28
	v_mul_f32_e32 v29, v85, v29
	v_mul_f32_e32 v30, v85, v30
	v_mul_f32_e32 v31, v85, v31
	v_mul_f32_e32 v118, v118, v190
	v_mul_f32_e32 v119, v119, v191
	v_mul_f32_e32 v120, v120, v192
	v_mul_f32_e32 v121, v121, v193
	v_exp_f32_e32 v28, v28
	v_exp_f32_e32 v29, v29
	v_exp_f32_e32 v30, v30
	v_exp_f32_e32 v31, v31
	s_nop 0
	v_fma_f32 v138, -v28, v28, 1.0
	v_fma_f32 v139, -v29, v29, 1.0
	v_fma_f32 v140, -v30, v30, 1.0
	v_fma_f32 v141, -v31, v31, 1.0
	v_max_f32_e32 v138, 0, v138
	v_max_f32_e32 v139, 0, v139
	v_max_f32_e32 v140, 0, v140
	v_max_f32_e32 v141, 0, v141
	v_sqrt_f32_e32 v138, v138
	v_sqrt_f32_e32 v139, v139
	v_sqrt_f32_e32 v140, v140
	v_sqrt_f32_e32 v141, v141
	s_nop 0
	v_mul_f32_e32 v118, v138, v118
	v_mul_f32_e32 v119, v139, v119
	v_mul_f32_e32 v120, v140, v120
	v_mul_f32_e32 v121, v141, v121
	v_mov_b32_e32 v253, v31
	v_mov_b32_e32 v254, v121
	v_fma_f32 v254, v30, v254, v120
	v_mul_f32_e32 v253, v253, v30
	v_fma_f32 v254, v29, v254, v119
	v_mul_f32_e32 v253, v253, v29
	v_fma_f32 v254, v28, v254, v118
	v_mul_f32_e32 v253, v253, v28
	v_fma_f32 v254, v27, v254, v117
	v_mul_f32_e32 v253, v253, v27
	v_fma_f32 v254, v26, v254, v116
	v_mul_f32_e32 v253, v253, v26
	v_fma_f32 v254, v25, v254, v115
	v_mul_f32_e32 v253, v253, v25
	v_fma_f32 v254, v24, v254, v114
	v_mul_f32_e32 v253, v253, v24
	v_fma_f32 v254, v23, v254, v113
	v_mul_f32_e32 v253, v253, v23
	v_fma_f32 v254, v22, v254, v112
	v_mul_f32_e32 v253, v253, v22
	v_fma_f32 v254, v21, v254, v111
	v_mul_f32_e32 v253, v253, v21
	v_fma_f32 v254, v20, v254, v110
	v_mul_f32_e32 v253, v253, v20
	v_fma_f32 v254, v19, v254, v109
	v_mul_f32_e32 v253, v253, v19
	v_fma_f32 v254, v18, v254, v108
	v_mul_f32_e32 v253, v253, v18
	v_fma_f32 v254, v17, v254, v107
	v_mul_f32_e32 v253, v253, v17
	v_fma_f32 v254, v16, v254, v106
	v_mul_f32_e32 v253, v253, v16
	v_fma_f32 v254, v15, v254, v105
	v_mul_f32_e32 v253, v253, v15
	v_fma_f32 v254, v14, v254, v104
	v_mul_f32_e32 v253, v253, v14
	v_fma_f32 v254, v13, v254, v103
	v_mul_f32_e32 v253, v253, v13
	v_fma_f32 v254, v12, v254, v102
	v_mul_f32_e32 v253, v253, v12
	v_fma_f32 v254, v11, v254, v101
	v_mul_f32_e32 v253, v253, v11
	v_fma_f32 v254, v10, v254, v100
	v_mul_f32_e32 v253, v253, v10
	v_fma_f32 v254, v9, v254, v99
	v_mul_f32_e32 v253, v253, v9
	v_fma_f32 v254, v8, v254, v98
	v_mul_f32_e32 v253, v253, v8
	v_fma_f32 v254, v7, v254, v97
	v_mul_f32_e32 v253, v253, v7
	v_fma_f32 v254, v6, v254, v96
	v_mul_f32_e32 v253, v253, v6
	v_fma_f32 v254, v5, v254, v95
	v_mul_f32_e32 v253, v253, v5
	v_fma_f32 v254, v4, v254, v94
	v_mul_f32_e32 v253, v253, v4
	v_fma_f32 v254, v3, v254, v93
	v_mul_f32_e32 v253, v253, v3
	v_fma_f32 v254, v2, v254, v92
	v_mul_f32_e32 v253, v253, v2
	v_fma_f32 v254, v1, v254, v91
	v_mul_f32_e32 v253, v253, v1
	v_fma_f32 v254, v0, v254, v90
	v_mul_f32_e32 v253, v253, v0
	v_mov_b32_e32 v138, v253
	v_mov_b32_e32 v139, v253
	s_nop 1
	v_permlane16_swap_b32_e32 v138, v139
	v_mov_b32_e32 v140, v138
	v_mov_b32_e32 v141, v139
	s_nop 1
	v_permlane32_swap_b32_e32 v138, v140
	v_permlane32_swap_b32_e32 v139, v141
	v_mov_b32_e32 v198, v254
	v_mov_b32_e32 v199, v254
	s_nop 1
	v_permlane16_swap_b32_e32 v198, v199
	v_mov_b32_e32 v200, v198
	v_mov_b32_e32 v201, v199
	s_nop 1
	v_permlane32_swap_b32_e32 v198, v200
	v_permlane32_swap_b32_e32 v199, v201
	v_mov_b32_e32 v202, 0
	v_fma_f32 v151, v141, v202, v201
	v_fma_f32 v150, v140, v151, v200
	v_fma_f32 v136, v139, v150, v199
	v_fma_f32 v254, v138, v136, v198
	v_mul_f32_e32 v253, v138, v139
	v_mul_f32_e32 v253, v253, v140
	v_mul_f32_e32 v200, v253, v141
	v_mov_b32_e32 v201, v254
	s_add_u32 s0, s71, 264
	s_lshl_b32 s0, s0, 12
	s_lshl_b32 s1, s56, 3
	s_add_u32 s0, s0, s1
	s_add_u32 s4, s18, s0
	s_addc_u32 s5, s19, 0
	global_store_dwordx2 v250, v[200:201], s[4:5]
	s_add_u32 s69, s69, 1
	s_cmp_lt_u32 s69, s70
	s_cbranch_scc1 .Lmy_lrua_tile
	s_waitcnt lgkmcnt(0)
	s_barrier

; __device__ __forceinline__ float bf2f(u16 h) { return __uint_as_float(((unsigned)h) << 16); }
; __device__ __forceinline__ void lru_tile(const Params& P, int chunk, int head, int pass, char* smem_raw) {
;     ...
;   {
;     const float w0 = P.conv_w[gch], w1 = P.conv_w[512 + gch], w2 = P.conv_w[1024 + gch], w3 = P.conv_w[1536 + gch];
;     const float cb = P.conv_b[gch];
;     const u16* zu = P.zq + gch;
;     const int r = row0 + q * 32;
;     float uv[35];
; #pragma unroll
;     for (int i = 0; i < 35; ++i) {
;       const int rr = r - 2 + i;
;       uv[i] = (rr >= seq_lo && rr < seq_hi) ? bf2f(zu[(long)rr * 1536]) : 0.f;
;     }
;     __syncthreads();
; #pragma unroll
;     for (int i = 0; i < 32; ++i) {
;       const float v = cb + uv[i] * w0 + uv[i + 1] * w1 + uv[i + 2] * w2 + uv[i + 3] * w3;
;       sm_uc[(q * 32 + i) * LDSS + ch] = f2bf(v);
;     }
;   }
.Lmy_lrub_fl:
	s_cmp_eq_u32 s57, 0
	s_cselect_b64 s[0:1], s[84:85], 0
	s_cmp_eq_u32 s57, s60
	s_cselect_b64 s[4:5], s[86:87], 0
	v_cndmask_b32_e64 v202, 1.0, 0, s[0:1]
	v_cndmask_b32_e64 v203, 1.0, 0, s[4:5]
	v_mov_b32_e32 v255, 0x1800
	v_cndmask_b32_e64 v150, 0, v255, s[0:1]
	v_lshlrev_b32_e32 v136, 1, v150
	v_add_u32_e32 v136, v134, v136
	v_add_u32_e32 v150, v134, v150
	v_cndmask_b32_e64 v151, 0, v255, s[4:5]
	v_sub_u32_e32 v151, v134, v151
	s_lshl_b32 s61, s71, 7
	s_mul_i32 s0, s61, 0xc00
	s_lshl_b32 s1, s56, 1
	s_add_u32 s0, s0, s1
	s_add_u32 s4, s10, s0
	s_addc_u32 s5, s11, 0
	s_sub_u32 s4, s4, 0x1800
	s_subb_u32 s5, s5, 0
	global_load_ushort v90, v136, s[4:5]
	s_add_u32 s4, s4, 0xc00
	s_addc_u32 s5, s5, 0
	global_load_ushort v91, v150, s[4:5]
	s_add_u32 s4, s4, 0xc00
	s_addc_u32 s5, s5, 0
	global_load_ushort v92, v134, s[4:5]
	s_add_u32 s4, s4, 0xc00
	s_addc_u32 s5, s5, 0
	global_load_ushort v93, v134, s[4:5]
	s_add_u32 s4, s4, 0xc00
	s_addc_u32 s5, s5, 0
	global_load_ushort v94, v134, s[4:5]
	s_add_u32 s4, s4, 0xc00
	s_addc_u32 s5, s5, 0
	global_load_ushort v95, v134, s[4:5]
	s_add_u32 s4, s4, 0xc00
	s_addc_u32 s5, s5, 0
	global_load_ushort v96, v134, s[4:5]
	s_add_u32 s4, s4, 0xc00
	s_addc_u32 s5, s5, 0
	global_load_ushort v97, v134, s[4:5]
	s_add_u32 s4, s4, 0xc00
	s_addc_u32 s5, s5, 0
	global_load_ushort v98, v134, s[4:5]
	s_add_u32 s4, s4, 0xc00
	s_addc_u32 s5, s5, 0
	global_load_ushort v99, v134, s[4:5]
	s_add_u32 s4, s4, 0xc00
	s_addc_u32 s5, s5, 0
	global_load_ushort v100, v134, s[4:5]
	s_add_u32 s4, s4, 0xc00
	s_addc_u32 s5, s5, 0
	global_load_ushort v101, v134, s[4:5]
	s_add_u32 s4, s4, 0xc00
	s_addc_u32 s5, s5, 0
	global_load_ushort v102, v134, s[4:5]
	s_add_u32 s4, s4, 0xc00
	s_addc_u32 s5, s5, 0
	global_load_ushort v103, v134, s[4:5]
	s_add_u32 s4, s4, 0xc00
	s_addc_u32 s5, s5, 0
	global_load_ushort v104, v134, s[4:5]
	s_add_u32 s4, s4, 0xc00
	s_addc_u32 s5, s5, 0
	global_load_ushort v105, v134, s[4:5]
	s_add_u32 s4, s4, 0xc00
	s_addc_u32 s5, s5, 0
	global_load_ushort v106, v134, s[4:5]
	s_add_u32 s4, s4, 0xc00
	s_addc_u32 s5, s5, 0
	global_load_ushort v107, v134, s[4:5]
	s_add_u32 s4, s4, 0xc00
	s_addc_u32 s5, s5, 0
	global_load_ushort v108, v134, s[4:5]
	s_add_u32 s4, s4, 0xc00
	s_addc_u32 s5, s5, 0
	global_load_ushort v109, v134, s[4:5]
	s_add_u32 s4, s4, 0xc00
	s_addc_u32 s5, s5, 0
	global_load_ushort v110, v134, s[4:5]
	s_add_u32 s4, s4, 0xc00
	s_addc_u32 s5, s5, 0
	global_load_ushort v111, v134, s[4:5]
	s_add_u32 s4, s4, 0xc00
	s_addc_u32 s5, s5, 0
	global_load_ushort v112, v134, s[4:5]
	s_add_u32 s4, s4, 0xc00
	s_addc_u32 s5, s5, 0
	global_load_ushort v113, v134, s[4:5]
	s_add_u32 s4, s4, 0xc00
	s_addc_u32 s5, s5, 0
	global_load_ushort v114, v134, s[4:5]
	s_add_u32 s4, s4, 0xc00
	s_addc_u32 s5, s5, 0
	global_load_ushort v115, v134, s[4:5]
	s_add_u32 s4, s4, 0xc00
	s_addc_u32 s5, s5, 0
	global_load_ushort v116, v134, s[4:5]
	s_add_u32 s4, s4, 0xc00
	s_addc_u32 s5, s5, 0
	global_load_ushort v117, v134, s[4:5]
	s_add_u32 s4, s4, 0xc00
	s_addc_u32 s5, s5, 0
	global_load_ushort v118, v134, s[4:5]
	s_add_u32 s4, s4, 0xc00
	s_addc_u32 s5, s5, 0
	global_load_ushort v119, v134, s[4:5]
	s_add_u32 s4, s4, 0xc00
	s_addc_u32 s5, s5, 0
	global_load_ushort v120, v134, s[4:5]
	s_add_u32 s4, s4, 0xc00
	s_addc_u32 s5, s5, 0
	global_load_ushort v121, v134, s[4:5]
	s_add_u32 s4, s4, 0xc00
	s_addc_u32 s5, s5, 0
	global_load_ushort v122, v134, s[4:5]
	s_add_u32 s4, s4, 0xc00
	s_addc_u32 s5, s5, 0
	global_load_ushort v123, v134, s[4:5]
	s_add_u32 s4, s4, 0xc00
	s_addc_u32 s5, s5, 0
	global_load_ushort v124, v151, s[4:5]
	v_bfe_u32 v255, v152, 6, 2
	v_and_b32_e32 v253, 15, v152
	v_lshl_add_u32 v255, v255, 4, v253
	v_add_u32_e32 v255, s56, v255
	v_lshlrev_b32_e32 v255, 2, v255
	global_load_dword v65, v255, s[24:25]
	global_load_dword v67, v255, s[24:25] offset:2048
	s_add_u32 s0, s24, 0x1000
	s_addc_u32 s1, s25, 0
	global_load_dword v68, v255, s[0:1]
	global_load_dword v70, v255, s[0:1] offset:2048
	global_load_dword v73, v255, s[26:27]
	s_barrier
	s_waitcnt vmcnt(0)
	v_lshlrev_b32_e32 v90, 16, v90
	v_lshlrev_b32_e32 v91, 16, v91
	v_lshlrev_b32_e32 v92, 16, v92
	v_lshlrev_b32_e32 v93, 16, v93
	v_lshlrev_b32_e32 v94, 16, v94
	v_lshlrev_b32_e32 v95, 16, v95
	v_lshlrev_b32_e32 v96, 16, v96
	v_lshlrev_b32_e32 v97, 16, v97
	v_lshlrev_b32_e32 v98, 16, v98
	v_lshlrev_b32_e32 v99, 16, v99
	v_lshlrev_b32_e32 v100, 16, v100
	v_lshlrev_b32_e32 v101, 16, v101
	v_lshlrev_b32_e32 v102, 16, v102
	v_lshlrev_b32_e32 v103, 16, v103
	v_lshlrev_b32_e32 v104, 16, v104
	v_lshlrev_b32_e32 v105, 16, v105
	v_lshlrev_b32_e32 v106, 16, v106
	v_lshlrev_b32_e32 v107, 16, v107
	v_lshlrev_b32_e32 v108, 16, v108
	v_lshlrev_b32_e32 v109, 16, v109
	v_lshlrev_b32_e32 v110, 16, v110
	v_lshlrev_b32_e32 v111, 16, v111
	v_lshlrev_b32_e32 v112, 16, v112
	v_lshlrev_b32_e32 v113, 16, v113
	v_lshlrev_b32_e32 v114, 16, v114
	v_lshlrev_b32_e32 v115, 16, v115
	v_lshlrev_b32_e32 v116, 16, v116
	v_lshlrev_b32_e32 v117, 16, v117
	v_lshlrev_b32_e32 v118, 16, v118
	v_lshlrev_b32_e32 v119, 16, v119
	v_lshlrev_b32_e32 v120, 16, v120
	v_lshlrev_b32_e32 v121, 16, v121
	v_lshlrev_b32_e32 v122, 16, v122
	v_lshlrev_b32_e32 v123, 16, v123
	v_lshlrev_b32_e32 v124, 16, v124
	v_mul_f32_e32 v90, v90, v202
	v_mul_f32_e32 v91, v91, v202
	v_mul_f32_e32 v124, v124, v203
	v_fma_f32 v162, v90, v65, v73
	v_fma_f32 v162, v91, v67, v162
	v_fma_f32 v162, v92, v68, v162
	v_fma_f32 v162, v93, v70, v162
	v_fma_f32 v163, v91, v65, v73
	v_fma_f32 v163, v92, v67, v163
	v_fma_f32 v163, v93, v68, v163
	v_fma_f32 v163, v94, v70, v163
	v_fma_f32 v164, v92, v65, v73
	v_fma_f32 v164, v93, v67, v164
	v_fma_f32 v164, v94, v68, v164
; __device__ __forceinline__ void lru_tile(const Params& P, int chunk, int head, int pass, char* smem_raw) {
;     ...
; #pragma unroll
;     for (int i = 0; i < 32; ++i) {
;       const float v = cb + uv[i] * w0 + uv[i + 1] * w1 + uv[i + 2] * w2 + uv[i + 3] * w3;
;       sm_uc[(q * 32 + i) * LDSS + ch] = f2bf(v);
;     }
;   }
	v_fma_f32 v164, v95, v70, v164
	v_fma_f32 v165, v93, v65, v73
	v_fma_f32 v165, v94, v67, v165
	v_fma_f32 v165, v95, v68, v165
	v_fma_f32 v165, v96, v70, v165
	v_fma_f32 v166, v94, v65, v73
	v_fma_f32 v166, v95, v67, v166
	v_fma_f32 v166, v96, v68, v166
	v_fma_f32 v166, v97, v70, v166
	v_fma_f32 v167, v95, v65, v73
	v_fma_f32 v167, v96, v67, v167
	v_fma_f32 v167, v97, v68, v167
	v_fma_f32 v167, v98, v70, v167
	v_fma_f32 v168, v96, v65, v73
	v_fma_f32 v168, v97, v67, v168
	v_fma_f32 v168, v98, v68, v168
	v_fma_f32 v168, v99, v70, v168
	v_fma_f32 v169, v97, v65, v73
	v_fma_f32 v169, v98, v67, v169
	v_fma_f32 v169, v99, v68, v169
	v_fma_f32 v169, v100, v70, v169
	v_fma_f32 v170, v98, v65, v73
	v_fma_f32 v170, v99, v67, v170
	v_fma_f32 v170, v100, v68, v170
	v_fma_f32 v170, v101, v70, v170
	v_fma_f32 v171, v99, v65, v73
	v_fma_f32 v171, v100, v67, v171
	v_fma_f32 v171, v101, v68, v171
	v_fma_f32 v171, v102, v70, v171
	v_fma_f32 v172, v100, v65, v73
	v_fma_f32 v172, v101, v67, v172
	v_fma_f32 v172, v102, v68, v172
	v_fma_f32 v172, v103, v70, v172
	v_fma_f32 v173, v101, v65, v73
	v_fma_f32 v173, v102, v67, v173
	v_fma_f32 v173, v103, v68, v173
	v_fma_f32 v173, v104, v70, v173
	v_fma_f32 v174, v102, v65, v73
	v_fma_f32 v174, v103, v67, v174
	v_fma_f32 v174, v104, v68, v174
	v_fma_f32 v174, v105, v70, v174
	v_fma_f32 v175, v103, v65, v73
	v_fma_f32 v175, v104, v67, v175
	v_fma_f32 v175, v105, v68, v175
	v_fma_f32 v175, v106, v70, v175
	v_fma_f32 v176, v104, v65, v73
	v_fma_f32 v176, v105, v67, v176
	v_fma_f32 v176, v106, v68, v176
	v_fma_f32 v176, v107, v70, v176
	v_fma_f32 v177, v105, v65, v73
	v_fma_f32 v177, v106, v67, v177
	v_fma_f32 v177, v107, v68, v177
	v_fma_f32 v177, v108, v70, v177
	v_fma_f32 v178, v106, v65, v73
	v_fma_f32 v178, v107, v67, v178
	v_fma_f32 v178, v108, v68, v178
	v_fma_f32 v178, v109, v70, v178
	v_fma_f32 v179, v107, v65, v73
	v_fma_f32 v179, v108, v67, v179
	v_fma_f32 v179, v109, v68, v179
	v_fma_f32 v179, v110, v70, v179
	v_fma_f32 v180, v108, v65, v73
	v_fma_f32 v180, v109, v67, v180
	v_fma_f32 v180, v110, v68, v180
	v_fma_f32 v180, v111, v70, v180
	v_fma_f32 v181, v109, v65, v73
	v_fma_f32 v181, v110, v67, v181
	v_fma_f32 v181, v111, v68, v181
	v_fma_f32 v181, v112, v70, v181
	v_fma_f32 v182, v110, v65, v73
	v_fma_f32 v182, v111, v67, v182
	v_fma_f32 v182, v112, v68, v182
	v_fma_f32 v182, v113, v70, v182
	v_fma_f32 v183, v111, v65, v73
	v_fma_f32 v183, v112, v67, v183
	v_fma_f32 v183, v113, v68, v183
	v_fma_f32 v183, v114, v70, v183
	v_fma_f32 v184, v112, v65, v73
	v_fma_f32 v184, v113, v67, v184
	v_fma_f32 v184, v114, v68, v184
	v_fma_f32 v184, v115, v70, v184
	v_fma_f32 v185, v113, v65, v73
	v_fma_f32 v185, v114, v67, v185
	v_fma_f32 v185, v115, v68, v185
	v_fma_f32 v185, v116, v70, v185
	v_fma_f32 v186, v114, v65, v73
	v_fma_f32 v186, v115, v67, v186
	v_fma_f32 v186, v116, v68, v186
	v_fma_f32 v186, v117, v70, v186
	v_fma_f32 v187, v115, v65, v73
	v_fma_f32 v187, v116, v67, v187
	v_fma_f32 v187, v117, v68, v187
	v_fma_f32 v187, v118, v70, v187
	v_fma_f32 v188, v116, v65, v73
	v_fma_f32 v188, v117, v67, v188
	v_fma_f32 v188, v118, v68, v188
	v_fma_f32 v188, v119, v70, v188
	v_fma_f32 v189, v117, v65, v73
	v_fma_f32 v189, v118, v67, v189
	v_fma_f32 v189, v119, v68, v189
	v_fma_f32 v189, v120, v70, v189
	v_fma_f32 v190, v118, v65, v73
	v_fma_f32 v190, v119, v67, v190
	v_fma_f32 v190, v120, v68, v190
	v_fma_f32 v190, v121, v70, v190
	v_fma_f32 v191, v119, v65, v73
	v_fma_f32 v191, v120, v67, v191
	v_fma_f32 v191, v121, v68, v191
	v_fma_f32 v191, v122, v70, v191
	v_fma_f32 v192, v120, v65, v73
	v_fma_f32 v192, v121, v67, v192
	v_fma_f32 v192, v122, v68, v192
	v_fma_f32 v192, v123, v70, v192
	v_fma_f32 v193, v121, v65, v73
	v_fma_f32 v193, v122, v67, v193
	v_fma_f32 v193, v123, v68, v193
	v_fma_f32 v193, v124, v70, v193
	v_cvt_pk_bf16_f32 v162, v162, v162
	v_cvt_pk_bf16_f32 v163, v163, v163
	v_cvt_pk_bf16_f32 v164, v164, v164
	v_cvt_pk_bf16_f32 v165, v165, v165
	v_cvt_pk_bf16_f32 v166, v166, v166
	v_cvt_pk_bf16_f32 v167, v167, v167
	v_cvt_pk_bf16_f32 v168, v168, v168
	v_cvt_pk_bf16_f32 v169, v169, v169
	v_cvt_pk_bf16_f32 v170, v170, v170
	v_cvt_pk_bf16_f32 v171, v171, v171
	v_cvt_pk_bf16_f32 v172, v172, v172
	v_cvt_pk_bf16_f32 v173, v173, v173
	v_cvt_pk_bf16_f32 v174, v174, v174
	v_cvt_pk_bf16_f32 v175, v175, v175
	v_cvt_pk_bf16_f32 v176, v176, v176
	v_cvt_pk_bf16_f32 v177, v177, v177
	v_cvt_pk_bf16_f32 v178, v178, v178
	v_cvt_pk_bf16_f32 v179, v179, v179
	v_cvt_pk_bf16_f32 v180, v180, v180
	v_cvt_pk_bf16_f32 v181, v181, v181
	v_cvt_pk_bf16_f32 v182, v182, v182
	v_cvt_pk_bf16_f32 v183, v183, v183
	v_cvt_pk_bf16_f32 v184, v184, v184
	v_cvt_pk_bf16_f32 v185, v185, v185
	v_cvt_pk_bf16_f32 v186, v186, v186
	v_cvt_pk_bf16_f32 v187, v187, v187
	v_cvt_pk_bf16_f32 v188, v188, v188
	v_cvt_pk_bf16_f32 v189, v189, v189
	v_cvt_pk_bf16_f32 v190, v190, v190
	v_cvt_pk_bf16_f32 v191, v191, v191
	v_cvt_pk_bf16_f32 v192, v192, v192
	v_cvt_pk_bf16_f32 v193, v193, v193
	ds_write_b16 v89, v162 offset:0
	ds_write_b16 v89, v163 offset:128
	ds_write_b16 v130, v164 offset:256
	ds_write_b16 v130, v165 offset:384
	ds_write_b16 v89, v166 offset:512
	ds_write_b16 v89, v167 offset:640
	ds_write_b16 v130, v168 offset:768
	ds_write_b16 v130, v169 offset:896
	ds_write_b16 v89, v170 offset:1024
	ds_write_b16 v89, v171 offset:1152
	ds_write_b16 v130, v172 offset:1280
	ds_write_b16 v130, v173 offset:1408
	ds_write_b16 v89, v174 offset:1536
	ds_write_b16 v89, v175 offset:1664
	ds_write_b16 v130, v176 offset:1792
	ds_write_b16 v130, v177 offset:1920
	ds_write_b16 v89, v178 offset:2048
	ds_write_b16 v89, v179 offset:2176
	ds_write_b16 v130, v180 offset:2304
; __device__ __forceinline__ void lru_tile(const Params& P, int chunk, int head, int pass, char* smem_raw) {
;     ...
;   if (pass == 2 && tid < 128) {
;     const int d = tid >> 6;
;     float h = 0.f;
;     const float2* S = P.summ + (long)d * 264 * 512 + gch;
;     if (chunk < 256) {
;       const int b = chunk >> 6, j = chunk & 63;
;       if (d == 0) {
;         float2 s = S[(long)(256 + 2 * b) * 512]; h = s.x * h + s.y;
;         s = S[(long)(256 + 2 * b + 1) * 512]; h = s.x * h + s.y;
;         int i = 0;
;         for (; i + 8 <= j; i += 8) {
;           float2 sv[8];
; #pragma unroll
;           for (int u = 0; u < 8; ++u) sv[u] = S[(long)(b * 64 + i + u) * 512];
; #pragma unroll
;           for (int u = 0; u < 8; ++u) h = sv[u].x * h + sv[u].y;
;         }
;         for (; i < j; ++i) { s = S[(long)(b * 64 + i) * 512]; h = s.x * h + s.y; }
	ds_write_b16 v130, v181 offset:2432
	ds_write_b16 v89, v182 offset:2560
	ds_write_b16 v89, v183 offset:2688
	ds_write_b16 v130, v184 offset:2816
	ds_write_b16 v130, v185 offset:2944
	ds_write_b16 v89, v186 offset:3072
	ds_write_b16 v89, v187 offset:3200
	ds_write_b16 v130, v188 offset:3328
	ds_write_b16 v130, v189 offset:3456
	ds_write_b16 v89, v190 offset:3584
	ds_write_b16 v89, v191 offset:3712
	ds_write_b16 v130, v192 offset:3840
	ds_write_b16 v130, v193 offset:3968
	v_lshlrev_b32_e32 v162, 16, v162
	v_lshlrev_b32_e32 v163, 16, v163
	v_lshlrev_b32_e32 v164, 16, v164
	v_lshlrev_b32_e32 v165, 16, v165
	v_lshlrev_b32_e32 v166, 16, v166
	v_lshlrev_b32_e32 v167, 16, v167
	v_lshlrev_b32_e32 v168, 16, v168
	v_lshlrev_b32_e32 v169, 16, v169
	v_lshlrev_b32_e32 v170, 16, v170
	v_lshlrev_b32_e32 v171, 16, v171
	v_lshlrev_b32_e32 v172, 16, v172
	v_lshlrev_b32_e32 v173, 16, v173
	v_lshlrev_b32_e32 v174, 16, v174
	v_lshlrev_b32_e32 v175, 16, v175
	v_lshlrev_b32_e32 v176, 16, v176
	v_lshlrev_b32_e32 v177, 16, v177
	v_lshlrev_b32_e32 v178, 16, v178
	v_lshlrev_b32_e32 v179, 16, v179
	v_lshlrev_b32_e32 v180, 16, v180
	v_lshlrev_b32_e32 v181, 16, v181
	v_lshlrev_b32_e32 v182, 16, v182
	v_lshlrev_b32_e32 v183, 16, v183
	v_lshlrev_b32_e32 v184, 16, v184
	v_lshlrev_b32_e32 v185, 16, v185
	v_lshlrev_b32_e32 v186, 16, v186
	v_lshlrev_b32_e32 v187, 16, v187
	v_lshlrev_b32_e32 v188, 16, v188
	v_lshlrev_b32_e32 v189, 16, v189
	v_lshlrev_b32_e32 v190, 16, v190
	v_lshlrev_b32_e32 v191, 16, v191
	v_lshlrev_b32_e32 v192, 16, v192
	v_lshlrev_b32_e32 v193, 16, v193
	s_waitcnt lgkmcnt(0)
	s_barrier
	v_mov_b32_e32 v65, 0
	s_lshl_b32 s0, s56, 3
	s_add_u32 s0, s0, 0x0
	s_add_u32 s4, s18, s0
	s_addc_u32 s5, s19, 0
	s_cmp_lt_u32 s71, 256
	s_cbranch_scc0 .Lmy_lrub_lb0_ctx
	s_lshr_b32 s0, s71, 6
	s_lshl_b32 s1, s0, 1
	s_add_u32 s1, s1, 256
	s_add_u32 s60, s1, 0
	s_lshl_b32 s60, s60, 12
	s_add_u32 s60, s4, s60
	s_addc_u32 s61, s5, 0
	global_load_dwordx2 v[0:1], v250, s[60:61]
	s_add_u32 s60, s1, 1
	s_lshl_b32 s60, s60, 12
	s_add_u32 s60, s4, s60
	s_addc_u32 s61, s5, 0
	global_load_dwordx2 v[2:3], v250, s[60:61]
	s_lshl_b32 s0, s0, 6
	s_mov_b32 s1, s57
	s_mov_b32 s60, s0
	s_waitcnt vmcnt(0)
	v_fma_f32 v65, v0, v65, v1
	v_fma_f32 v65, v2, v65, v3
.Lmy_lrub_lb0_loop:
	s_cmp_lt_i32 s1, 1
	s_cbranch_scc1 .Lmy_lrub_lb0_done
	s_add_u32 s61, s60, 0
	s_max_i32 s61, s61, s0
	s_add_u32 vcc_lo, s0, 63
	s_min_i32 s61, s61, vcc_lo
	s_lshl_b32 s61, s61, 12
	s_add_u32 vcc_lo, s4, s61
	s_addc_u32 vcc_hi, s5, 0
	global_load_dwordx2 v[0:1], v250, vcc
	s_add_u32 s61, s60, 1
	s_max_i32 s61, s61, s0
	s_add_u32 vcc_lo, s0, 63
	s_min_i32 s61, s61, vcc_lo
	s_lshl_b32 s61, s61, 12
	s_add_u32 vcc_lo, s4, s61
	s_addc_u32 vcc_hi, s5, 0
	global_load_dwordx2 v[2:3], v250, vcc
	s_add_u32 s61, s60, 2
	s_max_i32 s61, s61, s0
	s_add_u32 vcc_lo, s0, 63
	s_min_i32 s61, s61, vcc_lo
	s_lshl_b32 s61, s61, 12
	s_add_u32 vcc_lo, s4, s61
	s_addc_u32 vcc_hi, s5, 0
	global_load_dwordx2 v[4:5], v250, vcc
	s_add_u32 s61, s60, 3
	s_max_i32 s61, s61, s0
	s_add_u32 vcc_lo, s0, 63
	s_min_i32 s61, s61, vcc_lo
	s_lshl_b32 s61, s61, 12
	s_add_u32 vcc_lo, s4, s61
	s_addc_u32 vcc_hi, s5, 0
	global_load_dwordx2 v[6:7], v250, vcc
	s_add_u32 s61, s60, 4
	s_max_i32 s61, s61, s0
	s_add_u32 vcc_lo, s0, 63
	s_min_i32 s61, s61, vcc_lo
	s_lshl_b32 s61, s61, 12
	s_add_u32 vcc_lo, s4, s61
	s_addc_u32 vcc_hi, s5, 0
	global_load_dwordx2 v[8:9], v250, vcc
	s_add_u32 s61, s60, 5
	s_max_i32 s61, s61, s0
	s_add_u32 vcc_lo, s0, 63
	s_min_i32 s61, s61, vcc_lo
	s_lshl_b32 s61, s61, 12
	s_add_u32 vcc_lo, s4, s61
	s_addc_u32 vcc_hi, s5, 0
	global_load_dwordx2 v[10:11], v250, vcc
	s_add_u32 s61, s60, 6
	s_max_i32 s61, s61, s0
	s_add_u32 vcc_lo, s0, 63
	s_min_i32 s61, s61, vcc_lo
	s_lshl_b32 s61, s61, 12
	s_add_u32 vcc_lo, s4, s61
	s_addc_u32 vcc_hi, s5, 0
	global_load_dwordx2 v[12:13], v250, vcc
	s_add_u32 s61, s60, 7
	s_max_i32 s61, s61, s0
	s_add_u32 vcc_lo, s0, 63
	s_min_i32 s61, s61, vcc_lo
	s_lshl_b32 s61, s61, 12
	s_add_u32 vcc_lo, s4, s61
	s_addc_u32 vcc_hi, s5, 0
	global_load_dwordx2 v[14:15], v250, vcc
	s_waitcnt vmcnt(0)
	s_cmp_gt_i32 s1, 0
	s_cselect_b64 vcc, -1, 0
	v_cndmask_b32_e64 v0, 1.0, v0, vcc
	v_cndmask_b32_e64 v1, 0, v1, vcc
	v_fma_f32 v65, v0, v65, v1
	s_cmp_gt_i32 s1, 1
	s_cselect_b64 vcc, -1, 0
	v_cndmask_b32_e64 v2, 1.0, v2, vcc
	v_cndmask_b32_e64 v3, 0, v3, vcc
	v_fma_f32 v65, v2, v65, v3
	s_cmp_gt_i32 s1, 2
	s_cselect_b64 vcc, -1, 0
	v_cndmask_b32_e64 v4, 1.0, v4, vcc
	v_cndmask_b32_e64 v5, 0, v5, vcc
	v_fma_f32 v65, v4, v65, v5
	s_cmp_gt_i32 s1, 3
	s_cselect_b64 vcc, -1, 0
	v_cndmask_b32_e64 v6, 1.0, v6, vcc
	v_cndmask_b32_e64 v7, 0, v7, vcc
	v_fma_f32 v65, v6, v65, v7
	s_cmp_gt_i32 s1, 4
	s_cselect_b64 vcc, -1, 0
	v_cndmask_b32_e64 v8, 1.0, v8, vcc
	v_cndmask_b32_e64 v9, 0, v9, vcc
	v_fma_f32 v65, v8, v65, v9
	s_cmp_gt_i32 s1, 5
	s_cselect_b64 vcc, -1, 0
	v_cndmask_b32_e64 v10, 1.0, v10, vcc
	v_cndmask_b32_e64 v11, 0, v11, vcc
	v_fma_f32 v65, v10, v65, v11
	s_cmp_gt_i32 s1, 6
	s_cselect_b64 vcc, -1, 0
	v_cndmask_b32_e64 v12, 1.0, v12, vcc
	v_cndmask_b32_e64 v13, 0, v13, vcc
	v_fma_f32 v65, v12, v65, v13
	s_cmp_gt_i32 s1, 7
	s_cselect_b64 vcc, -1, 0
	v_cndmask_b32_e64 v14, 1.0, v14, vcc
	v_cndmask_b32_e64 v15, 0, v15, vcc
	v_fma_f32 v65, v14, v65, v15
	s_sub_u32 s1, s1, 8
	s_add_u32 s60, s60, 8
	s_branch .Lmy_lrub_lb0_loop
.Lmy_lrub_lb0_ctx:
	s_sub_u32 s0, s71, 256
	s_and_b32 s1, s0, 1
	s_cmp_eq_u32 s1, 1
	s_cbranch_scc0 .Lmy_lrub_lb0_done
	s_and_b32 s0, s0, -2
	s_add_u32 s0, s0, 256
	s_lshl_b32 s0, s0, 12
	s_add_u32 s60, s4, s0
	s_addc_u32 s61, s5, 0
	global_load_dwordx2 v[0:1], v250, s[60:61]
	s_waitcnt vmcnt(0)
	v_mov_b32_e32 v65, v1
; __device__ __forceinline__ void lru_tile(const Params& P, int chunk, int head, int pass, char* smem_raw) {
;     ...
;       } else {
;         float2 s = S[(long)(256 + 2 * b + 1) * 512]; h = s.x * h + s.y;
;         s = S[(long)(256 + 2 * b) * 512]; h = s.x * h + s.y;
;         int i = 63;
;         for (; i - 8 >= j; i -= 8) {
;           float2 sv[8];
; #pragma unroll
;           for (int u = 0; u < 8; ++u) sv[u] = S[(long)(b * 64 + i - u) * 512];
; #pragma unroll
;           for (int u = 0; u < 8; ++u) h = sv[u].x * h + sv[u].y;
;         }
;         for (; i > j; --i) { s = S[(long)(b * 64 + i) * 512]; h = s.x * h + s.y; }
;       }
;     } else {
;       const int b = (chunk - 256) >> 1, j = (chunk - 256) & 1;
;       if (d == 0) { if (j == 1) { const float2 s = S[(long)(256 + 2 * b) * 512]; h = s.y; } }
;       else        { if (j == 0) { const float2 s = S[(long)(256 + 2 * b + 1) * 512]; h = s.y; } }
;     }
;     sm_init[d * 64 + ch] = h;
;     ...
; #pragma unroll
;       for (int t = 0; t < 8; ++t) acc[t] = f32x4{0.f, 0.f, 0.f, 0.f};
; #pragma unroll
;       for (int s = 0; s < 2; ++s) {
;         const bf16x8 af = *reinterpret_cast<const bf16x8*>(&sm_uc[(sb * 64 + wid * 16 + (lane & 15)) * LDSS + s * 32 + (lane >> 4) * 8]);
; #pragma unroll
;         for (int t = 0; t < 8; ++t) {
;           const bf16x8 bfr = *reinterpret_cast<const bf16x8*>(&sm_w[(t * 16 + (lane & 15)) * LDSS + s * 32 + (lane >> 4) * 8]);
;           acc[t] = __builtin_amdgcn_mfma_f32_16x16x32_bf16(af, bfr, acc[t], 0, 0, 0);
;         }
;       }
.Lmy_lrub_lb0_done:
	v_mov_b32_e32 v67, 0
	s_lshl_b32 s0, s56, 3
	s_add_u32 s0, s0, 0x108000
	s_add_u32 s4, s18, s0
	s_addc_u32 s5, s19, 0
	s_cmp_lt_u32 s71, 256
	s_cbranch_scc0 .Lmy_lrub_lb1_ctx
	s_lshr_b32 s0, s71, 6
	s_lshl_b32 s1, s0, 1
	s_add_u32 s1, s1, 256
	s_add_u32 s60, s1, 1
	s_lshl_b32 s60, s60, 12
	s_add_u32 s60, s4, s60
	s_addc_u32 s61, s5, 0
	global_load_dwordx2 v[0:1], v250, s[60:61]
	s_add_u32 s60, s1, 0
	s_lshl_b32 s60, s60, 12
	s_add_u32 s60, s4, s60
	s_addc_u32 s61, s5, 0
	global_load_dwordx2 v[2:3], v250, s[60:61]
	s_lshl_b32 s0, s0, 6
	s_sub_u32 s1, 63, s57
	s_add_u32 s60, s0, 63
	s_waitcnt vmcnt(0)
	v_fma_f32 v67, v0, v67, v1
	v_fma_f32 v67, v2, v67, v3
.Lmy_lrub_lb1_loop:
	s_cmp_lt_i32 s1, 1
	s_cbranch_scc1 .Lmy_lrub_lb1_done
	s_sub_u32 s61, s60, 0
	s_max_i32 s61, s61, s0
	s_add_u32 vcc_lo, s0, 63
	s_min_i32 s61, s61, vcc_lo
	s_lshl_b32 s61, s61, 12
	s_add_u32 vcc_lo, s4, s61
	s_addc_u32 vcc_hi, s5, 0
	global_load_dwordx2 v[0:1], v250, vcc
	s_sub_u32 s61, s60, 1
	s_max_i32 s61, s61, s0
	s_add_u32 vcc_lo, s0, 63
	s_min_i32 s61, s61, vcc_lo
	s_lshl_b32 s61, s61, 12
	s_add_u32 vcc_lo, s4, s61
	s_addc_u32 vcc_hi, s5, 0
	global_load_dwordx2 v[2:3], v250, vcc
	s_sub_u32 s61, s60, 2
	s_max_i32 s61, s61, s0
	s_add_u32 vcc_lo, s0, 63
	s_min_i32 s61, s61, vcc_lo
	s_lshl_b32 s61, s61, 12
	s_add_u32 vcc_lo, s4, s61
	s_addc_u32 vcc_hi, s5, 0
	global_load_dwordx2 v[4:5], v250, vcc
	s_sub_u32 s61, s60, 3
	s_max_i32 s61, s61, s0
	s_add_u32 vcc_lo, s0, 63
	s_min_i32 s61, s61, vcc_lo
	s_lshl_b32 s61, s61, 12
	s_add_u32 vcc_lo, s4, s61
	s_addc_u32 vcc_hi, s5, 0
	global_load_dwordx2 v[6:7], v250, vcc
	s_sub_u32 s61, s60, 4
	s_max_i32 s61, s61, s0
	s_add_u32 vcc_lo, s0, 63
	s_min_i32 s61, s61, vcc_lo
	s_lshl_b32 s61, s61, 12
	s_add_u32 vcc_lo, s4, s61
	s_addc_u32 vcc_hi, s5, 0
	global_load_dwordx2 v[8:9], v250, vcc
	s_sub_u32 s61, s60, 5
	s_max_i32 s61, s61, s0
	s_add_u32 vcc_lo, s0, 63
	s_min_i32 s61, s61, vcc_lo
	s_lshl_b32 s61, s61, 12
	s_add_u32 vcc_lo, s4, s61
	s_addc_u32 vcc_hi, s5, 0
	global_load_dwordx2 v[10:11], v250, vcc
	s_sub_u32 s61, s60, 6
	s_max_i32 s61, s61, s0
	s_add_u32 vcc_lo, s0, 63
	s_min_i32 s61, s61, vcc_lo
	s_lshl_b32 s61, s61, 12
	s_add_u32 vcc_lo, s4, s61
	s_addc_u32 vcc_hi, s5, 0
	global_load_dwordx2 v[12:13], v250, vcc
	s_sub_u32 s61, s60, 7
	s_max_i32 s61, s61, s0
	s_add_u32 vcc_lo, s0, 63
	s_min_i32 s61, s61, vcc_lo
	s_lshl_b32 s61, s61, 12
	s_add_u32 vcc_lo, s4, s61
	s_addc_u32 vcc_hi, s5, 0
	global_load_dwordx2 v[14:15], v250, vcc
	s_waitcnt vmcnt(0)
	s_cmp_gt_i32 s1, 0
	s_cselect_b64 vcc, -1, 0
	v_cndmask_b32_e64 v0, 1.0, v0, vcc
	v_cndmask_b32_e64 v1, 0, v1, vcc
	v_fma_f32 v67, v0, v67, v1
	s_cmp_gt_i32 s1, 1
	s_cselect_b64 vcc, -1, 0
	v_cndmask_b32_e64 v2, 1.0, v2, vcc
	v_cndmask_b32_e64 v3, 0, v3, vcc
	v_fma_f32 v67, v2, v67, v3
	s_cmp_gt_i32 s1, 2
	s_cselect_b64 vcc, -1, 0
	v_cndmask_b32_e64 v4, 1.0, v4, vcc
	v_cndmask_b32_e64 v5, 0, v5, vcc
	v_fma_f32 v67, v4, v67, v5
	s_cmp_gt_i32 s1, 3
	s_cselect_b64 vcc, -1, 0
	v_cndmask_b32_e64 v6, 1.0, v6, vcc
	v_cndmask_b32_e64 v7, 0, v7, vcc
	v_fma_f32 v67, v6, v67, v7
	s_cmp_gt_i32 s1, 4
	s_cselect_b64 vcc, -1, 0
	v_cndmask_b32_e64 v8, 1.0, v8, vcc
	v_cndmask_b32_e64 v9, 0, v9, vcc
	v_fma_f32 v67, v8, v67, v9
	s_cmp_gt_i32 s1, 5
	s_cselect_b64 vcc, -1, 0
	v_cndmask_b32_e64 v10, 1.0, v10, vcc
	v_cndmask_b32_e64 v11, 0, v11, vcc
	v_fma_f32 v67, v10, v67, v11
	s_cmp_gt_i32 s1, 6
	s_cselect_b64 vcc, -1, 0
	v_cndmask_b32_e64 v12, 1.0, v12, vcc
	v_cndmask_b32_e64 v13, 0, v13, vcc
	v_fma_f32 v67, v12, v67, v13
	s_cmp_gt_i32 s1, 7
	s_cselect_b64 vcc, -1, 0
	v_cndmask_b32_e64 v14, 1.0, v14, vcc
	v_cndmask_b32_e64 v15, 0, v15, vcc
	v_fma_f32 v67, v14, v67, v15
	s_sub_u32 s1, s1, 8
	s_sub_u32 s60, s60, 8
	s_branch .Lmy_lrub_lb1_loop
.Lmy_lrub_lb1_ctx:
	s_sub_u32 s0, s71, 256
	s_and_b32 s1, s0, 1
	s_cmp_eq_u32 s1, 0
	s_cbranch_scc0 .Lmy_lrub_lb1_done
	s_and_b32 s0, s0, -2
	s_add_u32 s0, s0, 257
	s_lshl_b32 s0, s0, 12
	s_add_u32 s60, s4, s0
	s_addc_u32 s61, s5, 0
	global_load_dwordx2 v[0:1], v250, s[60:61]
	s_waitcnt vmcnt(0)
	v_mov_b32_e32 v67, v1
.Lmy_lrub_lb1_done:
	s_lshl_b32 s0, s56, 8
	s_add_u32 s0, s0, 0x0
	s_add_u32 s4, s20, s0
	s_addc_u32 s5, s21, 0
	global_load_dwordx4 v[238:241], v251, s[4:5]
	global_load_dwordx4 v[242:245], v251, s[4:5] offset:64
	s_add_u32 s4, s4, 0x2000
	s_addc_u32 s5, s5, 0
	global_load_dwordx4 v[246:249], v251, s[4:5]
	global_load_dwordx4 v[194:197], v251, s[4:5] offset:64
	v_bfe_u32 v255, v152, 6, 2
	v_and_b32_e32 v253, 15, v152
	v_lshl_add_u32 v255, v255, 4, v253
	v_add_u32_e32 v255, s56, v255
	v_lshlrev_b32_e32 v255, 2, v255
	s_add_u32 s0, s28, 0x0
	s_addc_u32 s1, s29, 0
	global_load_dword v75, v255, s[0:1]
	s_add_u32 s0, s30, 0x0
	s_addc_u32 s1, s31, 0
	global_load_dword v84, v255, s[0:1]
	s_add_u32 s0, s36, 0x0
	s_addc_u32 s1, s37, 0
	global_load_dword v85, v255, s[0:1]
	ds_read_b128 v[76:79], v131 offset:0
	ds_read_b128 v[80:83], v133 offset:0
	ds_read_b128 v[122:125], v131 offset:512
	ds_read_b128 v[126:129], v133 offset:512
	s_waitcnt vmcnt(3)
	s_waitcnt lgkmcnt(3)
	v_mfma_f32_16x16x32_bf16 v[0:3], v[76:79], v[238:241], 0
	v_mfma_f32_16x16x32_bf16 v[90:93], v[76:79], v[246:249], 0
	ds_read_b128 v[76:79], v131 offset:1024
	s_waitcnt lgkmcnt(3)
	v_mfma_f32_16x16x32_bf16 v[0:3], v[80:83], v[242:245], v[0:3]
	v_mfma_f32_16x16x32_bf16 v[90:93], v[80:83], v[194:197], v[90:93]
	ds_read_b128 v[80:83], v133 offset:1024
	s_waitcnt lgkmcnt(3)
	v_mfma_f32_16x16x32_bf16 v[4:7], v[122:125], v[238:241], 0
	v_mfma_f32_16x16x32_bf16 v[94:97], v[122:125], v[246:249], 0
	ds_read_b128 v[122:125], v131 offset:1536
	s_waitcnt lgkmcnt(3)
; __device__ __forceinline__ float bf2f(u16 h) { return __uint_as_float(((unsigned)h) << 16); }
; __device__ __forceinline__ void lru_tile(const Params& P, int chunk, int head, int pass, char* smem_raw) {
;     ...
; #pragma unroll
;     for (int tc = 0; tc < 4; ++tc) {
;       const int cidx = d * 512 + head * 64 + 16 * tc + (lane & 15);
;       ba[tc] = P.b_a[cidx] * -1.4426950408889634f; bi[tc] = P.b_i[cidx] * -1.4426950408889634f;
;       const float nl = -P.lam[cidx];
;       const float e_ = __expf(nl);
;       const float sp = (nl > 20.f) ? nl
;                      : (e_ < 0.03f ? e_ * (1.f - e_ * (0.5f - e_ * (0.33333334f - 0.25f * e_))) : __logf(1.f + e_));
;       c8[tc] = 8.f * 1.4426950408889634f * sp;
;     }
;     __syncthreads();
;     float cA = 1.f, cB = (pass == 2) ? sm_init[d * 64 + ch] : 0.f;
;     for (int sbi = 0; sbi < 2; ++sbi) {
;       const int sb = (d == 0) ? sbi : 1 - sbi;
;       f32x4 acc[8];
; #pragma unroll
;       for (int t = 0; t < 8; ++t) acc[t] = f32x4{0.f, 0.f, 0.f, 0.f};
; #pragma unroll
;       for (int s = 0; s < 2; ++s) {
;         const bf16x8 af = *reinterpret_cast<const bf16x8*>(&sm_uc[(sb * 64 + wid * 16 + (lane & 15)) * LDSS + s * 32 + (lane >> 4) * 8]);
; #pragma unroll
;         for (int t = 0; t < 8; ++t) {
;           const bf16x8 bfr = *reinterpret_cast<const bf16x8*>(&sm_w[(t * 16 + (lane & 15)) * LDSS + s * 32 + (lane >> 4) * 8]);
;           acc[t] = __builtin_amdgcn_mfma_f32_16x16x32_bf16(af, bfr, acc[t], 0, 0, 0);
;         }
;       }
; #pragma unroll
;       for (int tc = 0; tc < 4; ++tc)
; #pragma unroll
;         for (int reg = 0; reg < 4; ++reg) {
;           const int tl = wid * 16 + (lane >> 4) * 4 + reg;
;           const int c = 16 * tc + (lane & 15);
;           const float r = __builtin_amdgcn_rcpf(1.f + __builtin_amdgcn_exp2f(acc[tc][reg] + ba[tc]));
;           const float ii = __builtin_amdgcn_rcpf(1.f + __builtin_amdgcn_exp2f(acc[tc + 4][reg] + bi[tc]));
;           const float la = -c8[tc] * r;
;           const float a = __builtin_amdgcn_exp2f(la);
;           const float ucv = bf2f(sm_uc[(sb * 64 + tl) * LDSS + c]);
;           const float bt = __builtin_amdgcn_sqrtf(fmaxf(1.f - a * a, 0.f)) * (ii * ucv);
;           sm_a[tl * 64 + c] = a;
;           sm_b[tl * 64 + c] = bt;
;         }
	v_mfma_f32_16x16x32_bf16 v[4:7], v[126:129], v[242:245], v[4:7]
	v_mfma_f32_16x16x32_bf16 v[94:97], v[126:129], v[194:197], v[94:97]
	ds_read_b128 v[126:129], v133 offset:1536
	s_waitcnt lgkmcnt(3)
	v_mfma_f32_16x16x32_bf16 v[8:11], v[76:79], v[238:241], 0
	v_mfma_f32_16x16x32_bf16 v[98:101], v[76:79], v[246:249], 0
	ds_read_b128 v[76:79], v131 offset:2048
	s_waitcnt lgkmcnt(3)
	v_mfma_f32_16x16x32_bf16 v[8:11], v[80:83], v[242:245], v[8:11]
	v_mfma_f32_16x16x32_bf16 v[98:101], v[80:83], v[194:197], v[98:101]
	ds_read_b128 v[80:83], v133 offset:2048
	s_waitcnt lgkmcnt(3)
	v_mfma_f32_16x16x32_bf16 v[12:15], v[122:125], v[238:241], 0
	v_mfma_f32_16x16x32_bf16 v[102:105], v[122:125], v[246:249], 0
	ds_read_b128 v[122:125], v131 offset:2560
	s_waitcnt lgkmcnt(3)
	v_mfma_f32_16x16x32_bf16 v[12:15], v[126:129], v[242:245], v[12:15]
	v_mfma_f32_16x16x32_bf16 v[102:105], v[126:129], v[194:197], v[102:105]
	ds_read_b128 v[126:129], v133 offset:2560
	s_waitcnt lgkmcnt(3)
	v_mfma_f32_16x16x32_bf16 v[16:19], v[76:79], v[238:241], 0
	v_mfma_f32_16x16x32_bf16 v[106:109], v[76:79], v[246:249], 0
	ds_read_b128 v[76:79], v131 offset:3072
	s_waitcnt lgkmcnt(3)
	v_mfma_f32_16x16x32_bf16 v[16:19], v[80:83], v[242:245], v[16:19]
	v_mfma_f32_16x16x32_bf16 v[106:109], v[80:83], v[194:197], v[106:109]
	ds_read_b128 v[80:83], v133 offset:3072
	s_waitcnt lgkmcnt(3)
	v_mfma_f32_16x16x32_bf16 v[20:23], v[122:125], v[238:241], 0
	v_mfma_f32_16x16x32_bf16 v[110:113], v[122:125], v[246:249], 0
	ds_read_b128 v[122:125], v131 offset:3584
	s_waitcnt lgkmcnt(3)
	v_mfma_f32_16x16x32_bf16 v[20:23], v[126:129], v[242:245], v[20:23]
	v_mfma_f32_16x16x32_bf16 v[110:113], v[126:129], v[194:197], v[110:113]
	ds_read_b128 v[126:129], v133 offset:3584
	s_waitcnt lgkmcnt(3)
	v_mfma_f32_16x16x32_bf16 v[24:27], v[76:79], v[238:241], 0
	v_mfma_f32_16x16x32_bf16 v[114:117], v[76:79], v[246:249], 0
	s_waitcnt lgkmcnt(2)
	v_mfma_f32_16x16x32_bf16 v[24:27], v[80:83], v[242:245], v[24:27]
	v_mfma_f32_16x16x32_bf16 v[114:117], v[80:83], v[194:197], v[114:117]
	s_waitcnt lgkmcnt(1)
	v_mfma_f32_16x16x32_bf16 v[28:31], v[122:125], v[238:241], 0
	v_mfma_f32_16x16x32_bf16 v[118:121], v[122:125], v[246:249], 0
	s_waitcnt lgkmcnt(0)
	v_mfma_f32_16x16x32_bf16 v[28:31], v[126:129], v[242:245], v[28:31]
	v_mfma_f32_16x16x32_bf16 v[118:121], v[126:129], v[194:197], v[118:121]
	s_waitcnt vmcnt(0)
	v_mul_f32_e32 v75, 0xbfb8aa3b, v75
	v_mul_f32_e32 v84, 0xbfb8aa3b, v84
	v_sub_f32_e32 v138, 0, v85
	v_mul_f32_e32 v139, 0x3fb8aa3b, v138
	v_exp_f32_e32 v139, v139
	v_mul_f32_e32 v140, 0xbe800000, v139
	v_add_f32_e32 v140, 0x3eaaaaab, v140
	v_fma_f32 v140, -v139, v140, 0.5
	v_fma_f32 v140, -v139, v140, 1.0
	v_mul_f32_e32 v140, v139, v140
	v_add_f32_e32 v141, 1.0, v139
	v_log_f32_e32 v141, v141
	v_mov_b32_e32 v255, 0x3cf5c28f
	v_mul_f32_e32 v141, 0x3f317218, v141
	v_cmp_gt_f32_e32 vcc, v255, v139
	s_nop 1
	v_cndmask_b32_e32 v140, v141, v140, vcc
	v_mov_b32_e32 v255, 0x41a00000
	v_cmp_lt_f32_e32 vcc, v255, v138
	s_nop 1
	v_cndmask_b32_e32 v140, v140, v138, vcc
	v_mul_f32_e32 v85, 0xc138aa3b, v140
	s_nop 7
	v_add_f32_e32 v0, v0, v75
	v_add_f32_e32 v1, v1, v75
	v_add_f32_e32 v2, v2, v75
	v_add_f32_e32 v3, v3, v75
	v_add_f32_e32 v90, v90, v84
	v_add_f32_e32 v91, v91, v84
	v_add_f32_e32 v92, v92, v84
	v_add_f32_e32 v93, v93, v84
	v_exp_f32_e32 v0, v0
	v_exp_f32_e32 v1, v1
	v_exp_f32_e32 v2, v2
	v_exp_f32_e32 v3, v3
	v_exp_f32_e32 v90, v90
	v_exp_f32_e32 v91, v91
	v_exp_f32_e32 v92, v92
	v_exp_f32_e32 v93, v93
	v_add_f32_e32 v0, 1.0, v0
	v_add_f32_e32 v1, 1.0, v1
	v_add_f32_e32 v2, 1.0, v2
	v_add_f32_e32 v3, 1.0, v3
	v_add_f32_e32 v90, 1.0, v90
	v_add_f32_e32 v91, 1.0, v91
	v_add_f32_e32 v92, 1.0, v92
	v_add_f32_e32 v93, 1.0, v93
	v_rcp_f32_e32 v0, v0
	v_rcp_f32_e32 v1, v1
	v_rcp_f32_e32 v2, v2
	v_rcp_f32_e32 v3, v3
	v_rcp_f32_e32 v90, v90
	v_rcp_f32_e32 v91, v91
	v_rcp_f32_e32 v92, v92
	v_rcp_f32_e32 v93, v93
	v_mul_f32_e32 v0, v85, v0
	v_mul_f32_e32 v1, v85, v1
	v_mul_f32_e32 v2, v85, v2
	v_mul_f32_e32 v3, v85, v3
	v_mul_f32_e32 v90, v90, v162
	v_mul_f32_e32 v91, v91, v163
	v_mul_f32_e32 v92, v92, v164
	v_mul_f32_e32 v93, v93, v165
	v_exp_f32_e32 v0, v0
	v_exp_f32_e32 v1, v1
	v_exp_f32_e32 v2, v2
	v_exp_f32_e32 v3, v3
	s_nop 0
	v_fma_f32 v138, -v0, v0, 1.0
	v_fma_f32 v139, -v1, v1, 1.0
	v_fma_f32 v140, -v2, v2, 1.0
	v_fma_f32 v141, -v3, v3, 1.0
	v_max_f32_e32 v138, 0, v138
	v_max_f32_e32 v139, 0, v139
	v_max_f32_e32 v140, 0, v140
	v_max_f32_e32 v141, 0, v141
	v_sqrt_f32_e32 v138, v138
	v_sqrt_f32_e32 v139, v139
	v_sqrt_f32_e32 v140, v140
	v_sqrt_f32_e32 v141, v141
	s_nop 0
	v_mul_f32_e32 v90, v138, v90
	v_mul_f32_e32 v91, v139, v91
	v_mul_f32_e32 v92, v140, v92
	v_mul_f32_e32 v93, v141, v93
	v_add_f32_e32 v4, v4, v75
	v_add_f32_e32 v5, v5, v75
	v_add_f32_e32 v6, v6, v75
	v_add_f32_e32 v7, v7, v75
	v_add_f32_e32 v94, v94, v84
	v_add_f32_e32 v95, v95, v84
	v_add_f32_e32 v96, v96, v84
	v_add_f32_e32 v97, v97, v84
	v_exp_f32_e32 v4, v4
	v_exp_f32_e32 v5, v5
	v_exp_f32_e32 v6, v6
	v_exp_f32_e32 v7, v7
	v_exp_f32_e32 v94, v94
	v_exp_f32_e32 v95, v95
	v_exp_f32_e32 v96, v96
	v_exp_f32_e32 v97, v97
	v_add_f32_e32 v4, 1.0, v4
	v_add_f32_e32 v5, 1.0, v5
	v_add_f32_e32 v6, 1.0, v6
	v_add_f32_e32 v7, 1.0, v7
	v_add_f32_e32 v94, 1.0, v94
	v_add_f32_e32 v95, 1.0, v95
	v_add_f32_e32 v96, 1.0, v96
	v_add_f32_e32 v97, 1.0, v97
	v_rcp_f32_e32 v4, v4
	v_rcp_f32_e32 v5, v5
	v_rcp_f32_e32 v6, v6
	v_rcp_f32_e32 v7, v7
	v_rcp_f32_e32 v94, v94
	v_rcp_f32_e32 v95, v95
	v_rcp_f32_e32 v96, v96
	v_rcp_f32_e32 v97, v97
	v_mul_f32_e32 v4, v85, v4
	v_mul_f32_e32 v5, v85, v5
	v_mul_f32_e32 v6, v85, v6
	v_mul_f32_e32 v7, v85, v7
; __device__ __forceinline__ float bf2f(u16 h) { return __uint_as_float(((unsigned)h) << 16); }
; __device__ __forceinline__ void lru_tile(const Params& P, int chunk, int head, int pass, char* smem_raw) {
;     ...
;       for (int tc = 0; tc < 4; ++tc)
; #pragma unroll
;         for (int reg = 0; reg < 4; ++reg) {
;           const int tl = wid * 16 + (lane >> 4) * 4 + reg;
;           const int c = 16 * tc + (lane & 15);
;           const float r = __builtin_amdgcn_rcpf(1.f + __builtin_amdgcn_exp2f(acc[tc][reg] + ba[tc]));
;           const float ii = __builtin_amdgcn_rcpf(1.f + __builtin_amdgcn_exp2f(acc[tc + 4][reg] + bi[tc]));
;           const float la = -c8[tc] * r;
;           const float a = __builtin_amdgcn_exp2f(la);
;           const float ucv = bf2f(sm_uc[(sb * 64 + tl) * LDSS + c]);
;           const float bt = __builtin_amdgcn_sqrtf(fmaxf(1.f - a * a, 0.f)) * (ii * ucv);
;           sm_a[tl * 64 + c] = a;
;           sm_b[tl * 64 + c] = bt;
;         }
	v_mul_f32_e32 v94, v94, v166
	v_mul_f32_e32 v95, v95, v167
	v_mul_f32_e32 v96, v96, v168
	v_mul_f32_e32 v97, v97, v169
	v_exp_f32_e32 v4, v4
	v_exp_f32_e32 v5, v5
	v_exp_f32_e32 v6, v6
	v_exp_f32_e32 v7, v7
	s_nop 0
	v_fma_f32 v138, -v4, v4, 1.0
	v_fma_f32 v139, -v5, v5, 1.0
	v_fma_f32 v140, -v6, v6, 1.0
	v_fma_f32 v141, -v7, v7, 1.0
	v_max_f32_e32 v138, 0, v138
	v_max_f32_e32 v139, 0, v139
	v_max_f32_e32 v140, 0, v140
	v_max_f32_e32 v141, 0, v141
	v_sqrt_f32_e32 v138, v138
	v_sqrt_f32_e32 v139, v139
	v_sqrt_f32_e32 v140, v140
	v_sqrt_f32_e32 v141, v141
	s_nop 0
	v_mul_f32_e32 v94, v138, v94
	v_mul_f32_e32 v95, v139, v95
	v_mul_f32_e32 v96, v140, v96
	v_mul_f32_e32 v97, v141, v97
	v_add_f32_e32 v8, v8, v75
	v_add_f32_e32 v9, v9, v75
	v_add_f32_e32 v10, v10, v75
	v_add_f32_e32 v11, v11, v75
	v_add_f32_e32 v98, v98, v84
	v_add_f32_e32 v99, v99, v84
	v_add_f32_e32 v100, v100, v84
	v_add_f32_e32 v101, v101, v84
	v_exp_f32_e32 v8, v8
	v_exp_f32_e32 v9, v9
	v_exp_f32_e32 v10, v10
	v_exp_f32_e32 v11, v11
	v_exp_f32_e32 v98, v98
	v_exp_f32_e32 v99, v99
	v_exp_f32_e32 v100, v100
	v_exp_f32_e32 v101, v101
	v_add_f32_e32 v8, 1.0, v8
	v_add_f32_e32 v9, 1.0, v9
	v_add_f32_e32 v10, 1.0, v10
	v_add_f32_e32 v11, 1.0, v11
	v_add_f32_e32 v98, 1.0, v98
	v_add_f32_e32 v99, 1.0, v99
	v_add_f32_e32 v100, 1.0, v100
	v_add_f32_e32 v101, 1.0, v101
	v_rcp_f32_e32 v8, v8
	v_rcp_f32_e32 v9, v9
	v_rcp_f32_e32 v10, v10
	v_rcp_f32_e32 v11, v11
	v_rcp_f32_e32 v98, v98
	v_rcp_f32_e32 v99, v99
	v_rcp_f32_e32 v100, v100
	v_rcp_f32_e32 v101, v101
	v_mul_f32_e32 v8, v85, v8
	v_mul_f32_e32 v9, v85, v9
	v_mul_f32_e32 v10, v85, v10
	v_mul_f32_e32 v11, v85, v11
	v_mul_f32_e32 v98, v98, v170
	v_mul_f32_e32 v99, v99, v171
	v_mul_f32_e32 v100, v100, v172
	v_mul_f32_e32 v101, v101, v173
	v_exp_f32_e32 v8, v8
	v_exp_f32_e32 v9, v9
	v_exp_f32_e32 v10, v10
	v_exp_f32_e32 v11, v11
	s_nop 0
	v_fma_f32 v138, -v8, v8, 1.0
	v_fma_f32 v139, -v9, v9, 1.0
	v_fma_f32 v140, -v10, v10, 1.0
	v_fma_f32 v141, -v11, v11, 1.0
	v_max_f32_e32 v138, 0, v138
	v_max_f32_e32 v139, 0, v139
	v_max_f32_e32 v140, 0, v140
	v_max_f32_e32 v141, 0, v141
	v_sqrt_f32_e32 v138, v138
	v_sqrt_f32_e32 v139, v139
	v_sqrt_f32_e32 v140, v140
	v_sqrt_f32_e32 v141, v141
	s_nop 0
	v_mul_f32_e32 v98, v138, v98
	v_mul_f32_e32 v99, v139, v99
	v_mul_f32_e32 v100, v140, v100
	v_mul_f32_e32 v101, v141, v101
	v_add_f32_e32 v12, v12, v75
	v_add_f32_e32 v13, v13, v75
	v_add_f32_e32 v14, v14, v75
	v_add_f32_e32 v15, v15, v75
	v_add_f32_e32 v102, v102, v84
	v_add_f32_e32 v103, v103, v84
	v_add_f32_e32 v104, v104, v84
	v_add_f32_e32 v105, v105, v84
	v_exp_f32_e32 v12, v12
	v_exp_f32_e32 v13, v13
	v_exp_f32_e32 v14, v14
	v_exp_f32_e32 v15, v15
	v_exp_f32_e32 v102, v102
	v_exp_f32_e32 v103, v103
	v_exp_f32_e32 v104, v104
	v_exp_f32_e32 v105, v105
	v_add_f32_e32 v12, 1.0, v12
	v_add_f32_e32 v13, 1.0, v13
	v_add_f32_e32 v14, 1.0, v14
	v_add_f32_e32 v15, 1.0, v15
	v_add_f32_e32 v102, 1.0, v102
	v_add_f32_e32 v103, 1.0, v103
	v_add_f32_e32 v104, 1.0, v104
	v_add_f32_e32 v105, 1.0, v105
	v_rcp_f32_e32 v12, v12
	v_rcp_f32_e32 v13, v13
	v_rcp_f32_e32 v14, v14
	v_rcp_f32_e32 v15, v15
	v_rcp_f32_e32 v102, v102
	v_rcp_f32_e32 v103, v103
	v_rcp_f32_e32 v104, v104
	v_rcp_f32_e32 v105, v105
	v_mul_f32_e32 v12, v85, v12
	v_mul_f32_e32 v13, v85, v13
	v_mul_f32_e32 v14, v85, v14
	v_mul_f32_e32 v15, v85, v15
	v_mul_f32_e32 v102, v102, v174
	v_mul_f32_e32 v103, v103, v175
	v_mul_f32_e32 v104, v104, v176
	v_mul_f32_e32 v105, v105, v177
	v_exp_f32_e32 v12, v12
	v_exp_f32_e32 v13, v13
	v_exp_f32_e32 v14, v14
	v_exp_f32_e32 v15, v15
	s_nop 0
	v_fma_f32 v138, -v12, v12, 1.0
	v_fma_f32 v139, -v13, v13, 1.0
	v_fma_f32 v140, -v14, v14, 1.0
	v_fma_f32 v141, -v15, v15, 1.0
	v_max_f32_e32 v138, 0, v138
	v_max_f32_e32 v139, 0, v139
	v_max_f32_e32 v140, 0, v140
	v_max_f32_e32 v141, 0, v141
	v_sqrt_f32_e32 v138, v138
	v_sqrt_f32_e32 v139, v139
	v_sqrt_f32_e32 v140, v140
	v_sqrt_f32_e32 v141, v141
	s_nop 0
	v_mul_f32_e32 v102, v138, v102
	v_mul_f32_e32 v103, v139, v103
	v_mul_f32_e32 v104, v140, v104
	v_mul_f32_e32 v105, v141, v105
	v_add_f32_e32 v16, v16, v75
	v_add_f32_e32 v17, v17, v75
	v_add_f32_e32 v18, v18, v75
	v_add_f32_e32 v19, v19, v75
	v_add_f32_e32 v106, v106, v84
	v_add_f32_e32 v107, v107, v84
	v_add_f32_e32 v108, v108, v84
	v_add_f32_e32 v109, v109, v84
	v_exp_f32_e32 v16, v16
	v_exp_f32_e32 v17, v17
	v_exp_f32_e32 v18, v18
	v_exp_f32_e32 v19, v19
	v_exp_f32_e32 v106, v106
	v_exp_f32_e32 v107, v107
	v_exp_f32_e32 v108, v108
	v_exp_f32_e32 v109, v109
	v_add_f32_e32 v16, 1.0, v16
	v_add_f32_e32 v17, 1.0, v17
	v_add_f32_e32 v18, 1.0, v18
	v_add_f32_e32 v19, 1.0, v19
	v_add_f32_e32 v106, 1.0, v106
	v_add_f32_e32 v107, 1.0, v107
	v_add_f32_e32 v108, 1.0, v108
	v_add_f32_e32 v109, 1.0, v109
	v_rcp_f32_e32 v16, v16
	v_rcp_f32_e32 v17, v17
	v_rcp_f32_e32 v18, v18
	v_rcp_f32_e32 v19, v19
	v_rcp_f32_e32 v106, v106
	v_rcp_f32_e32 v107, v107
	v_rcp_f32_e32 v108, v108
	v_rcp_f32_e32 v109, v109
	v_mul_f32_e32 v16, v85, v16
	v_mul_f32_e32 v17, v85, v17
	v_mul_f32_e32 v18, v85, v18
	v_mul_f32_e32 v19, v85, v19
	v_mul_f32_e32 v106, v106, v178
	v_mul_f32_e32 v107, v107, v179
	v_mul_f32_e32 v108, v108, v180
	v_mul_f32_e32 v109, v109, v181
	v_exp_f32_e32 v16, v16
	v_exp_f32_e32 v17, v17
	v_exp_f32_e32 v18, v18
	v_exp_f32_e32 v19, v19
	s_nop 0
	v_fma_f32 v138, -v16, v16, 1.0
	v_fma_f32 v139, -v17, v17, 1.0
	v_fma_f32 v140, -v18, v18, 1.0
	v_fma_f32 v141, -v19, v19, 1.0
	v_max_f32_e32 v138, 0, v138
	v_max_f32_e32 v139, 0, v139
	v_max_f32_e32 v140, 0, v140
	v_max_f32_e32 v141, 0, v141
	v_sqrt_f32_e32 v138, v138
	v_sqrt_f32_e32 v139, v139
	v_sqrt_f32_e32 v140, v140
; __device__ __forceinline__ float bf2f(u16 h) { return __uint_as_float(((unsigned)h) << 16); }
; __device__ __forceinline__ void lru_tile(const Params& P, int chunk, int head, int pass, char* smem_raw) {
;     ...
;       for (int tc = 0; tc < 4; ++tc)
; #pragma unroll
;         for (int reg = 0; reg < 4; ++reg) {
;           const int tl = wid * 16 + (lane >> 4) * 4 + reg;
;           const int c = 16 * tc + (lane & 15);
;           const float r = __builtin_amdgcn_rcpf(1.f + __builtin_amdgcn_exp2f(acc[tc][reg] + ba[tc]));
;           const float ii = __builtin_amdgcn_rcpf(1.f + __builtin_amdgcn_exp2f(acc[tc + 4][reg] + bi[tc]));
;           const float la = -c8[tc] * r;
;           const float a = __builtin_amdgcn_exp2f(la);
;           const float ucv = bf2f(sm_uc[(sb * 64 + tl) * LDSS + c]);
;           const float bt = __builtin_amdgcn_sqrtf(fmaxf(1.f - a * a, 0.f)) * (ii * ucv);
;           sm_a[tl * 64 + c] = a;
;           sm_b[tl * 64 + c] = bt;
;         }
;       __syncthreads();
;       const int pos = (d == 0) ? q : 3 - q;
;       {
;         float Pp = 1.f, H = 0.f;
; #pragma unroll 4
;         for (int i = 0; i < 16; ++i) {
;           const int tl = (d == 0) ? (q * 16 + i) : (q * 16 + 15 - i);
;           const float a = sm_a[tl * 64 + ch], b = sm_b[tl * 64 + ch];
;           H = a * H + b; Pp *= a;
;         }
;         sm_ph[pos * 64 + ch] = make_float2(Pp, H);
	v_sqrt_f32_e32 v141, v141
	s_nop 0
	v_mul_f32_e32 v106, v138, v106
	v_mul_f32_e32 v107, v139, v107
	v_mul_f32_e32 v108, v140, v108
	v_mul_f32_e32 v109, v141, v109
	v_add_f32_e32 v20, v20, v75
	v_add_f32_e32 v21, v21, v75
	v_add_f32_e32 v22, v22, v75
	v_add_f32_e32 v23, v23, v75
	v_add_f32_e32 v110, v110, v84
	v_add_f32_e32 v111, v111, v84
	v_add_f32_e32 v112, v112, v84
	v_add_f32_e32 v113, v113, v84
	v_exp_f32_e32 v20, v20
	v_exp_f32_e32 v21, v21
	v_exp_f32_e32 v22, v22
	v_exp_f32_e32 v23, v23
	v_exp_f32_e32 v110, v110
	v_exp_f32_e32 v111, v111
	v_exp_f32_e32 v112, v112
	v_exp_f32_e32 v113, v113
	v_add_f32_e32 v20, 1.0, v20
	v_add_f32_e32 v21, 1.0, v21
	v_add_f32_e32 v22, 1.0, v22
	v_add_f32_e32 v23, 1.0, v23
	v_add_f32_e32 v110, 1.0, v110
	v_add_f32_e32 v111, 1.0, v111
	v_add_f32_e32 v112, 1.0, v112
	v_add_f32_e32 v113, 1.0, v113
	v_rcp_f32_e32 v20, v20
	v_rcp_f32_e32 v21, v21
	v_rcp_f32_e32 v22, v22
	v_rcp_f32_e32 v23, v23
	v_rcp_f32_e32 v110, v110
	v_rcp_f32_e32 v111, v111
	v_rcp_f32_e32 v112, v112
	v_rcp_f32_e32 v113, v113
	v_mul_f32_e32 v20, v85, v20
	v_mul_f32_e32 v21, v85, v21
	v_mul_f32_e32 v22, v85, v22
	v_mul_f32_e32 v23, v85, v23
	v_mul_f32_e32 v110, v110, v182
	v_mul_f32_e32 v111, v111, v183
	v_mul_f32_e32 v112, v112, v184
	v_mul_f32_e32 v113, v113, v185
	v_exp_f32_e32 v20, v20
	v_exp_f32_e32 v21, v21
	v_exp_f32_e32 v22, v22
	v_exp_f32_e32 v23, v23
	s_nop 0
	v_fma_f32 v138, -v20, v20, 1.0
	v_fma_f32 v139, -v21, v21, 1.0
	v_fma_f32 v140, -v22, v22, 1.0
	v_fma_f32 v141, -v23, v23, 1.0
	v_max_f32_e32 v138, 0, v138
	v_max_f32_e32 v139, 0, v139
	v_max_f32_e32 v140, 0, v140
	v_max_f32_e32 v141, 0, v141
	v_sqrt_f32_e32 v138, v138
	v_sqrt_f32_e32 v139, v139
	v_sqrt_f32_e32 v140, v140
	v_sqrt_f32_e32 v141, v141
	s_nop 0
	v_mul_f32_e32 v110, v138, v110
	v_mul_f32_e32 v111, v139, v111
	v_mul_f32_e32 v112, v140, v112
	v_mul_f32_e32 v113, v141, v113
	v_add_f32_e32 v24, v24, v75
	v_add_f32_e32 v25, v25, v75
	v_add_f32_e32 v26, v26, v75
	v_add_f32_e32 v27, v27, v75
	v_add_f32_e32 v114, v114, v84
	v_add_f32_e32 v115, v115, v84
	v_add_f32_e32 v116, v116, v84
	v_add_f32_e32 v117, v117, v84
	v_exp_f32_e32 v24, v24
	v_exp_f32_e32 v25, v25
	v_exp_f32_e32 v26, v26
	v_exp_f32_e32 v27, v27
	v_exp_f32_e32 v114, v114
	v_exp_f32_e32 v115, v115
	v_exp_f32_e32 v116, v116
	v_exp_f32_e32 v117, v117
	v_add_f32_e32 v24, 1.0, v24
	v_add_f32_e32 v25, 1.0, v25
	v_add_f32_e32 v26, 1.0, v26
	v_add_f32_e32 v27, 1.0, v27
	v_add_f32_e32 v114, 1.0, v114
	v_add_f32_e32 v115, 1.0, v115
	v_add_f32_e32 v116, 1.0, v116
	v_add_f32_e32 v117, 1.0, v117
	v_rcp_f32_e32 v24, v24
	v_rcp_f32_e32 v25, v25
	v_rcp_f32_e32 v26, v26
	v_rcp_f32_e32 v27, v27
	v_rcp_f32_e32 v114, v114
	v_rcp_f32_e32 v115, v115
	v_rcp_f32_e32 v116, v116
	v_rcp_f32_e32 v117, v117
	v_mul_f32_e32 v24, v85, v24
	v_mul_f32_e32 v25, v85, v25
	v_mul_f32_e32 v26, v85, v26
	v_mul_f32_e32 v27, v85, v27
	v_mul_f32_e32 v114, v114, v186
	v_mul_f32_e32 v115, v115, v187
	v_mul_f32_e32 v116, v116, v188
	v_mul_f32_e32 v117, v117, v189
	v_exp_f32_e32 v24, v24
	v_exp_f32_e32 v25, v25
	v_exp_f32_e32 v26, v26
	v_exp_f32_e32 v27, v27
	s_nop 0
	v_fma_f32 v138, -v24, v24, 1.0
	v_fma_f32 v139, -v25, v25, 1.0
	v_fma_f32 v140, -v26, v26, 1.0
	v_fma_f32 v141, -v27, v27, 1.0
	v_max_f32_e32 v138, 0, v138
	v_max_f32_e32 v139, 0, v139
	v_max_f32_e32 v140, 0, v140
	v_max_f32_e32 v141, 0, v141
	v_sqrt_f32_e32 v138, v138
	v_sqrt_f32_e32 v139, v139
	v_sqrt_f32_e32 v140, v140
	v_sqrt_f32_e32 v141, v141
	s_nop 0
	v_mul_f32_e32 v114, v138, v114
	v_mul_f32_e32 v115, v139, v115
	v_mul_f32_e32 v116, v140, v116
	v_mul_f32_e32 v117, v141, v117
	v_add_f32_e32 v28, v28, v75
	v_add_f32_e32 v29, v29, v75
	v_add_f32_e32 v30, v30, v75
	v_add_f32_e32 v31, v31, v75
	v_add_f32_e32 v118, v118, v84
	v_add_f32_e32 v119, v119, v84
	v_add_f32_e32 v120, v120, v84
	v_add_f32_e32 v121, v121, v84
	v_exp_f32_e32 v28, v28
	v_exp_f32_e32 v29, v29
	v_exp_f32_e32 v30, v30
	v_exp_f32_e32 v31, v31
	v_exp_f32_e32 v118, v118
	v_exp_f32_e32 v119, v119
	v_exp_f32_e32 v120, v120
	v_exp_f32_e32 v121, v121
	v_add_f32_e32 v28, 1.0, v28
	v_add_f32_e32 v29, 1.0, v29
	v_add_f32_e32 v30, 1.0, v30
	v_add_f32_e32 v31, 1.0, v31
	v_add_f32_e32 v118, 1.0, v118
	v_add_f32_e32 v119, 1.0, v119
	v_add_f32_e32 v120, 1.0, v120
	v_add_f32_e32 v121, 1.0, v121
	v_rcp_f32_e32 v28, v28
	v_rcp_f32_e32 v29, v29
	v_rcp_f32_e32 v30, v30
	v_rcp_f32_e32 v31, v31
	v_rcp_f32_e32 v118, v118
	v_rcp_f32_e32 v119, v119
	v_rcp_f32_e32 v120, v120
	v_rcp_f32_e32 v121, v121
	v_mul_f32_e32 v28, v85, v28
	v_mul_f32_e32 v29, v85, v29
	v_mul_f32_e32 v30, v85, v30
	v_mul_f32_e32 v31, v85, v31
	v_mul_f32_e32 v118, v118, v190
	v_mul_f32_e32 v119, v119, v191
	v_mul_f32_e32 v120, v120, v192
	v_mul_f32_e32 v121, v121, v193
	v_exp_f32_e32 v28, v28
	v_exp_f32_e32 v29, v29
	v_exp_f32_e32 v30, v30
	v_exp_f32_e32 v31, v31
	s_nop 0
	v_fma_f32 v138, -v28, v28, 1.0
	v_fma_f32 v139, -v29, v29, 1.0
	v_fma_f32 v140, -v30, v30, 1.0
	v_fma_f32 v141, -v31, v31, 1.0
	v_max_f32_e32 v138, 0, v138
	v_max_f32_e32 v139, 0, v139
	v_max_f32_e32 v140, 0, v140
	v_max_f32_e32 v141, 0, v141
	v_sqrt_f32_e32 v138, v138
	v_sqrt_f32_e32 v139, v139
	v_sqrt_f32_e32 v140, v140
	v_sqrt_f32_e32 v141, v141
	s_nop 0
	v_mul_f32_e32 v118, v138, v118
	v_mul_f32_e32 v119, v139, v119
	v_mul_f32_e32 v120, v140, v120
	v_mul_f32_e32 v121, v141, v121
	v_mov_b32_e32 v253, v0
	v_mov_b32_e32 v254, v90
	v_fma_f32 v254, v1, v254, v91
	v_mul_f32_e32 v253, v253, v1
	v_fma_f32 v254, v2, v254, v92
	v_mul_f32_e32 v253, v253, v2
	v_fma_f32 v254, v3, v254, v93
	v_mul_f32_e32 v253, v253, v3
	v_fma_f32 v254, v4, v254, v94
	v_mul_f32_e32 v253, v253, v4
	v_fma_f32 v254, v5, v254, v95
; __device__ __forceinline__ float bf2f(u16 h) { return __uint_as_float(((unsigned)h) << 16); }
; __device__ __forceinline__ void lru_tile(const Params& P, int chunk, int head, int pass, char* smem_raw) {
;     ...
;       const float2 p0 = sm_ph[ch], p1 = sm_ph[64 + ch], p2 = sm_ph[128 + ch], p3 = sm_ph[192 + ch];
;       if (pass == 2) {
;         float hin = cB;
;         if (pos > 0) hin = p0.x * hin + p0.y;
;         if (pos > 1) hin = p1.x * hin + p1.y;
;         if (pos > 2) hin = p2.x * hin + p2.y;
;         float h = hin;
;         float hfp[16], gp[16];
;         if (d == 1) {
; #pragma unroll
;           for (int i = 0; i < 16; ++i) {
;             const long rowp = row0 + sb * 64 + q * 16 + 15 - i;
;             hfp[i] = hfbuf[rowp * 512 + gch];
;             gp[i] = bf2f(P.zq[rowp * 1536 + 512 + gch]);
;           }
;         }
; #pragma unroll
;         for (int i = 0; i < 16; ++i) {
;           const int tl = (d == 0) ? (q * 16 + i) : (q * 16 + 15 - i);
;           const float a = sm_a[tl * 64 + ch], b = sm_b[tl * 64 + ch];
;           h = a * h + b;
;           const long row = row0 + sb * 64 + tl;
;           if (d == 0) {
;             hfw[row * 512 + gch] = h;
	v_mul_f32_e32 v253, v253, v5
	v_fma_f32 v254, v6, v254, v96
	v_mul_f32_e32 v253, v253, v6
	v_fma_f32 v254, v7, v254, v97
	v_mul_f32_e32 v253, v253, v7
	v_fma_f32 v254, v8, v254, v98
	v_mul_f32_e32 v253, v253, v8
	v_fma_f32 v254, v9, v254, v99
	v_mul_f32_e32 v253, v253, v9
	v_fma_f32 v254, v10, v254, v100
	v_mul_f32_e32 v253, v253, v10
	v_fma_f32 v254, v11, v254, v101
	v_mul_f32_e32 v253, v253, v11
	v_fma_f32 v254, v12, v254, v102
	v_mul_f32_e32 v253, v253, v12
	v_fma_f32 v254, v13, v254, v103
	v_mul_f32_e32 v253, v253, v13
	v_fma_f32 v254, v14, v254, v104
	v_mul_f32_e32 v253, v253, v14
	v_fma_f32 v254, v15, v254, v105
	v_mul_f32_e32 v253, v253, v15
	v_fma_f32 v254, v16, v254, v106
	v_mul_f32_e32 v253, v253, v16
	v_fma_f32 v254, v17, v254, v107
	v_mul_f32_e32 v253, v253, v17
	v_fma_f32 v254, v18, v254, v108
	v_mul_f32_e32 v253, v253, v18
	v_fma_f32 v254, v19, v254, v109
	v_mul_f32_e32 v253, v253, v19
	v_fma_f32 v254, v20, v254, v110
	v_mul_f32_e32 v253, v253, v20
	v_fma_f32 v254, v21, v254, v111
	v_mul_f32_e32 v253, v253, v21
	v_fma_f32 v254, v22, v254, v112
	v_mul_f32_e32 v253, v253, v22
	v_fma_f32 v254, v23, v254, v113
	v_mul_f32_e32 v253, v253, v23
	v_fma_f32 v254, v24, v254, v114
	v_mul_f32_e32 v253, v253, v24
	v_fma_f32 v254, v25, v254, v115
	v_mul_f32_e32 v253, v253, v25
	v_fma_f32 v254, v26, v254, v116
	v_mul_f32_e32 v253, v253, v26
	v_fma_f32 v254, v27, v254, v117
	v_mul_f32_e32 v253, v253, v27
	v_fma_f32 v254, v28, v254, v118
	v_mul_f32_e32 v253, v253, v28
	v_fma_f32 v254, v29, v254, v119
	v_mul_f32_e32 v253, v253, v29
	v_fma_f32 v254, v30, v254, v120
	v_mul_f32_e32 v253, v253, v30
	v_fma_f32 v254, v31, v254, v121
	v_mul_f32_e32 v253, v253, v31
	v_mov_b32_e32 v138, v253
	v_mov_b32_e32 v139, v253
	s_nop 1
	v_permlane16_swap_b32_e32 v138, v139
	v_mov_b32_e32 v140, v138
	v_mov_b32_e32 v141, v139
	s_nop 1
	v_permlane32_swap_b32_e32 v138, v140
	v_permlane32_swap_b32_e32 v139, v141
	v_mov_b32_e32 v198, v254
	v_mov_b32_e32 v199, v254
	s_nop 1
	v_permlane16_swap_b32_e32 v198, v199
	v_mov_b32_e32 v200, v198
	v_mov_b32_e32 v201, v199
	s_nop 1
	v_permlane32_swap_b32_e32 v198, v200
	v_permlane32_swap_b32_e32 v199, v201
	v_mov_b32_e32 v136, v65
	v_fma_f32 v150, v138, v136, v198
	v_fma_f32 v151, v139, v150, v199
	v_fma_f32 v202, v140, v151, v200
	v_mov_b32_e32 v254, v136
	v_cndmask_b32_e64 v254, v254, v150, s[72:73]
	v_cndmask_b32_e64 v254, v254, v151, s[74:75]
	v_cndmask_b32_e64 v254, v254, v202, s[76:77]
	v_fma_f32 v205, v0, v254, v90
	v_fma_f32 v206, v1, v205, v91
	v_fma_f32 v207, v2, v206, v92
	v_fma_f32 v208, v3, v207, v93
	v_fma_f32 v209, v4, v208, v94
	v_fma_f32 v210, v5, v209, v95
	v_fma_f32 v211, v6, v210, v96
	v_fma_f32 v212, v7, v211, v97
	v_fma_f32 v213, v8, v212, v98
	v_fma_f32 v214, v9, v213, v99
	v_fma_f32 v215, v10, v214, v100
	v_fma_f32 v216, v11, v215, v101
	v_fma_f32 v217, v12, v216, v102
	v_fma_f32 v218, v13, v217, v103
	v_fma_f32 v219, v14, v218, v104
	v_fma_f32 v220, v15, v219, v105
	v_fma_f32 v221, v16, v220, v106
	v_fma_f32 v222, v17, v221, v107
	v_fma_f32 v223, v18, v222, v108
	v_fma_f32 v224, v19, v223, v109
	v_fma_f32 v225, v20, v224, v110
	v_fma_f32 v226, v21, v225, v111
	v_fma_f32 v227, v22, v226, v112
	v_fma_f32 v228, v23, v227, v113
	v_fma_f32 v229, v24, v228, v114
	v_fma_f32 v230, v25, v229, v115
	v_fma_f32 v231, v26, v230, v116
	v_fma_f32 v232, v27, v231, v117
	v_fma_f32 v233, v28, v232, v118
	v_fma_f32 v234, v29, v233, v119
	v_fma_f32 v235, v30, v234, v120
	v_fma_f32 v236, v31, v235, v121
	s_lshl_b32 s0, s56, 8
	s_add_u32 s0, s0, 0x20000
	s_add_u32 s4, s20, s0
	s_addc_u32 s5, s21, 0
	global_load_dwordx4 v[238:241], v251, s[4:5]
	global_load_dwordx4 v[242:245], v251, s[4:5] offset:64
	s_add_u32 s4, s4, 0x2000
	s_addc_u32 s5, s5, 0
	global_load_dwordx4 v[246:249], v251, s[4:5]
	global_load_dwordx4 v[194:197], v251, s[4:5] offset:64
	v_bfe_u32 v255, v152, 6, 2
	v_and_b32_e32 v253, 15, v152
	v_lshl_add_u32 v255, v255, 4, v253
	v_add_u32_e32 v255, s56, v255
	v_lshlrev_b32_e32 v255, 2, v255
	s_add_u32 s0, s28, 0x800
	s_addc_u32 s1, s29, 0
	global_load_dword v75, v255, s[0:1]
	s_add_u32 s0, s30, 0x800
	s_addc_u32 s1, s31, 0
	global_load_dword v84, v255, s[0:1]
	s_add_u32 s0, s36, 0x800
	s_addc_u32 s1, s37, 0
	global_load_dword v85, v255, s[0:1]
	ds_read_b128 v[76:79], v131 offset:0
	ds_read_b128 v[80:83], v133 offset:0
	ds_read_b128 v[122:125], v131 offset:512
	ds_read_b128 v[126:129], v133 offset:512
	s_waitcnt vmcnt(3)
	s_waitcnt lgkmcnt(3)
	v_mfma_f32_16x16x32_bf16 v[0:3], v[76:79], v[238:241], 0
	v_mfma_f32_16x16x32_bf16 v[90:93], v[76:79], v[246:249], 0
	ds_read_b128 v[76:79], v131 offset:1024
	s_waitcnt lgkmcnt(3)
	v_mfma_f32_16x16x32_bf16 v[0:3], v[80:83], v[242:245], v[0:3]
	v_mfma_f32_16x16x32_bf16 v[90:93], v[80:83], v[194:197], v[90:93]
	ds_read_b128 v[80:83], v133 offset:1024
	s_waitcnt lgkmcnt(3)
	v_mfma_f32_16x16x32_bf16 v[4:7], v[122:125], v[238:241], 0
	v_mfma_f32_16x16x32_bf16 v[94:97], v[122:125], v[246:249], 0
	ds_read_b128 v[122:125], v131 offset:1536
	s_waitcnt lgkmcnt(3)
	v_mfma_f32_16x16x32_bf16 v[4:7], v[126:129], v[242:245], v[4:7]
	v_mfma_f32_16x16x32_bf16 v[94:97], v[126:129], v[194:197], v[94:97]
	ds_read_b128 v[126:129], v133 offset:1536
	s_waitcnt lgkmcnt(3)
	v_mfma_f32_16x16x32_bf16 v[8:11], v[76:79], v[238:241], 0
	v_mfma_f32_16x16x32_bf16 v[98:101], v[76:79], v[246:249], 0
	ds_read_b128 v[76:79], v131 offset:2048
	s_waitcnt lgkmcnt(3)
	v_mfma_f32_16x16x32_bf16 v[8:11], v[80:83], v[242:245], v[8:11]
	v_mfma_f32_16x16x32_bf16 v[98:101], v[80:83], v[194:197], v[98:101]
	ds_read_b128 v[80:83], v133 offset:2048
	s_waitcnt lgkmcnt(3)
; __device__ __forceinline__ float bf2f(u16 h) { return __uint_as_float(((unsigned)h) << 16); }
; __device__ __forceinline__ void lru_tile(const Params& P, int chunk, int head, int pass, char* smem_raw) {
;     ...
; #pragma unroll
;     for (int tc = 0; tc < 4; ++tc) {
;       const int cidx = d * 512 + head * 64 + 16 * tc + (lane & 15);
;       ba[tc] = P.b_a[cidx] * -1.4426950408889634f; bi[tc] = P.b_i[cidx] * -1.4426950408889634f;
;       const float nl = -P.lam[cidx];
;       const float e_ = __expf(nl);
;       const float sp = (nl > 20.f) ? nl
;                      : (e_ < 0.03f ? e_ * (1.f - e_ * (0.5f - e_ * (0.33333334f - 0.25f * e_))) : __logf(1.f + e_));
;       c8[tc] = 8.f * 1.4426950408889634f * sp;
;     }
;     __syncthreads();
;     float cA = 1.f, cB = (pass == 2) ? sm_init[d * 64 + ch] : 0.f;
;     for (int sbi = 0; sbi < 2; ++sbi) {
;       const int sb = (d == 0) ? sbi : 1 - sbi;
;       f32x4 acc[8];
; #pragma unroll
;       for (int t = 0; t < 8; ++t) acc[t] = f32x4{0.f, 0.f, 0.f, 0.f};
; #pragma unroll
;       for (int s = 0; s < 2; ++s) {
;         const bf16x8 af = *reinterpret_cast<const bf16x8*>(&sm_uc[(sb * 64 + wid * 16 + (lane & 15)) * LDSS + s * 32 + (lane >> 4) * 8]);
; #pragma unroll
;         for (int t = 0; t < 8; ++t) {
;           const bf16x8 bfr = *reinterpret_cast<const bf16x8*>(&sm_w[(t * 16 + (lane & 15)) * LDSS + s * 32 + (lane >> 4) * 8]);
;           acc[t] = __builtin_amdgcn_mfma_f32_16x16x32_bf16(af, bfr, acc[t], 0, 0, 0);
;         }
;       }
; #pragma unroll
;       for (int tc = 0; tc < 4; ++tc)
; #pragma unroll
;         for (int reg = 0; reg < 4; ++reg) {
;           const int tl = wid * 16 + (lane >> 4) * 4 + reg;
;           const int c = 16 * tc + (lane & 15);
;           const float r = __builtin_amdgcn_rcpf(1.f + __builtin_amdgcn_exp2f(acc[tc][reg] + ba[tc]));
;           const float ii = __builtin_amdgcn_rcpf(1.f + __builtin_amdgcn_exp2f(acc[tc + 4][reg] + bi[tc]));
;           const float la = -c8[tc] * r;
;           const float a = __builtin_amdgcn_exp2f(la);
;           const float ucv = bf2f(sm_uc[(sb * 64 + tl) * LDSS + c]);
;           const float bt = __builtin_amdgcn_sqrtf(fmaxf(1.f - a * a, 0.f)) * (ii * ucv);
;           sm_a[tl * 64 + c] = a;
;           sm_b[tl * 64 + c] = bt;
;         }
	v_mfma_f32_16x16x32_bf16 v[12:15], v[122:125], v[238:241], 0
	v_mfma_f32_16x16x32_bf16 v[102:105], v[122:125], v[246:249], 0
	ds_read_b128 v[122:125], v131 offset:2560
	s_waitcnt lgkmcnt(3)
	v_mfma_f32_16x16x32_bf16 v[12:15], v[126:129], v[242:245], v[12:15]
	v_mfma_f32_16x16x32_bf16 v[102:105], v[126:129], v[194:197], v[102:105]
	ds_read_b128 v[126:129], v133 offset:2560
	s_waitcnt lgkmcnt(3)
	v_mfma_f32_16x16x32_bf16 v[16:19], v[76:79], v[238:241], 0
	v_mfma_f32_16x16x32_bf16 v[106:109], v[76:79], v[246:249], 0
	ds_read_b128 v[76:79], v131 offset:3072
	s_waitcnt lgkmcnt(3)
	v_mfma_f32_16x16x32_bf16 v[16:19], v[80:83], v[242:245], v[16:19]
	v_mfma_f32_16x16x32_bf16 v[106:109], v[80:83], v[194:197], v[106:109]
	ds_read_b128 v[80:83], v133 offset:3072
	s_waitcnt lgkmcnt(3)
	v_mfma_f32_16x16x32_bf16 v[20:23], v[122:125], v[238:241], 0
	v_mfma_f32_16x16x32_bf16 v[110:113], v[122:125], v[246:249], 0
	ds_read_b128 v[122:125], v131 offset:3584
	s_waitcnt lgkmcnt(3)
	v_mfma_f32_16x16x32_bf16 v[20:23], v[126:129], v[242:245], v[20:23]
	v_mfma_f32_16x16x32_bf16 v[110:113], v[126:129], v[194:197], v[110:113]
	ds_read_b128 v[126:129], v133 offset:3584
	s_waitcnt lgkmcnt(3)
	v_mfma_f32_16x16x32_bf16 v[24:27], v[76:79], v[238:241], 0
	v_mfma_f32_16x16x32_bf16 v[114:117], v[76:79], v[246:249], 0
	s_waitcnt lgkmcnt(2)
	v_mfma_f32_16x16x32_bf16 v[24:27], v[80:83], v[242:245], v[24:27]
	v_mfma_f32_16x16x32_bf16 v[114:117], v[80:83], v[194:197], v[114:117]
	s_waitcnt lgkmcnt(1)
	v_mfma_f32_16x16x32_bf16 v[28:31], v[122:125], v[238:241], 0
	v_mfma_f32_16x16x32_bf16 v[118:121], v[122:125], v[246:249], 0
	s_waitcnt lgkmcnt(0)
	v_mfma_f32_16x16x32_bf16 v[28:31], v[126:129], v[242:245], v[28:31]
	v_mfma_f32_16x16x32_bf16 v[118:121], v[126:129], v[194:197], v[118:121]
	s_waitcnt vmcnt(0)
	v_mul_f32_e32 v75, 0xbfb8aa3b, v75
	v_mul_f32_e32 v84, 0xbfb8aa3b, v84
	v_sub_f32_e32 v138, 0, v85
	v_mul_f32_e32 v139, 0x3fb8aa3b, v138
	v_exp_f32_e32 v139, v139
	v_mul_f32_e32 v140, 0xbe800000, v139
	v_add_f32_e32 v140, 0x3eaaaaab, v140
	v_fma_f32 v140, -v139, v140, 0.5
	v_fma_f32 v140, -v139, v140, 1.0
	v_mul_f32_e32 v140, v139, v140
	v_add_f32_e32 v141, 1.0, v139
	v_log_f32_e32 v141, v141
	v_mov_b32_e32 v255, 0x3cf5c28f
	v_mul_f32_e32 v141, 0x3f317218, v141
	v_cmp_gt_f32_e32 vcc, v255, v139
	s_nop 1
	v_cndmask_b32_e32 v140, v141, v140, vcc
	v_mov_b32_e32 v255, 0x41a00000
	v_cmp_lt_f32_e32 vcc, v255, v138
	s_nop 1
	v_cndmask_b32_e32 v140, v140, v138, vcc
	v_mul_f32_e32 v85, 0xc138aa3b, v140
	s_nop 7
	v_add_f32_e32 v0, v0, v75
	v_add_f32_e32 v1, v1, v75
	v_add_f32_e32 v2, v2, v75
	v_add_f32_e32 v3, v3, v75
	v_add_f32_e32 v90, v90, v84
	v_add_f32_e32 v91, v91, v84
	v_add_f32_e32 v92, v92, v84
	v_add_f32_e32 v93, v93, v84
	v_exp_f32_e32 v0, v0
	v_exp_f32_e32 v1, v1
	v_exp_f32_e32 v2, v2
	v_exp_f32_e32 v3, v3
	v_exp_f32_e32 v90, v90
	v_exp_f32_e32 v91, v91
	v_exp_f32_e32 v92, v92
	v_exp_f32_e32 v93, v93
	v_add_f32_e32 v0, 1.0, v0
	v_add_f32_e32 v1, 1.0, v1
	v_add_f32_e32 v2, 1.0, v2
	v_add_f32_e32 v3, 1.0, v3
	v_add_f32_e32 v90, 1.0, v90
	v_add_f32_e32 v91, 1.0, v91
	v_add_f32_e32 v92, 1.0, v92
	v_add_f32_e32 v93, 1.0, v93
	v_rcp_f32_e32 v0, v0
	v_rcp_f32_e32 v1, v1
	v_rcp_f32_e32 v2, v2
	v_rcp_f32_e32 v3, v3
	v_rcp_f32_e32 v90, v90
	v_rcp_f32_e32 v91, v91
	v_rcp_f32_e32 v92, v92
	v_rcp_f32_e32 v93, v93
	v_mul_f32_e32 v0, v85, v0
	v_mul_f32_e32 v1, v85, v1
	v_mul_f32_e32 v2, v85, v2
	v_mul_f32_e32 v3, v85, v3
	v_mul_f32_e32 v90, v90, v162
	v_mul_f32_e32 v91, v91, v163
	v_mul_f32_e32 v92, v92, v164
	v_mul_f32_e32 v93, v93, v165
	v_exp_f32_e32 v0, v0
	v_exp_f32_e32 v1, v1
	v_exp_f32_e32 v2, v2
	v_exp_f32_e32 v3, v3
	s_nop 0
	v_fma_f32 v138, -v0, v0, 1.0
	v_fma_f32 v139, -v1, v1, 1.0
	v_fma_f32 v140, -v2, v2, 1.0
	v_fma_f32 v141, -v3, v3, 1.0
	v_max_f32_e32 v138, 0, v138
	v_max_f32_e32 v139, 0, v139
	v_max_f32_e32 v140, 0, v140
	v_max_f32_e32 v141, 0, v141
	v_sqrt_f32_e32 v138, v138
	v_sqrt_f32_e32 v139, v139
	v_sqrt_f32_e32 v140, v140
	v_sqrt_f32_e32 v141, v141
	s_nop 0
	v_mul_f32_e32 v90, v138, v90
	v_mul_f32_e32 v91, v139, v91
	v_mul_f32_e32 v92, v140, v92
	v_mul_f32_e32 v93, v141, v93
	v_add_f32_e32 v4, v4, v75
	v_add_f32_e32 v5, v5, v75
	v_add_f32_e32 v6, v6, v75
	v_add_f32_e32 v7, v7, v75
	v_add_f32_e32 v94, v94, v84
	v_add_f32_e32 v95, v95, v84
	v_add_f32_e32 v96, v96, v84
	v_add_f32_e32 v97, v97, v84
	v_exp_f32_e32 v4, v4
	v_exp_f32_e32 v5, v5
	v_exp_f32_e32 v6, v6
	v_exp_f32_e32 v7, v7
	v_exp_f32_e32 v94, v94
	v_exp_f32_e32 v95, v95
	v_exp_f32_e32 v96, v96
	v_exp_f32_e32 v97, v97
	v_add_f32_e32 v4, 1.0, v4
	v_add_f32_e32 v5, 1.0, v5
	v_add_f32_e32 v6, 1.0, v6
	v_add_f32_e32 v7, 1.0, v7
	v_add_f32_e32 v94, 1.0, v94
	v_add_f32_e32 v95, 1.0, v95
	v_add_f32_e32 v96, 1.0, v96
	v_add_f32_e32 v97, 1.0, v97
	v_rcp_f32_e32 v4, v4
	v_rcp_f32_e32 v5, v5
	v_rcp_f32_e32 v6, v6
	v_rcp_f32_e32 v7, v7
	v_rcp_f32_e32 v94, v94
	v_rcp_f32_e32 v95, v95
	v_rcp_f32_e32 v96, v96
	v_rcp_f32_e32 v97, v97
	v_mul_f32_e32 v4, v85, v4
	v_mul_f32_e32 v5, v85, v5
	v_mul_f32_e32 v6, v85, v6
	v_mul_f32_e32 v7, v85, v7
	v_mul_f32_e32 v94, v94, v166
	v_mul_f32_e32 v95, v95, v167
	v_mul_f32_e32 v96, v96, v168
	v_mul_f32_e32 v97, v97, v169
	v_exp_f32_e32 v4, v4
	v_exp_f32_e32 v5, v5
	v_exp_f32_e32 v6, v6
	v_exp_f32_e32 v7, v7
	s_nop 0
	v_fma_f32 v138, -v4, v4, 1.0
	v_fma_f32 v139, -v5, v5, 1.0
	v_fma_f32 v140, -v6, v6, 1.0
	v_fma_f32 v141, -v7, v7, 1.0
	v_max_f32_e32 v138, 0, v138
	v_max_f32_e32 v139, 0, v139
	v_max_f32_e32 v140, 0, v140
	v_max_f32_e32 v141, 0, v141
	v_sqrt_f32_e32 v138, v138
	v_sqrt_f32_e32 v139, v139
	v_sqrt_f32_e32 v140, v140
	v_sqrt_f32_e32 v141, v141
	s_nop 0
	v_mul_f32_e32 v94, v138, v94
; __device__ __forceinline__ float bf2f(u16 h) { return __uint_as_float(((unsigned)h) << 16); }
; __device__ __forceinline__ void lru_tile(const Params& P, int chunk, int head, int pass, char* smem_raw) {
;     ...
;       for (int tc = 0; tc < 4; ++tc)
; #pragma unroll
;         for (int reg = 0; reg < 4; ++reg) {
;           const int tl = wid * 16 + (lane >> 4) * 4 + reg;
;           const int c = 16 * tc + (lane & 15);
;           const float r = __builtin_amdgcn_rcpf(1.f + __builtin_amdgcn_exp2f(acc[tc][reg] + ba[tc]));
;           const float ii = __builtin_amdgcn_rcpf(1.f + __builtin_amdgcn_exp2f(acc[tc + 4][reg] + bi[tc]));
;           const float la = -c8[tc] * r;
;           const float a = __builtin_amdgcn_exp2f(la);
;           const float ucv = bf2f(sm_uc[(sb * 64 + tl) * LDSS + c]);
;           const float bt = __builtin_amdgcn_sqrtf(fmaxf(1.f - a * a, 0.f)) * (ii * ucv);
;           sm_a[tl * 64 + c] = a;
;           sm_b[tl * 64 + c] = bt;
;         }
	v_mul_f32_e32 v95, v139, v95
	v_mul_f32_e32 v96, v140, v96
	v_mul_f32_e32 v97, v141, v97
	v_add_f32_e32 v8, v8, v75
	v_add_f32_e32 v9, v9, v75
	v_add_f32_e32 v10, v10, v75
	v_add_f32_e32 v11, v11, v75
	v_add_f32_e32 v98, v98, v84
	v_add_f32_e32 v99, v99, v84
	v_add_f32_e32 v100, v100, v84
	v_add_f32_e32 v101, v101, v84
	v_exp_f32_e32 v8, v8
	v_exp_f32_e32 v9, v9
	v_exp_f32_e32 v10, v10
	v_exp_f32_e32 v11, v11
	v_exp_f32_e32 v98, v98
	v_exp_f32_e32 v99, v99
	v_exp_f32_e32 v100, v100
	v_exp_f32_e32 v101, v101
	v_add_f32_e32 v8, 1.0, v8
	v_add_f32_e32 v9, 1.0, v9
	v_add_f32_e32 v10, 1.0, v10
	v_add_f32_e32 v11, 1.0, v11
	v_add_f32_e32 v98, 1.0, v98
	v_add_f32_e32 v99, 1.0, v99
	v_add_f32_e32 v100, 1.0, v100
	v_add_f32_e32 v101, 1.0, v101
	v_rcp_f32_e32 v8, v8
	v_rcp_f32_e32 v9, v9
	v_rcp_f32_e32 v10, v10
	v_rcp_f32_e32 v11, v11
	v_rcp_f32_e32 v98, v98
	v_rcp_f32_e32 v99, v99
	v_rcp_f32_e32 v100, v100
	v_rcp_f32_e32 v101, v101
	v_mul_f32_e32 v8, v85, v8
	v_mul_f32_e32 v9, v85, v9
	v_mul_f32_e32 v10, v85, v10
	v_mul_f32_e32 v11, v85, v11
	v_mul_f32_e32 v98, v98, v170
	v_mul_f32_e32 v99, v99, v171
	v_mul_f32_e32 v100, v100, v172
	v_mul_f32_e32 v101, v101, v173
	v_exp_f32_e32 v8, v8
	v_exp_f32_e32 v9, v9
	v_exp_f32_e32 v10, v10
	v_exp_f32_e32 v11, v11
	s_nop 0
	v_fma_f32 v138, -v8, v8, 1.0
	v_fma_f32 v139, -v9, v9, 1.0
	v_fma_f32 v140, -v10, v10, 1.0
	v_fma_f32 v141, -v11, v11, 1.0
	v_max_f32_e32 v138, 0, v138
	v_max_f32_e32 v139, 0, v139
	v_max_f32_e32 v140, 0, v140
	v_max_f32_e32 v141, 0, v141
	v_sqrt_f32_e32 v138, v138
	v_sqrt_f32_e32 v139, v139
	v_sqrt_f32_e32 v140, v140
	v_sqrt_f32_e32 v141, v141
	s_nop 0
	v_mul_f32_e32 v98, v138, v98
	v_mul_f32_e32 v99, v139, v99
	v_mul_f32_e32 v100, v140, v100
	v_mul_f32_e32 v101, v141, v101
	v_add_f32_e32 v12, v12, v75
	v_add_f32_e32 v13, v13, v75
	v_add_f32_e32 v14, v14, v75
	v_add_f32_e32 v15, v15, v75
	v_add_f32_e32 v102, v102, v84
	v_add_f32_e32 v103, v103, v84
	v_add_f32_e32 v104, v104, v84
	v_add_f32_e32 v105, v105, v84
	v_exp_f32_e32 v12, v12
	v_exp_f32_e32 v13, v13
	v_exp_f32_e32 v14, v14
	v_exp_f32_e32 v15, v15
	v_exp_f32_e32 v102, v102
	v_exp_f32_e32 v103, v103
	v_exp_f32_e32 v104, v104
	v_exp_f32_e32 v105, v105
	v_add_f32_e32 v12, 1.0, v12
	v_add_f32_e32 v13, 1.0, v13
	v_add_f32_e32 v14, 1.0, v14
	v_add_f32_e32 v15, 1.0, v15
	v_add_f32_e32 v102, 1.0, v102
	v_add_f32_e32 v103, 1.0, v103
	v_add_f32_e32 v104, 1.0, v104
	v_add_f32_e32 v105, 1.0, v105
	v_rcp_f32_e32 v12, v12
	v_rcp_f32_e32 v13, v13
	v_rcp_f32_e32 v14, v14
	v_rcp_f32_e32 v15, v15
	v_rcp_f32_e32 v102, v102
	v_rcp_f32_e32 v103, v103
	v_rcp_f32_e32 v104, v104
	v_rcp_f32_e32 v105, v105
	v_mul_f32_e32 v12, v85, v12
	v_mul_f32_e32 v13, v85, v13
	v_mul_f32_e32 v14, v85, v14
	v_mul_f32_e32 v15, v85, v15
	v_mul_f32_e32 v102, v102, v174
	v_mul_f32_e32 v103, v103, v175
	v_mul_f32_e32 v104, v104, v176
	v_mul_f32_e32 v105, v105, v177
	v_exp_f32_e32 v12, v12
	v_exp_f32_e32 v13, v13
	v_exp_f32_e32 v14, v14
	v_exp_f32_e32 v15, v15
	s_nop 0
	v_fma_f32 v138, -v12, v12, 1.0
	v_fma_f32 v139, -v13, v13, 1.0
	v_fma_f32 v140, -v14, v14, 1.0
	v_fma_f32 v141, -v15, v15, 1.0
	v_max_f32_e32 v138, 0, v138
	v_max_f32_e32 v139, 0, v139
	v_max_f32_e32 v140, 0, v140
	v_max_f32_e32 v141, 0, v141
	v_sqrt_f32_e32 v138, v138
	v_sqrt_f32_e32 v139, v139
	v_sqrt_f32_e32 v140, v140
	v_sqrt_f32_e32 v141, v141
	s_nop 0
	v_mul_f32_e32 v102, v138, v102
	v_mul_f32_e32 v103, v139, v103
	v_mul_f32_e32 v104, v140, v104
	v_mul_f32_e32 v105, v141, v105
	v_add_f32_e32 v16, v16, v75
	v_add_f32_e32 v17, v17, v75
	v_add_f32_e32 v18, v18, v75
	v_add_f32_e32 v19, v19, v75
	v_add_f32_e32 v106, v106, v84
	v_add_f32_e32 v107, v107, v84
	v_add_f32_e32 v108, v108, v84
	v_add_f32_e32 v109, v109, v84
	v_exp_f32_e32 v16, v16
	v_exp_f32_e32 v17, v17
	v_exp_f32_e32 v18, v18
	v_exp_f32_e32 v19, v19
	v_exp_f32_e32 v106, v106
	v_exp_f32_e32 v107, v107
	v_exp_f32_e32 v108, v108
	v_exp_f32_e32 v109, v109
	v_add_f32_e32 v16, 1.0, v16
	v_add_f32_e32 v17, 1.0, v17
	v_add_f32_e32 v18, 1.0, v18
	v_add_f32_e32 v19, 1.0, v19
	v_add_f32_e32 v106, 1.0, v106
	v_add_f32_e32 v107, 1.0, v107
	v_add_f32_e32 v108, 1.0, v108
	v_add_f32_e32 v109, 1.0, v109
	v_rcp_f32_e32 v16, v16
	v_rcp_f32_e32 v17, v17
	v_rcp_f32_e32 v18, v18
	v_rcp_f32_e32 v19, v19
	v_rcp_f32_e32 v106, v106
	v_rcp_f32_e32 v107, v107
	v_rcp_f32_e32 v108, v108
	v_rcp_f32_e32 v109, v109
	v_mul_f32_e32 v16, v85, v16
	v_mul_f32_e32 v17, v85, v17
	v_mul_f32_e32 v18, v85, v18
	v_mul_f32_e32 v19, v85, v19
	v_mul_f32_e32 v106, v106, v178
	v_mul_f32_e32 v107, v107, v179
	v_mul_f32_e32 v108, v108, v180
	v_mul_f32_e32 v109, v109, v181
	v_exp_f32_e32 v16, v16
	v_exp_f32_e32 v17, v17
	v_exp_f32_e32 v18, v18
	v_exp_f32_e32 v19, v19
	s_nop 0
	v_fma_f32 v138, -v16, v16, 1.0
	v_fma_f32 v139, -v17, v17, 1.0
	v_fma_f32 v140, -v18, v18, 1.0
	v_fma_f32 v141, -v19, v19, 1.0
	v_max_f32_e32 v138, 0, v138
	v_max_f32_e32 v139, 0, v139
	v_max_f32_e32 v140, 0, v140
	v_max_f32_e32 v141, 0, v141
	v_sqrt_f32_e32 v138, v138
	v_sqrt_f32_e32 v139, v139
	v_sqrt_f32_e32 v140, v140
	v_sqrt_f32_e32 v141, v141
	s_nop 0
	v_mul_f32_e32 v106, v138, v106
	v_mul_f32_e32 v107, v139, v107
	v_mul_f32_e32 v108, v140, v108
	v_mul_f32_e32 v109, v141, v109
	v_add_f32_e32 v20, v20, v75
	v_add_f32_e32 v21, v21, v75
	v_add_f32_e32 v22, v22, v75
	v_add_f32_e32 v23, v23, v75
	v_add_f32_e32 v110, v110, v84
	v_add_f32_e32 v111, v111, v84
	v_add_f32_e32 v112, v112, v84
	v_add_f32_e32 v113, v113, v84
	v_exp_f32_e32 v20, v20
	v_exp_f32_e32 v21, v21
	v_exp_f32_e32 v22, v22
	v_exp_f32_e32 v23, v23
	v_exp_f32_e32 v110, v110
	v_exp_f32_e32 v111, v111
	v_exp_f32_e32 v112, v112
	v_exp_f32_e32 v113, v113
; __device__ __forceinline__ float bf2f(u16 h) { return __uint_as_float(((unsigned)h) << 16); }
; __device__ __forceinline__ void lru_tile(const Params& P, int chunk, int head, int pass, char* smem_raw) {
;     ...
;       for (int tc = 0; tc < 4; ++tc)
; #pragma unroll
;         for (int reg = 0; reg < 4; ++reg) {
;           const int tl = wid * 16 + (lane >> 4) * 4 + reg;
;           const int c = 16 * tc + (lane & 15);
;           const float r = __builtin_amdgcn_rcpf(1.f + __builtin_amdgcn_exp2f(acc[tc][reg] + ba[tc]));
;           const float ii = __builtin_amdgcn_rcpf(1.f + __builtin_amdgcn_exp2f(acc[tc + 4][reg] + bi[tc]));
;           const float la = -c8[tc] * r;
;           const float a = __builtin_amdgcn_exp2f(la);
;           const float ucv = bf2f(sm_uc[(sb * 64 + tl) * LDSS + c]);
;           const float bt = __builtin_amdgcn_sqrtf(fmaxf(1.f - a * a, 0.f)) * (ii * ucv);
;           sm_a[tl * 64 + c] = a;
;           sm_b[tl * 64 + c] = bt;
;         }
;     ...
;         if (d == 1) {
; #pragma unroll
;           for (int i = 0; i < 16; ++i) {
;             const long rowp = row0 + sb * 64 + q * 16 + 15 - i;
;             hfp[i] = hfbuf[rowp * 512 + gch];
;             gp[i] = bf2f(P.zq[rowp * 1536 + 512 + gch]);
;           }
;         }
	v_add_f32_e32 v20, 1.0, v20
	v_add_f32_e32 v21, 1.0, v21
	v_add_f32_e32 v22, 1.0, v22
	v_add_f32_e32 v23, 1.0, v23
	v_add_f32_e32 v110, 1.0, v110
	v_add_f32_e32 v111, 1.0, v111
	v_add_f32_e32 v112, 1.0, v112
	v_add_f32_e32 v113, 1.0, v113
	v_rcp_f32_e32 v20, v20
	v_rcp_f32_e32 v21, v21
	v_rcp_f32_e32 v22, v22
	v_rcp_f32_e32 v23, v23
	v_rcp_f32_e32 v110, v110
	v_rcp_f32_e32 v111, v111
	v_rcp_f32_e32 v112, v112
	v_rcp_f32_e32 v113, v113
	v_mul_f32_e32 v20, v85, v20
	v_mul_f32_e32 v21, v85, v21
	v_mul_f32_e32 v22, v85, v22
	v_mul_f32_e32 v23, v85, v23
	v_mul_f32_e32 v110, v110, v182
	v_mul_f32_e32 v111, v111, v183
	v_mul_f32_e32 v112, v112, v184
	v_mul_f32_e32 v113, v113, v185
	v_exp_f32_e32 v20, v20
	v_exp_f32_e32 v21, v21
	v_exp_f32_e32 v22, v22
	v_exp_f32_e32 v23, v23
	s_nop 0
	v_fma_f32 v138, -v20, v20, 1.0
	v_fma_f32 v139, -v21, v21, 1.0
	v_fma_f32 v140, -v22, v22, 1.0
	v_fma_f32 v141, -v23, v23, 1.0
	v_max_f32_e32 v138, 0, v138
	v_max_f32_e32 v139, 0, v139
	v_max_f32_e32 v140, 0, v140
	v_max_f32_e32 v141, 0, v141
	v_sqrt_f32_e32 v138, v138
	v_sqrt_f32_e32 v139, v139
	v_sqrt_f32_e32 v140, v140
	v_sqrt_f32_e32 v141, v141
	s_nop 0
	v_mul_f32_e32 v110, v138, v110
	v_mul_f32_e32 v111, v139, v111
	v_mul_f32_e32 v112, v140, v112
	v_mul_f32_e32 v113, v141, v113
	v_add_f32_e32 v24, v24, v75
	v_add_f32_e32 v25, v25, v75
	v_add_f32_e32 v26, v26, v75
	v_add_f32_e32 v27, v27, v75
	v_add_f32_e32 v114, v114, v84
	v_add_f32_e32 v115, v115, v84
	v_add_f32_e32 v116, v116, v84
	v_add_f32_e32 v117, v117, v84
	v_exp_f32_e32 v24, v24
	v_exp_f32_e32 v25, v25
	v_exp_f32_e32 v26, v26
	v_exp_f32_e32 v27, v27
	v_exp_f32_e32 v114, v114
	v_exp_f32_e32 v115, v115
	v_exp_f32_e32 v116, v116
	v_exp_f32_e32 v117, v117
	v_add_f32_e32 v24, 1.0, v24
	v_add_f32_e32 v25, 1.0, v25
	v_add_f32_e32 v26, 1.0, v26
	v_add_f32_e32 v27, 1.0, v27
	v_add_f32_e32 v114, 1.0, v114
	v_add_f32_e32 v115, 1.0, v115
	v_add_f32_e32 v116, 1.0, v116
	v_add_f32_e32 v117, 1.0, v117
	v_rcp_f32_e32 v24, v24
	v_rcp_f32_e32 v25, v25
	v_rcp_f32_e32 v26, v26
	v_rcp_f32_e32 v27, v27
	v_rcp_f32_e32 v114, v114
	v_rcp_f32_e32 v115, v115
	v_rcp_f32_e32 v116, v116
	v_rcp_f32_e32 v117, v117
	v_mul_f32_e32 v24, v85, v24
	v_mul_f32_e32 v25, v85, v25
	v_mul_f32_e32 v26, v85, v26
	v_mul_f32_e32 v27, v85, v27
	v_mul_f32_e32 v114, v114, v186
	v_mul_f32_e32 v115, v115, v187
	v_mul_f32_e32 v116, v116, v188
	v_mul_f32_e32 v117, v117, v189
	v_exp_f32_e32 v24, v24
	v_exp_f32_e32 v25, v25
	v_exp_f32_e32 v26, v26
	v_exp_f32_e32 v27, v27
	s_nop 0
	v_fma_f32 v138, -v24, v24, 1.0
	v_fma_f32 v139, -v25, v25, 1.0
	v_fma_f32 v140, -v26, v26, 1.0
	v_fma_f32 v141, -v27, v27, 1.0
	v_max_f32_e32 v138, 0, v138
	v_max_f32_e32 v139, 0, v139
	v_max_f32_e32 v140, 0, v140
	v_max_f32_e32 v141, 0, v141
	v_sqrt_f32_e32 v138, v138
	v_sqrt_f32_e32 v139, v139
	v_sqrt_f32_e32 v140, v140
	v_sqrt_f32_e32 v141, v141
	s_nop 0
	v_mul_f32_e32 v114, v138, v114
	v_mul_f32_e32 v115, v139, v115
	v_mul_f32_e32 v116, v140, v116
	v_mul_f32_e32 v117, v141, v117
	v_add_f32_e32 v28, v28, v75
	v_add_f32_e32 v29, v29, v75
	v_add_f32_e32 v30, v30, v75
	v_add_f32_e32 v31, v31, v75
	v_add_f32_e32 v118, v118, v84
	v_add_f32_e32 v119, v119, v84
	v_add_f32_e32 v120, v120, v84
	v_add_f32_e32 v121, v121, v84
	v_exp_f32_e32 v28, v28
	v_exp_f32_e32 v29, v29
	v_exp_f32_e32 v30, v30
	v_exp_f32_e32 v31, v31
	v_exp_f32_e32 v118, v118
	v_exp_f32_e32 v119, v119
	v_exp_f32_e32 v120, v120
	v_exp_f32_e32 v121, v121
	v_add_f32_e32 v28, 1.0, v28
	v_add_f32_e32 v29, 1.0, v29
	v_add_f32_e32 v30, 1.0, v30
	v_add_f32_e32 v31, 1.0, v31
	v_add_f32_e32 v118, 1.0, v118
	v_add_f32_e32 v119, 1.0, v119
	v_add_f32_e32 v120, 1.0, v120
	v_add_f32_e32 v121, 1.0, v121
	v_rcp_f32_e32 v28, v28
	v_rcp_f32_e32 v29, v29
	v_rcp_f32_e32 v30, v30
	v_rcp_f32_e32 v31, v31
	v_rcp_f32_e32 v118, v118
	v_rcp_f32_e32 v119, v119
	v_rcp_f32_e32 v120, v120
	v_rcp_f32_e32 v121, v121
	v_mul_f32_e32 v28, v85, v28
	v_mul_f32_e32 v29, v85, v29
	v_mul_f32_e32 v30, v85, v30
	v_mul_f32_e32 v31, v85, v31
	v_mul_f32_e32 v118, v118, v190
	v_mul_f32_e32 v119, v119, v191
	v_mul_f32_e32 v120, v120, v192
	v_mul_f32_e32 v121, v121, v193
	v_exp_f32_e32 v28, v28
	v_exp_f32_e32 v29, v29
	v_exp_f32_e32 v30, v30
	v_exp_f32_e32 v31, v31
	s_nop 0
	v_fma_f32 v138, -v28, v28, 1.0
	v_fma_f32 v139, -v29, v29, 1.0
	v_fma_f32 v140, -v30, v30, 1.0
	v_fma_f32 v141, -v31, v31, 1.0
	v_max_f32_e32 v138, 0, v138
	v_max_f32_e32 v139, 0, v139
	v_max_f32_e32 v140, 0, v140
	v_max_f32_e32 v141, 0, v141
	v_sqrt_f32_e32 v138, v138
	v_sqrt_f32_e32 v139, v139
	v_sqrt_f32_e32 v140, v140
	v_sqrt_f32_e32 v141, v141
	s_nop 0
	v_mul_f32_e32 v118, v138, v118
	v_mul_f32_e32 v119, v139, v119
	v_mul_f32_e32 v120, v140, v120
	v_mul_f32_e32 v121, v141, v121
	s_mul_i32 s0, s71, 0x60000
	s_lshl_b32 s1, s56, 1
	s_add_u32 s0, s0, s1
	s_add_u32 s0, s0, 0x400
	s_add_u32 s4, s10, s0
	s_addc_u32 s5, s11, 0
	global_load_ushort v162, v134, s[4:5]
	s_add_u32 s4, s4, 0xc00
	s_addc_u32 s5, s5, 0
	global_load_ushort v163, v134, s[4:5]
	s_add_u32 s4, s4, 0xc00
	s_addc_u32 s5, s5, 0
	global_load_ushort v164, v134, s[4:5]
	s_add_u32 s4, s4, 0xc00
	s_addc_u32 s5, s5, 0
	global_load_ushort v165, v134, s[4:5]
	s_add_u32 s4, s4, 0xc00
	s_addc_u32 s5, s5, 0
	global_load_ushort v166, v134, s[4:5]
	s_add_u32 s4, s4, 0xc00
	s_addc_u32 s5, s5, 0
	global_load_ushort v167, v134, s[4:5]
	s_add_u32 s4, s4, 0xc00
	s_addc_u32 s5, s5, 0
	global_load_ushort v168, v134, s[4:5]
	s_add_u32 s4, s4, 0xc00
	s_addc_u32 s5, s5, 0
	global_load_ushort v169, v134, s[4:5]
	s_add_u32 s4, s4, 0xc00
	s_addc_u32 s5, s5, 0
	global_load_ushort v170, v134, s[4:5]
	s_add_u32 s4, s4, 0xc00
	s_addc_u32 s5, s5, 0
; __device__ __forceinline__ float bf2f(u16 h) { return __uint_as_float(((unsigned)h) << 16); }
; __device__ __forceinline__ void lru_tile(const Params& P, int chunk, int head, int pass, char* smem_raw) {
;     ...
;         float Pp = 1.f, H = 0.f;
; #pragma unroll 4
;         for (int i = 0; i < 16; ++i) {
;           const int tl = (d == 0) ? (q * 16 + i) : (q * 16 + 15 - i);
;           const float a = sm_a[tl * 64 + ch], b = sm_b[tl * 64 + ch];
;           H = a * H + b; Pp *= a;
;         }
;         sm_ph[pos * 64 + ch] = make_float2(Pp, H);
;       }
;       __syncthreads();
;       const float2 p0 = sm_ph[ch], p1 = sm_ph[64 + ch], p2 = sm_ph[128 + ch], p3 = sm_ph[192 + ch];
;       if (pass == 2) {
;         float hin = cB;
;         if (pos > 0) hin = p0.x * hin + p0.y;
;         if (pos > 1) hin = p1.x * hin + p1.y;
;         if (pos > 2) hin = p2.x * hin + p2.y;
;         float h = hin;
;         float hfp[16], gp[16];
;         if (d == 1) {
; #pragma unroll
;           for (int i = 0; i < 16; ++i) {
;             const long rowp = row0 + sb * 64 + q * 16 + 15 - i;
;             hfp[i] = hfbuf[rowp * 512 + gch];
;             gp[i] = bf2f(P.zq[rowp * 1536 + 512 + gch]);
;           }
;         }
; #pragma unroll
;         for (int i = 0; i < 16; ++i) {
;           const int tl = (d == 0) ? (q * 16 + i) : (q * 16 + 15 - i);
;           const float a = sm_a[tl * 64 + ch], b = sm_b[tl * 64 + ch];
;           h = a * h + b;
;           const long row = row0 + sb * 64 + tl;
;           if (d == 0) {
;             hfw[row * 512 + gch] = h;
;           } else {
;             const float hfv = hfp[i];
;             const float g = gp[i];
;             const float tz = 0.7978845608028654f * (g + 0.044715f * g * g * g);
;             const float th = 1.f - 2.f * __builtin_amdgcn_rcpf(1.f + __expf(2.f * tz));
;             const float ge = 0.5f * g * (1.f + th);
;             P.cat[row * 1024 + gch] = f2bf((hfv + h) * ge);
;           }
;         }
	global_load_ushort v171, v134, s[4:5]
	s_add_u32 s4, s4, 0xc00
	s_addc_u32 s5, s5, 0
	global_load_ushort v172, v134, s[4:5]
	s_add_u32 s4, s4, 0xc00
	s_addc_u32 s5, s5, 0
	global_load_ushort v173, v134, s[4:5]
	s_add_u32 s4, s4, 0xc00
	s_addc_u32 s5, s5, 0
	global_load_ushort v174, v134, s[4:5]
	s_add_u32 s4, s4, 0xc00
	s_addc_u32 s5, s5, 0
	global_load_ushort v175, v134, s[4:5]
	s_add_u32 s4, s4, 0xc00
	s_addc_u32 s5, s5, 0
	global_load_ushort v176, v134, s[4:5]
	s_add_u32 s4, s4, 0xc00
	s_addc_u32 s5, s5, 0
	global_load_ushort v177, v134, s[4:5]
	s_add_u32 s4, s4, 0xc00
	s_addc_u32 s5, s5, 0
	global_load_ushort v178, v134, s[4:5]
	s_add_u32 s4, s4, 0xc00
	s_addc_u32 s5, s5, 0
	global_load_ushort v179, v134, s[4:5]
	s_add_u32 s4, s4, 0xc00
	s_addc_u32 s5, s5, 0
	global_load_ushort v180, v134, s[4:5]
	s_add_u32 s4, s4, 0xc00
	s_addc_u32 s5, s5, 0
	global_load_ushort v181, v134, s[4:5]
	s_add_u32 s4, s4, 0xc00
	s_addc_u32 s5, s5, 0
	global_load_ushort v182, v134, s[4:5]
	s_add_u32 s4, s4, 0xc00
	s_addc_u32 s5, s5, 0
	global_load_ushort v183, v134, s[4:5]
	s_add_u32 s4, s4, 0xc00
	s_addc_u32 s5, s5, 0
	global_load_ushort v184, v134, s[4:5]
	s_add_u32 s4, s4, 0xc00
	s_addc_u32 s5, s5, 0
	global_load_ushort v185, v134, s[4:5]
	s_add_u32 s4, s4, 0xc00
	s_addc_u32 s5, s5, 0
	global_load_ushort v186, v134, s[4:5]
	s_add_u32 s4, s4, 0xc00
	s_addc_u32 s5, s5, 0
	global_load_ushort v187, v134, s[4:5]
	s_add_u32 s4, s4, 0xc00
	s_addc_u32 s5, s5, 0
	global_load_ushort v188, v134, s[4:5]
	s_add_u32 s4, s4, 0xc00
	s_addc_u32 s5, s5, 0
	global_load_ushort v189, v134, s[4:5]
	s_add_u32 s4, s4, 0xc00
	s_addc_u32 s5, s5, 0
	global_load_ushort v190, v134, s[4:5]
	s_add_u32 s4, s4, 0xc00
	s_addc_u32 s5, s5, 0
	global_load_ushort v191, v134, s[4:5]
	s_add_u32 s4, s4, 0xc00
	s_addc_u32 s5, s5, 0
	global_load_ushort v192, v134, s[4:5]
	s_add_u32 s4, s4, 0xc00
	s_addc_u32 s5, s5, 0
	global_load_ushort v193, v134, s[4:5]
	v_mov_b32_e32 v253, v31
	v_mov_b32_e32 v254, v121
	v_fma_f32 v254, v30, v254, v120
	v_mul_f32_e32 v253, v253, v30
	v_fma_f32 v254, v29, v254, v119
	v_mul_f32_e32 v253, v253, v29
	v_fma_f32 v254, v28, v254, v118
	v_mul_f32_e32 v253, v253, v28
	v_fma_f32 v254, v27, v254, v117
	v_mul_f32_e32 v253, v253, v27
	v_fma_f32 v254, v26, v254, v116
	v_mul_f32_e32 v253, v253, v26
	v_fma_f32 v254, v25, v254, v115
	v_mul_f32_e32 v253, v253, v25
	v_fma_f32 v254, v24, v254, v114
	v_mul_f32_e32 v253, v253, v24
	v_fma_f32 v254, v23, v254, v113
	v_mul_f32_e32 v253, v253, v23
	v_fma_f32 v254, v22, v254, v112
	v_mul_f32_e32 v253, v253, v22
	v_fma_f32 v254, v21, v254, v111
	v_mul_f32_e32 v253, v253, v21
	v_fma_f32 v254, v20, v254, v110
	v_mul_f32_e32 v253, v253, v20
	v_fma_f32 v254, v19, v254, v109
	v_mul_f32_e32 v253, v253, v19
	v_fma_f32 v254, v18, v254, v108
	v_mul_f32_e32 v253, v253, v18
	v_fma_f32 v254, v17, v254, v107
	v_mul_f32_e32 v253, v253, v17
	v_fma_f32 v254, v16, v254, v106
	v_mul_f32_e32 v253, v253, v16
	v_fma_f32 v254, v15, v254, v105
	v_mul_f32_e32 v253, v253, v15
	v_fma_f32 v254, v14, v254, v104
	v_mul_f32_e32 v253, v253, v14
	v_fma_f32 v254, v13, v254, v103
	v_mul_f32_e32 v253, v253, v13
	v_fma_f32 v254, v12, v254, v102
	v_mul_f32_e32 v253, v253, v12
	v_fma_f32 v254, v11, v254, v101
	v_mul_f32_e32 v253, v253, v11
	v_fma_f32 v254, v10, v254, v100
	v_mul_f32_e32 v253, v253, v10
	v_fma_f32 v254, v9, v254, v99
	v_mul_f32_e32 v253, v253, v9
	v_fma_f32 v254, v8, v254, v98
	v_mul_f32_e32 v253, v253, v8
	v_fma_f32 v254, v7, v254, v97
	v_mul_f32_e32 v253, v253, v7
	v_fma_f32 v254, v6, v254, v96
	v_mul_f32_e32 v253, v253, v6
	v_fma_f32 v254, v5, v254, v95
	v_mul_f32_e32 v253, v253, v5
	v_fma_f32 v254, v4, v254, v94
	v_mul_f32_e32 v253, v253, v4
	v_fma_f32 v254, v3, v254, v93
	v_mul_f32_e32 v253, v253, v3
	v_fma_f32 v254, v2, v254, v92
	v_mul_f32_e32 v253, v253, v2
	v_fma_f32 v254, v1, v254, v91
	v_mul_f32_e32 v253, v253, v1
	v_fma_f32 v254, v0, v254, v90
	v_mul_f32_e32 v253, v253, v0
	v_mov_b32_e32 v138, v253
	v_mov_b32_e32 v139, v253
	s_nop 1
	v_permlane16_swap_b32_e32 v138, v139
	v_mov_b32_e32 v140, v138
	v_mov_b32_e32 v141, v139
	s_nop 1
	v_permlane32_swap_b32_e32 v138, v140
	v_permlane32_swap_b32_e32 v139, v141
	v_mov_b32_e32 v198, v254
	v_mov_b32_e32 v199, v254
	s_nop 1
	v_permlane16_swap_b32_e32 v198, v199
	v_mov_b32_e32 v200, v198
	v_mov_b32_e32 v201, v199
	s_nop 1
	v_permlane32_swap_b32_e32 v198, v200
	v_permlane32_swap_b32_e32 v199, v201
	v_mov_b32_e32 v202, v67
	v_fma_f32 v151, v141, v202, v201
	v_fma_f32 v150, v140, v151, v200
	v_fma_f32 v136, v139, v150, v199
	v_mov_b32_e32 v254, v202
	v_cndmask_b32_e64 v254, v254, v151, s[78:79]
	v_cndmask_b32_e64 v254, v254, v150, s[80:81]
	v_cndmask_b32_e64 v254, v254, v136, s[82:83]
	v_fma_f32 v121, v31, v254, v121
	v_fma_f32 v120, v30, v121, v120
	v_fma_f32 v119, v29, v120, v119
	v_fma_f32 v118, v28, v119, v118
	v_fma_f32 v117, v27, v118, v117
	v_fma_f32 v116, v26, v117, v116
	v_fma_f32 v115, v25, v116, v115
	v_fma_f32 v114, v24, v115, v114
	v_fma_f32 v113, v23, v114, v113
	v_fma_f32 v112, v22, v113, v112
	v_fma_f32 v111, v21, v112, v111
	v_fma_f32 v110, v20, v111, v110
	v_fma_f32 v109, v19, v110, v109
	v_fma_f32 v108, v18, v109, v108
	v_fma_f32 v107, v17, v108, v107
	v_fma_f32 v106, v16, v107, v106
	v_fma_f32 v105, v15, v106, v105
	v_fma_f32 v104, v14, v105, v104
	v_fma_f32 v103, v13, v104, v103
	v_fma_f32 v102, v12, v103, v102
	v_fma_f32 v101, v11, v102, v101
	v_fma_f32 v100, v10, v101, v100
	v_fma_f32 v99, v9, v100, v99
	v_fma_f32 v98, v8, v99, v98
	v_fma_f32 v97, v7, v98, v97
	v_fma_f32 v96, v6, v97, v96
	v_fma_f32 v95, v5, v96, v95
	v_fma_f32 v94, v4, v95, v94
	v_fma_f32 v93, v3, v94, v93
	v_fma_f32 v92, v2, v93, v92
	v_fma_f32 v91, v1, v92, v91
	v_fma_f32 v90, v0, v91, v90
	s_waitcnt vmcnt(0)
; __device__ __forceinline__ void lru_tile(const Params& P, int chunk, int head, int pass, char* smem_raw) {
;     ...
; #pragma unroll
;         for (int i = 0; i < 16; ++i) {
;           const int tl = (d == 0) ? (q * 16 + i) : (q * 16 + 15 - i);
;           const float a = sm_a[tl * 64 + ch], b = sm_b[tl * 64 + ch];
;           h = a * h + b;
;           const long row = row0 + sb * 64 + tl;
;           if (d == 0) {
;             hfw[row * 512 + gch] = h;
;           } else {
;             const float hfv = hfp[i];
;             const float g = gp[i];
;             const float tz = 0.7978845608028654f * (g + 0.044715f * g * g * g);
;             const float th = 1.f - 2.f * __builtin_amdgcn_rcpf(1.f + __expf(2.f * tz));
;             const float ge = 0.5f * g * (1.f + th);
;             P.cat[row * 1024 + gch] = f2bf((hfv + h) * ge);
;           }
	v_lshlrev_b32_e32 v162, 16, v162
	v_lshlrev_b32_e32 v163, 16, v163
	v_lshlrev_b32_e32 v164, 16, v164
	v_lshlrev_b32_e32 v165, 16, v165
	v_lshlrev_b32_e32 v166, 16, v166
	v_lshlrev_b32_e32 v167, 16, v167
	v_lshlrev_b32_e32 v168, 16, v168
	v_lshlrev_b32_e32 v169, 16, v169
	v_lshlrev_b32_e32 v170, 16, v170
	v_lshlrev_b32_e32 v171, 16, v171
	v_lshlrev_b32_e32 v172, 16, v172
	v_lshlrev_b32_e32 v173, 16, v173
	v_lshlrev_b32_e32 v174, 16, v174
	v_lshlrev_b32_e32 v175, 16, v175
	v_lshlrev_b32_e32 v176, 16, v176
	v_lshlrev_b32_e32 v177, 16, v177
	v_lshlrev_b32_e32 v178, 16, v178
	v_lshlrev_b32_e32 v179, 16, v179
	v_lshlrev_b32_e32 v180, 16, v180
	v_lshlrev_b32_e32 v181, 16, v181
	v_lshlrev_b32_e32 v182, 16, v182
	v_lshlrev_b32_e32 v183, 16, v183
	v_lshlrev_b32_e32 v184, 16, v184
	v_lshlrev_b32_e32 v185, 16, v185
	v_lshlrev_b32_e32 v186, 16, v186
	v_lshlrev_b32_e32 v187, 16, v187
	v_lshlrev_b32_e32 v188, 16, v188
	v_lshlrev_b32_e32 v189, 16, v189
	v_lshlrev_b32_e32 v190, 16, v190
	v_lshlrev_b32_e32 v191, 16, v191
	v_lshlrev_b32_e32 v192, 16, v192
	v_lshlrev_b32_e32 v193, 16, v193
	v_mov_b32_e32 v202, 0x3d372713
	v_mul_f32_e32 v138, v162, v162
	v_mul_f32_e32 v139, v163, v163
	v_mul_f32_e32 v140, v164, v164
	v_mul_f32_e32 v141, v165, v165
	v_mul_f32_e32 v138, v138, v162
	v_mul_f32_e32 v139, v139, v163
	v_mul_f32_e32 v140, v140, v164
	v_mul_f32_e32 v141, v141, v165
	v_fma_f32 v138, v202, v138, v162
	v_fma_f32 v139, v202, v139, v163
	v_fma_f32 v140, v202, v140, v164
	v_fma_f32 v141, v202, v141, v165
	v_mul_f32_e32 v138, 0x40135761, v138
	v_mul_f32_e32 v139, 0x40135761, v139
	v_mul_f32_e32 v140, 0x40135761, v140
	v_mul_f32_e32 v141, 0x40135761, v141
	v_exp_f32_e32 v138, v138
	v_exp_f32_e32 v139, v139
	v_exp_f32_e32 v140, v140
	v_exp_f32_e32 v141, v141
	s_nop 0
	v_add_f32_e32 v138, 1.0, v138
	v_add_f32_e32 v139, 1.0, v139
	v_add_f32_e32 v140, 1.0, v140
	v_add_f32_e32 v141, 1.0, v141
	v_rcp_f32_e32 v138, v138
	v_rcp_f32_e32 v139, v139
	v_rcp_f32_e32 v140, v140
	v_rcp_f32_e32 v141, v141
	s_nop 0
	v_fma_f32 v138, -2.0, v138, 1.0
	v_fma_f32 v139, -2.0, v139, 1.0
	v_fma_f32 v140, -2.0, v140, 1.0
	v_fma_f32 v141, -2.0, v141, 1.0
	v_add_f32_e32 v138, 1.0, v138
	v_add_f32_e32 v139, 1.0, v139
	v_add_f32_e32 v140, 1.0, v140
	v_add_f32_e32 v141, 1.0, v141
	v_mul_f32_e32 v162, 0.5, v162
	v_mul_f32_e32 v163, 0.5, v163
	v_mul_f32_e32 v164, 0.5, v164
	v_mul_f32_e32 v165, 0.5, v165
	v_mul_f32_e32 v162, v162, v138
	v_mul_f32_e32 v163, v163, v139
	v_mul_f32_e32 v164, v164, v140
	v_mul_f32_e32 v165, v165, v141
	v_add_f32_e32 v90, v205, v90
	v_add_f32_e32 v91, v206, v91
	v_add_f32_e32 v92, v207, v92
	v_add_f32_e32 v93, v208, v93
	v_mul_f32_e32 v90, v90, v162
	v_mul_f32_e32 v91, v91, v163
	v_mul_f32_e32 v92, v92, v164
	v_mul_f32_e32 v93, v93, v165
	v_cvt_pk_bf16_f32 v90, v90, v90
	v_cvt_pk_bf16_f32 v91, v91, v91
	v_cvt_pk_bf16_f32 v92, v92, v92
	v_cvt_pk_bf16_f32 v93, v93, v93
	v_mul_f32_e32 v138, v166, v166
	v_mul_f32_e32 v139, v167, v167
	v_mul_f32_e32 v140, v168, v168
	v_mul_f32_e32 v141, v169, v169
	v_mul_f32_e32 v138, v138, v166
	v_mul_f32_e32 v139, v139, v167
	v_mul_f32_e32 v140, v140, v168
	v_mul_f32_e32 v141, v141, v169
	v_fma_f32 v138, v202, v138, v166
	v_fma_f32 v139, v202, v139, v167
	v_fma_f32 v140, v202, v140, v168
	v_fma_f32 v141, v202, v141, v169
	v_mul_f32_e32 v138, 0x40135761, v138
	v_mul_f32_e32 v139, 0x40135761, v139
	v_mul_f32_e32 v140, 0x40135761, v140
	v_mul_f32_e32 v141, 0x40135761, v141
	v_exp_f32_e32 v138, v138
	v_exp_f32_e32 v139, v139
	v_exp_f32_e32 v140, v140
	v_exp_f32_e32 v141, v141
	s_nop 0
	v_add_f32_e32 v138, 1.0, v138
	v_add_f32_e32 v139, 1.0, v139
	v_add_f32_e32 v140, 1.0, v140
	v_add_f32_e32 v141, 1.0, v141
	v_rcp_f32_e32 v138, v138
	v_rcp_f32_e32 v139, v139
	v_rcp_f32_e32 v140, v140
	v_rcp_f32_e32 v141, v141
	s_nop 0
	v_fma_f32 v138, -2.0, v138, 1.0
	v_fma_f32 v139, -2.0, v139, 1.0
	v_fma_f32 v140, -2.0, v140, 1.0
	v_fma_f32 v141, -2.0, v141, 1.0
	v_add_f32_e32 v138, 1.0, v138
	v_add_f32_e32 v139, 1.0, v139
	v_add_f32_e32 v140, 1.0, v140
	v_add_f32_e32 v141, 1.0, v141
	v_mul_f32_e32 v166, 0.5, v166
	v_mul_f32_e32 v167, 0.5, v167
	v_mul_f32_e32 v168, 0.5, v168
	v_mul_f32_e32 v169, 0.5, v169
	v_mul_f32_e32 v166, v166, v138
	v_mul_f32_e32 v167, v167, v139
	v_mul_f32_e32 v168, v168, v140
	v_mul_f32_e32 v169, v169, v141
	v_add_f32_e32 v94, v209, v94
	v_add_f32_e32 v95, v210, v95
	v_add_f32_e32 v96, v211, v96
	v_add_f32_e32 v97, v212, v97
	v_mul_f32_e32 v94, v94, v166
	v_mul_f32_e32 v95, v95, v167
	v_mul_f32_e32 v96, v96, v168
	v_mul_f32_e32 v97, v97, v169
	v_cvt_pk_bf16_f32 v94, v94, v94
	v_cvt_pk_bf16_f32 v95, v95, v95
	v_cvt_pk_bf16_f32 v96, v96, v96
	v_cvt_pk_bf16_f32 v97, v97, v97
	v_mul_f32_e32 v138, v170, v170
	v_mul_f32_e32 v139, v171, v171
	v_mul_f32_e32 v140, v172, v172
	v_mul_f32_e32 v141, v173, v173
	v_mul_f32_e32 v138, v138, v170
	v_mul_f32_e32 v139, v139, v171
	v_mul_f32_e32 v140, v140, v172
	v_mul_f32_e32 v141, v141, v173
	v_fma_f32 v138, v202, v138, v170
	v_fma_f32 v139, v202, v139, v171
	v_fma_f32 v140, v202, v140, v172
	v_fma_f32 v141, v202, v141, v173
	v_mul_f32_e32 v138, 0x40135761, v138
	v_mul_f32_e32 v139, 0x40135761, v139
	v_mul_f32_e32 v140, 0x40135761, v140
	v_mul_f32_e32 v141, 0x40135761, v141
	v_exp_f32_e32 v138, v138
	v_exp_f32_e32 v139, v139
	v_exp_f32_e32 v140, v140
	v_exp_f32_e32 v141, v141
	s_nop 0
	v_add_f32_e32 v138, 1.0, v138
	v_add_f32_e32 v139, 1.0, v139
	v_add_f32_e32 v140, 1.0, v140
	v_add_f32_e32 v141, 1.0, v141
	v_rcp_f32_e32 v138, v138
	v_rcp_f32_e32 v139, v139
	v_rcp_f32_e32 v140, v140
	v_rcp_f32_e32 v141, v141
	s_nop 0
	v_fma_f32 v138, -2.0, v138, 1.0
	v_fma_f32 v139, -2.0, v139, 1.0
; __device__ __forceinline__ void lru_tile(const Params& P, int chunk, int head, int pass, char* smem_raw) {
;     ...
;           } else {
;             const float hfv = hfp[i];
;             const float g = gp[i];
;             const float tz = 0.7978845608028654f * (g + 0.044715f * g * g * g);
;             const float th = 1.f - 2.f * __builtin_amdgcn_rcpf(1.f + __expf(2.f * tz));
;             const float ge = 0.5f * g * (1.f + th);
;             P.cat[row * 1024 + gch] = f2bf((hfv + h) * ge);
;           }
	v_fma_f32 v140, -2.0, v140, 1.0
	v_fma_f32 v141, -2.0, v141, 1.0
	v_add_f32_e32 v138, 1.0, v138
	v_add_f32_e32 v139, 1.0, v139
	v_add_f32_e32 v140, 1.0, v140
	v_add_f32_e32 v141, 1.0, v141
	v_mul_f32_e32 v170, 0.5, v170
	v_mul_f32_e32 v171, 0.5, v171
	v_mul_f32_e32 v172, 0.5, v172
	v_mul_f32_e32 v173, 0.5, v173
	v_mul_f32_e32 v170, v170, v138
	v_mul_f32_e32 v171, v171, v139
	v_mul_f32_e32 v172, v172, v140
	v_mul_f32_e32 v173, v173, v141
	v_add_f32_e32 v98, v213, v98
	v_add_f32_e32 v99, v214, v99
	v_add_f32_e32 v100, v215, v100
	v_add_f32_e32 v101, v216, v101
	v_mul_f32_e32 v98, v98, v170
	v_mul_f32_e32 v99, v99, v171
	v_mul_f32_e32 v100, v100, v172
	v_mul_f32_e32 v101, v101, v173
	v_cvt_pk_bf16_f32 v98, v98, v98
	v_cvt_pk_bf16_f32 v99, v99, v99
	v_cvt_pk_bf16_f32 v100, v100, v100
	v_cvt_pk_bf16_f32 v101, v101, v101
	v_mul_f32_e32 v138, v174, v174
	v_mul_f32_e32 v139, v175, v175
	v_mul_f32_e32 v140, v176, v176
	v_mul_f32_e32 v141, v177, v177
	v_mul_f32_e32 v138, v138, v174
	v_mul_f32_e32 v139, v139, v175
	v_mul_f32_e32 v140, v140, v176
	v_mul_f32_e32 v141, v141, v177
	v_fma_f32 v138, v202, v138, v174
	v_fma_f32 v139, v202, v139, v175
	v_fma_f32 v140, v202, v140, v176
	v_fma_f32 v141, v202, v141, v177
	v_mul_f32_e32 v138, 0x40135761, v138
	v_mul_f32_e32 v139, 0x40135761, v139
	v_mul_f32_e32 v140, 0x40135761, v140
	v_mul_f32_e32 v141, 0x40135761, v141
	v_exp_f32_e32 v138, v138
	v_exp_f32_e32 v139, v139
	v_exp_f32_e32 v140, v140
	v_exp_f32_e32 v141, v141
	s_nop 0
	v_add_f32_e32 v138, 1.0, v138
	v_add_f32_e32 v139, 1.0, v139
	v_add_f32_e32 v140, 1.0, v140
	v_add_f32_e32 v141, 1.0, v141
	v_rcp_f32_e32 v138, v138
	v_rcp_f32_e32 v139, v139
	v_rcp_f32_e32 v140, v140
	v_rcp_f32_e32 v141, v141
	s_nop 0
	v_fma_f32 v138, -2.0, v138, 1.0
	v_fma_f32 v139, -2.0, v139, 1.0
	v_fma_f32 v140, -2.0, v140, 1.0
	v_fma_f32 v141, -2.0, v141, 1.0
	v_add_f32_e32 v138, 1.0, v138
	v_add_f32_e32 v139, 1.0, v139
	v_add_f32_e32 v140, 1.0, v140
	v_add_f32_e32 v141, 1.0, v141
	v_mul_f32_e32 v174, 0.5, v174
	v_mul_f32_e32 v175, 0.5, v175
	v_mul_f32_e32 v176, 0.5, v176
	v_mul_f32_e32 v177, 0.5, v177
	v_mul_f32_e32 v174, v174, v138
	v_mul_f32_e32 v175, v175, v139
	v_mul_f32_e32 v176, v176, v140
	v_mul_f32_e32 v177, v177, v141
	v_add_f32_e32 v102, v217, v102
	v_add_f32_e32 v103, v218, v103
	v_add_f32_e32 v104, v219, v104
	v_add_f32_e32 v105, v220, v105
	v_mul_f32_e32 v102, v102, v174
	v_mul_f32_e32 v103, v103, v175
	v_mul_f32_e32 v104, v104, v176
	v_mul_f32_e32 v105, v105, v177
	v_cvt_pk_bf16_f32 v102, v102, v102
	v_cvt_pk_bf16_f32 v103, v103, v103
	v_cvt_pk_bf16_f32 v104, v104, v104
	v_cvt_pk_bf16_f32 v105, v105, v105
	v_mul_f32_e32 v138, v178, v178
	v_mul_f32_e32 v139, v179, v179
	v_mul_f32_e32 v140, v180, v180
	v_mul_f32_e32 v141, v181, v181
	v_mul_f32_e32 v138, v138, v178
	v_mul_f32_e32 v139, v139, v179
	v_mul_f32_e32 v140, v140, v180
	v_mul_f32_e32 v141, v141, v181
	v_fma_f32 v138, v202, v138, v178
	v_fma_f32 v139, v202, v139, v179
	v_fma_f32 v140, v202, v140, v180
	v_fma_f32 v141, v202, v141, v181
	v_mul_f32_e32 v138, 0x40135761, v138
	v_mul_f32_e32 v139, 0x40135761, v139
	v_mul_f32_e32 v140, 0x40135761, v140
	v_mul_f32_e32 v141, 0x40135761, v141
	v_exp_f32_e32 v138, v138
	v_exp_f32_e32 v139, v139
	v_exp_f32_e32 v140, v140
	v_exp_f32_e32 v141, v141
	s_nop 0
	v_add_f32_e32 v138, 1.0, v138
	v_add_f32_e32 v139, 1.0, v139
	v_add_f32_e32 v140, 1.0, v140
	v_add_f32_e32 v141, 1.0, v141
	v_rcp_f32_e32 v138, v138
	v_rcp_f32_e32 v139, v139
	v_rcp_f32_e32 v140, v140
	v_rcp_f32_e32 v141, v141
	s_nop 0
	v_fma_f32 v138, -2.0, v138, 1.0
	v_fma_f32 v139, -2.0, v139, 1.0
	v_fma_f32 v140, -2.0, v140, 1.0
	v_fma_f32 v141, -2.0, v141, 1.0
	v_add_f32_e32 v138, 1.0, v138
	v_add_f32_e32 v139, 1.0, v139
	v_add_f32_e32 v140, 1.0, v140
	v_add_f32_e32 v141, 1.0, v141
	v_mul_f32_e32 v178, 0.5, v178
	v_mul_f32_e32 v179, 0.5, v179
	v_mul_f32_e32 v180, 0.5, v180
	v_mul_f32_e32 v181, 0.5, v181
	v_mul_f32_e32 v178, v178, v138
	v_mul_f32_e32 v179, v179, v139
	v_mul_f32_e32 v180, v180, v140
	v_mul_f32_e32 v181, v181, v141
	v_add_f32_e32 v106, v221, v106
	v_add_f32_e32 v107, v222, v107
	v_add_f32_e32 v108, v223, v108
	v_add_f32_e32 v109, v224, v109
	v_mul_f32_e32 v106, v106, v178
	v_mul_f32_e32 v107, v107, v179
	v_mul_f32_e32 v108, v108, v180
	v_mul_f32_e32 v109, v109, v181
	v_cvt_pk_bf16_f32 v106, v106, v106
	v_cvt_pk_bf16_f32 v107, v107, v107
	v_cvt_pk_bf16_f32 v108, v108, v108
	v_cvt_pk_bf16_f32 v109, v109, v109
	v_mul_f32_e32 v138, v182, v182
	v_mul_f32_e32 v139, v183, v183
	v_mul_f32_e32 v140, v184, v184
	v_mul_f32_e32 v141, v185, v185
	v_mul_f32_e32 v138, v138, v182
	v_mul_f32_e32 v139, v139, v183
	v_mul_f32_e32 v140, v140, v184
	v_mul_f32_e32 v141, v141, v185
	v_fma_f32 v138, v202, v138, v182
	v_fma_f32 v139, v202, v139, v183
	v_fma_f32 v140, v202, v140, v184
	v_fma_f32 v141, v202, v141, v185
	v_mul_f32_e32 v138, 0x40135761, v138
	v_mul_f32_e32 v139, 0x40135761, v139
	v_mul_f32_e32 v140, 0x40135761, v140
	v_mul_f32_e32 v141, 0x40135761, v141
	v_exp_f32_e32 v138, v138
	v_exp_f32_e32 v139, v139
	v_exp_f32_e32 v140, v140
	v_exp_f32_e32 v141, v141
	s_nop 0
	v_add_f32_e32 v138, 1.0, v138
	v_add_f32_e32 v139, 1.0, v139
	v_add_f32_e32 v140, 1.0, v140
	v_add_f32_e32 v141, 1.0, v141
	v_rcp_f32_e32 v138, v138
	v_rcp_f32_e32 v139, v139
	v_rcp_f32_e32 v140, v140
	v_rcp_f32_e32 v141, v141
	s_nop 0
	v_fma_f32 v138, -2.0, v138, 1.0
	v_fma_f32 v139, -2.0, v139, 1.0
	v_fma_f32 v140, -2.0, v140, 1.0
	v_fma_f32 v141, -2.0, v141, 1.0
	v_add_f32_e32 v138, 1.0, v138
	v_add_f32_e32 v139, 1.0, v139
	v_add_f32_e32 v140, 1.0, v140
	v_add_f32_e32 v141, 1.0, v141
	v_mul_f32_e32 v182, 0.5, v182
	v_mul_f32_e32 v183, 0.5, v183
; __device__ __forceinline__ void lru_tile(const Params& P, int chunk, int head, int pass, char* smem_raw) {
;     ...
;           } else {
;             const float hfv = hfp[i];
;             const float g = gp[i];
;             const float tz = 0.7978845608028654f * (g + 0.044715f * g * g * g);
;             const float th = 1.f - 2.f * __builtin_amdgcn_rcpf(1.f + __expf(2.f * tz));
;             const float ge = 0.5f * g * (1.f + th);
;             P.cat[row * 1024 + gch] = f2bf((hfv + h) * ge);
;           }
	v_mul_f32_e32 v184, 0.5, v184
	v_mul_f32_e32 v185, 0.5, v185
	v_mul_f32_e32 v182, v182, v138
	v_mul_f32_e32 v183, v183, v139
	v_mul_f32_e32 v184, v184, v140
	v_mul_f32_e32 v185, v185, v141
	v_add_f32_e32 v110, v225, v110
	v_add_f32_e32 v111, v226, v111
	v_add_f32_e32 v112, v227, v112
	v_add_f32_e32 v113, v228, v113
	v_mul_f32_e32 v110, v110, v182
	v_mul_f32_e32 v111, v111, v183
	v_mul_f32_e32 v112, v112, v184
	v_mul_f32_e32 v113, v113, v185
	v_cvt_pk_bf16_f32 v110, v110, v110
	v_cvt_pk_bf16_f32 v111, v111, v111
	v_cvt_pk_bf16_f32 v112, v112, v112
	v_cvt_pk_bf16_f32 v113, v113, v113
	v_mul_f32_e32 v138, v186, v186
	v_mul_f32_e32 v139, v187, v187
	v_mul_f32_e32 v140, v188, v188
	v_mul_f32_e32 v141, v189, v189
	v_mul_f32_e32 v138, v138, v186
	v_mul_f32_e32 v139, v139, v187
	v_mul_f32_e32 v140, v140, v188
	v_mul_f32_e32 v141, v141, v189
	v_fma_f32 v138, v202, v138, v186
	v_fma_f32 v139, v202, v139, v187
	v_fma_f32 v140, v202, v140, v188
	v_fma_f32 v141, v202, v141, v189
	v_mul_f32_e32 v138, 0x40135761, v138
	v_mul_f32_e32 v139, 0x40135761, v139
	v_mul_f32_e32 v140, 0x40135761, v140
	v_mul_f32_e32 v141, 0x40135761, v141
	v_exp_f32_e32 v138, v138
	v_exp_f32_e32 v139, v139
	v_exp_f32_e32 v140, v140
	v_exp_f32_e32 v141, v141
	s_nop 0
	v_add_f32_e32 v138, 1.0, v138
	v_add_f32_e32 v139, 1.0, v139
	v_add_f32_e32 v140, 1.0, v140
	v_add_f32_e32 v141, 1.0, v141
	v_rcp_f32_e32 v138, v138
	v_rcp_f32_e32 v139, v139
	v_rcp_f32_e32 v140, v140
	v_rcp_f32_e32 v141, v141
	s_nop 0
	v_fma_f32 v138, -2.0, v138, 1.0
	v_fma_f32 v139, -2.0, v139, 1.0
	v_fma_f32 v140, -2.0, v140, 1.0
	v_fma_f32 v141, -2.0, v141, 1.0
	v_add_f32_e32 v138, 1.0, v138
	v_add_f32_e32 v139, 1.0, v139
	v_add_f32_e32 v140, 1.0, v140
	v_add_f32_e32 v141, 1.0, v141
	v_mul_f32_e32 v186, 0.5, v186
	v_mul_f32_e32 v187, 0.5, v187
	v_mul_f32_e32 v188, 0.5, v188
	v_mul_f32_e32 v189, 0.5, v189
	v_mul_f32_e32 v186, v186, v138
	v_mul_f32_e32 v187, v187, v139
	v_mul_f32_e32 v188, v188, v140
	v_mul_f32_e32 v189, v189, v141
	v_add_f32_e32 v114, v229, v114
	v_add_f32_e32 v115, v230, v115
	v_add_f32_e32 v116, v231, v116
	v_add_f32_e32 v117, v232, v117
	v_mul_f32_e32 v114, v114, v186
	v_mul_f32_e32 v115, v115, v187
	v_mul_f32_e32 v116, v116, v188
	v_mul_f32_e32 v117, v117, v189
	v_cvt_pk_bf16_f32 v114, v114, v114
	v_cvt_pk_bf16_f32 v115, v115, v115
	v_cvt_pk_bf16_f32 v116, v116, v116
	v_cvt_pk_bf16_f32 v117, v117, v117
	v_mul_f32_e32 v138, v190, v190
	v_mul_f32_e32 v139, v191, v191
	v_mul_f32_e32 v140, v192, v192
	v_mul_f32_e32 v141, v193, v193
	v_mul_f32_e32 v138, v138, v190
	v_mul_f32_e32 v139, v139, v191
	v_mul_f32_e32 v140, v140, v192
	v_mul_f32_e32 v141, v141, v193
	v_fma_f32 v138, v202, v138, v190
	v_fma_f32 v139, v202, v139, v191
	v_fma_f32 v140, v202, v140, v192
	v_fma_f32 v141, v202, v141, v193
	v_mul_f32_e32 v138, 0x40135761, v138
	v_mul_f32_e32 v139, 0x40135761, v139
	v_mul_f32_e32 v140, 0x40135761, v140
	v_mul_f32_e32 v141, 0x40135761, v141
	v_exp_f32_e32 v138, v138
	v_exp_f32_e32 v139, v139
	v_exp_f32_e32 v140, v140
	v_exp_f32_e32 v141, v141
	s_nop 0
	v_add_f32_e32 v138, 1.0, v138
	v_add_f32_e32 v139, 1.0, v139
	v_add_f32_e32 v140, 1.0, v140
	v_add_f32_e32 v141, 1.0, v141
	v_rcp_f32_e32 v138, v138
	v_rcp_f32_e32 v139, v139
	v_rcp_f32_e32 v140, v140
	v_rcp_f32_e32 v141, v141
	s_nop 0
	v_fma_f32 v138, -2.0, v138, 1.0
	v_fma_f32 v139, -2.0, v139, 1.0
	v_fma_f32 v140, -2.0, v140, 1.0
	v_fma_f32 v141, -2.0, v141, 1.0
	v_add_f32_e32 v138, 1.0, v138
	v_add_f32_e32 v139, 1.0, v139
	v_add_f32_e32 v140, 1.0, v140
	v_add_f32_e32 v141, 1.0, v141
	v_mul_f32_e32 v190, 0.5, v190
; __device__ __forceinline__ void lru_tile(const Params& P, int chunk, int head, int pass, char* smem_raw) {
;     ...
;           if (d == 0) {
;             hfw[row * 512 + gch] = h;
;           } else {
;             const float hfv = hfp[i];
;             const float g = gp[i];
;             const float tz = 0.7978845608028654f * (g + 0.044715f * g * g * g);
;             const float th = 1.f - 2.f * __builtin_amdgcn_rcpf(1.f + __expf(2.f * tz));
;             const float ge = 0.5f * g * (1.f + th);
;             P.cat[row * 1024 + gch] = f2bf((hfv + h) * ge);
;           }
; __device__ __forceinline__ void run_phase(const Params& P, const int ph, char* smem_raw) {
;     ...
;       for (int t = VBID; t < 2112; t += VGRID) lru_tile(P, t >> 3, t & 7, 2, smv_raw);
	v_mul_f32_e32 v191, 0.5, v191
	v_mul_f32_e32 v192, 0.5, v192
	v_mul_f32_e32 v193, 0.5, v193
	v_mul_f32_e32 v190, v190, v138
	v_mul_f32_e32 v191, v191, v139
	v_mul_f32_e32 v192, v192, v140
	v_mul_f32_e32 v193, v193, v141
	v_add_f32_e32 v118, v233, v118
	v_add_f32_e32 v119, v234, v119
	v_add_f32_e32 v120, v235, v120
	v_add_f32_e32 v121, v236, v121
	v_mul_f32_e32 v118, v118, v190
	v_mul_f32_e32 v119, v119, v191
	v_mul_f32_e32 v120, v120, v192
	v_mul_f32_e32 v121, v121, v193
	v_cvt_pk_bf16_f32 v118, v118, v118
	v_cvt_pk_bf16_f32 v119, v119, v119
	v_cvt_pk_bf16_f32 v120, v120, v120
	v_cvt_pk_bf16_f32 v121, v121, v121
	s_lshl_b32 s0, s71, 18
	s_lshl_b32 s1, s56, 1
	s_add_u32 s0, s0, s1
	s_add_u32 s4, s12, s0
	s_addc_u32 s5, s13, 0
	global_store_short v237, v90, s[4:5]
	s_add_u32 s4, s4, 0x800
	s_addc_u32 s5, s5, 0
	global_store_short v237, v91, s[4:5]
	s_add_u32 s4, s4, 0x800
	s_addc_u32 s5, s5, 0
	global_store_short v237, v92, s[4:5]
	s_add_u32 s4, s4, 0x800
	s_addc_u32 s5, s5, 0
	global_store_short v237, v93, s[4:5]
	s_add_u32 s4, s4, 0x800
	s_addc_u32 s5, s5, 0
	global_store_short v237, v94, s[4:5]
	s_add_u32 s4, s4, 0x800
	s_addc_u32 s5, s5, 0
	global_store_short v237, v95, s[4:5]
	s_add_u32 s4, s4, 0x800
	s_addc_u32 s5, s5, 0
	global_store_short v237, v96, s[4:5]
	s_add_u32 s4, s4, 0x800
	s_addc_u32 s5, s5, 0
	global_store_short v237, v97, s[4:5]
	s_add_u32 s4, s4, 0x800
	s_addc_u32 s5, s5, 0
	global_store_short v237, v98, s[4:5]
	s_add_u32 s4, s4, 0x800
	s_addc_u32 s5, s5, 0
	global_store_short v237, v99, s[4:5]
	s_add_u32 s4, s4, 0x800
	s_addc_u32 s5, s5, 0
	global_store_short v237, v100, s[4:5]
	s_add_u32 s4, s4, 0x800
	s_addc_u32 s5, s5, 0
	global_store_short v237, v101, s[4:5]
	s_add_u32 s4, s4, 0x800
	s_addc_u32 s5, s5, 0
	global_store_short v237, v102, s[4:5]
	s_add_u32 s4, s4, 0x800
	s_addc_u32 s5, s5, 0
	global_store_short v237, v103, s[4:5]
	s_add_u32 s4, s4, 0x800
	s_addc_u32 s5, s5, 0
	global_store_short v237, v104, s[4:5]
	s_add_u32 s4, s4, 0x800
	s_addc_u32 s5, s5, 0
	global_store_short v237, v105, s[4:5]
	s_add_u32 s4, s4, 0x800
	s_addc_u32 s5, s5, 0
	global_store_short v237, v106, s[4:5]
	s_add_u32 s4, s4, 0x800
	s_addc_u32 s5, s5, 0
	global_store_short v237, v107, s[4:5]
	s_add_u32 s4, s4, 0x800
	s_addc_u32 s5, s5, 0
	global_store_short v237, v108, s[4:5]
	s_add_u32 s4, s4, 0x800
	s_addc_u32 s5, s5, 0
	global_store_short v237, v109, s[4:5]
	s_add_u32 s4, s4, 0x800
	s_addc_u32 s5, s5, 0
	global_store_short v237, v110, s[4:5]
	s_add_u32 s4, s4, 0x800
	s_addc_u32 s5, s5, 0
	global_store_short v237, v111, s[4:5]
	s_add_u32 s4, s4, 0x800
	s_addc_u32 s5, s5, 0
	global_store_short v237, v112, s[4:5]
	s_add_u32 s4, s4, 0x800
	s_addc_u32 s5, s5, 0
	global_store_short v237, v113, s[4:5]
	s_add_u32 s4, s4, 0x800
	s_addc_u32 s5, s5, 0
	global_store_short v237, v114, s[4:5]
	s_add_u32 s4, s4, 0x800
	s_addc_u32 s5, s5, 0
	global_store_short v237, v115, s[4:5]
	s_add_u32 s4, s4, 0x800
	s_addc_u32 s5, s5, 0
	global_store_short v237, v116, s[4:5]
	s_add_u32 s4, s4, 0x800
	s_addc_u32 s5, s5, 0
	global_store_short v237, v117, s[4:5]
	s_add_u32 s4, s4, 0x800
	s_addc_u32 s5, s5, 0
	global_store_short v237, v118, s[4:5]
	s_add_u32 s4, s4, 0x800
	s_addc_u32 s5, s5, 0
	global_store_short v237, v119, s[4:5]
	s_add_u32 s4, s4, 0x800
	s_addc_u32 s5, s5, 0
	global_store_short v237, v120, s[4:5]
	s_add_u32 s4, s4, 0x800
	s_addc_u32 s5, s5, 0
	global_store_short v237, v121, s[4:5]
	s_add_u32 s69, s69, 1
	s_cmp_lt_u32 s69, s70
	s_cbranch_scc1 .Lmy_lrub_tile
	s_waitcnt lgkmcnt(0)
	s_barrier
	s_branch .LBB0_680
